# speedup vs baseline: 1.0869x; 1.0869x over previous
; template <bool SWAP, bool SS>
; __device__ __forceinline__ void gemm_main(const u16* __restrict__ A, int lda, int M, int m0,
;                                           const u16* __restrict__ Bt, int ldb, int n0, int K,
;                                           char* smraw, f32x16 (&acc)[2][2]) {
;     ...
;   unsigned aoff[4], boff[4];
; #pragma unroll
;   for (int j = 0; j < 4; ++j) {
;     int r = lrow + 32 * j;
;     int ar = m0 + r; ar = ar < M ? ar : M - 1;
;     aoff[j] = ((unsigned)ar * (unsigned)lda + (unsigned)kc * 8u) * 2u;
;     boff[j] = ((unsigned)(n0 + r) * (unsigned)ldb + (unsigned)kc * 8u) * 2u;
;   }
; #pragma unroll
;   for (int i = 0; i < 2; ++i)
; #pragma unroll
;     for (int j = 0; j < 2; ++j)
; #pragma unroll
;       for (int r = 0; r < 16; ++r) acc[i][j][r] = 0.f;
;   float ss[4] = {0.f, 0.f, 0.f, 0.f};
;   const int nk = K / 64;
;   auto gload = [&](u32x4 (&ga)[4], u32x4 (&gb)[4], int kt) {
; #pragma unroll
;     for (int j = 0; j < 4; ++j) { ga[j] = *(const u32x4*)(Ab + (aoff[j] + (unsigned)kt * 128u)); gb[j] = *(const u32x4*)(Bb + (boff[j] + (unsigned)kt * 128u)); }
;   };
;   auto lwrite = [&](const u32x4 (&ga)[4], const u32x4 (&gb)[4], int buf) {
;     u16* As = sm + buf * (2 * 128 * TSTR);
;     u16* Bs = As + 128 * TSTR;
; #pragma unroll
;     for (int j = 0; j < 4; ++j) {
;       *(u32x4*)(As + (lrow + 32 * j) * TSTR + kc * 8) = ga[j];
;       *(u32x4*)(Bs + (lrow + 32 * j) * TSTR + kc * 8) = gb[j];
;       if (SS) ss[j] += sumsq8(ga[j]);
;     }
;   };
;   auto compute = [&](int buf) {
;     const u16* As = sm + buf * (2 * 128 * TSTR);
;     const u16* Bs = As + 128 * TSTR;
; #pragma unroll
;     for (int ks = 0; ks < 4; ++ks) {
;       bf16x8 af[2], bf[2];
; #pragma unroll
;       for (int i = 0; i < 2; ++i) af[i] = *(const bf16x8*)(As + (wm * 64 + i * 32 + lc) * TSTR + ks * 16 + hf * 8);
; #pragma unroll
;       for (int j = 0; j < 2; ++j) bf[j] = *(const bf16x8*)(Bs + (wn * 64 + j * 32 + lc) * TSTR + ks * 16 + hf * 8);
; #pragma unroll
;       for (int i = 0; i < 2; ++i)
; #pragma unroll
;         for (int j = 0; j < 2; ++j)
;           acc[i][j] = SWAP ? mfma32(bf[j], af[i], acc[i][j]) : mfma32(af[i], bf[j], acc[i][j]);
;     }
;   };
;   u32x4 ga0[4], gb0[4], ga1[4], gb1[4];
;   gload(ga0, gb0, 0);
;   if (nk > 1) gload(ga1, gb1, 1);
;   lwrite(ga0, gb0, 0);
;   if (nk > 2) gload(ga0, gb0, 2);
;   __syncthreads();
.LBB0_321:
	s_add_i32 s15, s15, s96
	s_add_i32 s8, s8, s9
	s_cmpk_lt_i32 s15, 0x808
	s_cbranch_scc0 .LBB0_513
.LBB0_322:
	s_ashr_i32 s0, s15, 31
	s_lshr_b32 s0, s0, 29
	s_add_i32 s0, s15, s0
	s_ashr_i32 s0, s0, 3
	v_mov_b32_e32 v33, v189
	s_lshl_b32 s1, s0, 7
	s_lshl_b32 s0, s0, 10
	v_ashrrev_i32_e32 v35, 3, v33
	v_lshlrev_b32_e32 v0, 4, v33
	v_and_b32_e32 v32, 0x70, v0
	v_add_u32_e32 v0, s1, v35
	v_min_i32_e32 v1, 0x803f, v0
	v_lshl_or_b32 v68, v1, 11, v32
	v_subrev_u32_e32 v1, s0, v35
	v_add_u32_e32 v1, s8, v1
	v_lshl_or_b32 v69, v1, 11, v32
	v_add_u32_e32 v1, 32, v0
	v_min_i32_e32 v1, 0x803f, v1
	v_lshl_or_b32 v70, v1, 11, v32
	v_add_u32_e32 v1, 64, v0
	v_add_u32_e32 v0, 0x60, v0
	v_min_i32_e32 v1, 0x803f, v1
	v_min_i32_e32 v0, 0x803f, v0
	v_add_u32_e32 v71, 0x10000, v69
	v_lshl_or_b32 v72, v1, 11, v32
	v_add_u32_e32 v73, 0x20000, v69
	v_lshl_or_b32 v75, v0, 11, v32
	v_add_u32_e32 v76, 0x30000, v69
	global_load_dwordx4 v[0:3], v68, s[66:67]
	global_load_dwordx4 v[4:7], v69, s[80:81]
	global_load_dwordx4 v[8:11], v70, s[66:67]
	global_load_dwordx4 v[12:15], v71, s[80:81]
	global_load_dwordx4 v[16:19], v72, s[66:67]
	global_load_dwordx4 v[20:23], v73, s[80:81]
	global_load_dwordx4 v[24:27], v75, s[66:67]
	global_load_dwordx4 v[28:31], v76, s[80:81]
	global_load_dwordx4 v[78:81], v68, s[66:67] offset:128
	global_load_dwordx4 v[82:85], v69, s[80:81] offset:128
	global_load_dwordx4 v[86:89], v68, s[66:67] offset:256
	global_load_dwordx4 v[90:93], v69, s[80:81] offset:256
	global_load_dwordx4 v[94:97], v70, s[66:67] offset:128
	global_load_dwordx4 v[98:101], v71, s[80:81] offset:128
	global_load_dwordx4 v[102:105], v72, s[66:67] offset:128
	global_load_dwordx4 v[106:109], v73, s[80:81] offset:128
	global_load_dwordx4 v[110:113], v75, s[66:67] offset:128
	global_load_dwordx4 v[114:117], v76, s[80:81] offset:128
	global_load_dwordx4 v[118:121], v70, s[66:67] offset:256
	global_load_dwordx4 v[122:125], v71, s[80:81] offset:256
	global_load_dwordx4 v[126:129], v72, s[66:67] offset:256
	global_load_dwordx4 v[130:133], v73, s[80:81] offset:256
	global_load_dwordx4 v[134:137], v75, s[66:67] offset:256
	global_load_dwordx4 v[138:141], v76, s[80:81] offset:256
	v_and_b32_e32 v34, 31, v33
	v_lshrrev_b32_e32 v36, 1, v33
	v_and_or_b32 v37, v36, s11, v34
	v_and_b32_e32 v34, 16, v36
	v_mad_u64_u32 v[66:67], s[4:5], v35, s10, v[32:33]
	v_mad_u64_u32 v[64:65], s[4:5], v37, s10, v[34:35]
	v_add_u32_e32 v67, 0xd800, v66
	s_waitcnt vmcnt(23)
	ds_write_b128 v66, v[0:3]
	s_waitcnt vmcnt(22)
	ds_write_b128 v66, v[4:7] offset:18432
	s_waitcnt vmcnt(21)
	ds_write_b128 v66, v[8:11] offset:4608
	s_waitcnt vmcnt(20)
	ds_write_b128 v66, v[12:15] offset:23040
	s_waitcnt vmcnt(19)
	ds_write_b128 v66, v[16:19] offset:9216
	s_waitcnt vmcnt(18)
	ds_write_b128 v66, v[20:23] offset:27648
	s_waitcnt vmcnt(17)
	ds_write_b128 v66, v[24:27] offset:13824
	s_waitcnt vmcnt(16)
	ds_write_b128 v66, v[28:31] offset:32256
	s_waitcnt lgkmcnt(0)
	s_barrier
	ds_read_b128 v[0:3], v64
	v_and_b32_e32 v4, 0x5f, v33
	v_mul_u32_u24_e32 v4, 0x48, v4
	v_lshl_add_u32 v65, v4, 1, v34
	ds_read_b128 v[4:7], v65 offset:18432
	ds_read_b128 v[142:145], v64 offset:32
	ds_read_b128 v[146:149], v65 offset:18464
	ds_read_b128 v[8:11], v65 offset:23040
	ds_read_b128 v[150:153], v65 offset:23072
	s_waitcnt lgkmcnt(4)
	v_mfma_f32_32x32x16_bf16 v[48:63], v[0:3], v[4:7], 0
	s_waitcnt lgkmcnt(1)
	v_mfma_f32_32x32x16_bf16 v[32:47], v[0:3], v[8:11], 0
	ds_read_b128 v[0:3], v64 offset:4608
	ds_read_b128 v[154:157], v64 offset:4640
	s_waitcnt lgkmcnt(1)
	v_mfma_f32_32x32x16_bf16 v[16:31], v[0:3], v[4:7], 0
	v_mfma_f32_32x32x16_bf16 v[0:15], v[0:3], v[8:11], 0
	v_mfma_f32_32x32x16_bf16 v[48:63], v[142:145], v[146:149], v[48:63]
	v_mfma_f32_32x32x16_bf16 v[32:47], v[142:145], v[150:153], v[32:47]
	s_waitcnt lgkmcnt(0)
	v_mfma_f32_32x32x16_bf16 v[16:31], v[154:157], v[146:149], v[16:31]
	v_mfma_f32_32x32x16_bf16 v[0:15], v[154:157], v[150:153], v[0:15]
	ds_read_b128 v[142:145], v64 offset:64
	ds_read_b128 v[146:149], v65 offset:18496
	ds_read_b128 v[150:153], v64 offset:96
	ds_read_b128 v[154:157], v65 offset:18528
	ds_read_b128 v[158:161], v65 offset:23104
	ds_read_b128 v[162:165], v65 offset:23136
	s_waitcnt lgkmcnt(4)
	v_mfma_f32_32x32x16_bf16 v[48:63], v[142:145], v[146:149], v[48:63]
	s_waitcnt lgkmcnt(1)
	v_mfma_f32_32x32x16_bf16 v[32:47], v[142:145], v[158:161], v[32:47]
	ds_read_b128 v[142:145], v64 offset:4672
	ds_read_b128 v[166:169], v64 offset:4704
	s_waitcnt vmcnt(15)
	ds_write_b128 v66, v[78:81] offset:36864
	s_waitcnt vmcnt(14)
	ds_write_b128 v66, v[82:85] offset:55296
	s_waitcnt vmcnt(11)
	ds_write_b128 v66, v[94:97] offset:41472
	s_waitcnt vmcnt(10)
	ds_write_b128 v66, v[98:101] offset:59904
	s_waitcnt vmcnt(9)
	ds_write_b128 v66, v[102:105] offset:46080
	s_waitcnt vmcnt(8)
	ds_write_b128 v66, v[106:109] offset:64512
	s_waitcnt vmcnt(7)
	ds_write_b128 v66, v[110:113] offset:50688
	s_waitcnt vmcnt(6)
	ds_write_b128 v67, v[114:117] offset:13824
	global_load_dwordx4 v[78:81], v68, s[66:67] offset:384
	global_load_dwordx4 v[82:85], v69, s[80:81] offset:384
	global_load_dwordx4 v[94:97], v70, s[66:67] offset:384
	global_load_dwordx4 v[98:101], v71, s[80:81] offset:384
	global_load_dwordx4 v[102:105], v72, s[66:67] offset:384
	global_load_dwordx4 v[106:109], v73, s[80:81] offset:384
	global_load_dwordx4 v[110:113], v75, s[66:67] offset:384
	global_load_dwordx4 v[114:117], v76, s[80:81] offset:384
	s_waitcnt lgkmcnt(0)
	s_barrier
; template <bool SWAP, bool SS>
; __device__ __forceinline__ void gemm_main(const u16* __restrict__ A, int lda, int M, int m0,
;                                           const u16* __restrict__ Bt, int ldb, int n0, int K,
;                                           char* smraw, f32x16 (&acc)[2][2]) {
;     ...
;   auto gload = [&](u32x4 (&ga)[4], u32x4 (&gb)[4], int kt) {
; #pragma unroll
;     for (int j = 0; j < 4; ++j) { ga[j] = *(const u32x4*)(Ab + (aoff[j] + (unsigned)kt * 128u)); gb[j] = *(const u32x4*)(Bb + (boff[j] + (unsigned)kt * 128u)); }
;   };
;   auto lwrite = [&](const u32x4 (&ga)[4], const u32x4 (&gb)[4], int buf) {
;     u16* As = sm + buf * (2 * 128 * TSTR);
;     u16* Bs = As + 128 * TSTR;
; #pragma unroll
;     for (int j = 0; j < 4; ++j) {
;       *(u32x4*)(As + (lrow + 32 * j) * TSTR + kc * 8) = ga[j];
;       *(u32x4*)(Bs + (lrow + 32 * j) * TSTR + kc * 8) = gb[j];
;       if (SS) ss[j] += sumsq8(ga[j]);
;     }
;   };
;   auto compute = [&](int buf) {
;     const u16* As = sm + buf * (2 * 128 * TSTR);
;     const u16* Bs = As + 128 * TSTR;
; #pragma unroll
;     for (int ks = 0; ks < 4; ++ks) {
;       bf16x8 af[2], bf[2];
; #pragma unroll
;       for (int i = 0; i < 2; ++i) af[i] = *(const bf16x8*)(As + (wm * 64 + i * 32 + lc) * TSTR + ks * 16 + hf * 8);
; #pragma unroll
;       for (int j = 0; j < 2; ++j) bf[j] = *(const bf16x8*)(Bs + (wn * 64 + j * 32 + lc) * TSTR + ks * 16 + hf * 8);
; #pragma unroll
;       for (int i = 0; i < 2; ++i)
; #pragma unroll
;         for (int j = 0; j < 2; ++j)
;           acc[i][j] = SWAP ? mfma32(bf[j], af[i], acc[i][j]) : mfma32(af[i], bf[j], acc[i][j]);
;     }
;   };
;   u32x4 ga0[4], gb0[4], ga1[4], gb1[4];
;   gload(ga0, gb0, 0);
;   if (nk > 1) gload(ga1, gb1, 1);
;   lwrite(ga0, gb0, 0);
;   if (nk > 2) gload(ga0, gb0, 2);
;   __syncthreads();
;   for (int kt = 0; kt < nk; kt += 2) {
;     compute(0);
;     if (kt + 1 < nk) lwrite(ga1, gb1, 1);
;     if (kt + 3 < nk) gload(ga1, gb1, kt + 3);
;     __syncthreads();
;     if (kt + 1 < nk) {
;       compute(1);
;       if (kt + 2 < nk) lwrite(ga0, gb0, 0);
;       if (kt + 4 < nk) gload(ga0, gb0, kt + 4);
;       __syncthreads();
;     }
	v_mfma_f32_32x32x16_bf16 v[16:31], v[142:145], v[146:149], v[16:31]
	v_mfma_f32_32x32x16_bf16 v[0:15], v[142:145], v[158:161], v[0:15]
	v_mfma_f32_32x32x16_bf16 v[48:63], v[150:153], v[154:157], v[48:63]
	v_mfma_f32_32x32x16_bf16 v[32:47], v[150:153], v[162:165], v[32:47]
	v_mfma_f32_32x32x16_bf16 v[16:31], v[166:169], v[154:157], v[16:31]
	ds_read_b128 v[142:145], v64 offset:36864
	ds_read_b128 v[146:149], v65 offset:55296
	ds_read_b128 v[150:153], v64 offset:36896
	ds_read_b128 v[154:157], v65 offset:55328
	v_mfma_f32_32x32x16_bf16 v[0:15], v[166:169], v[162:165], v[0:15]
	ds_read_b128 v[158:161], v65 offset:59904
	ds_read_b128 v[162:165], v65 offset:59936
	s_waitcnt lgkmcnt(4)
	v_mfma_f32_32x32x16_bf16 v[48:63], v[142:145], v[146:149], v[48:63]
	s_waitcnt lgkmcnt(1)
	v_mfma_f32_32x32x16_bf16 v[32:47], v[142:145], v[158:161], v[32:47]
	ds_read_b128 v[142:145], v64 offset:41472
	ds_read_b128 v[166:169], v64 offset:41504
	s_waitcnt lgkmcnt(1)
	v_mfma_f32_32x32x16_bf16 v[16:31], v[142:145], v[146:149], v[16:31]
	v_mfma_f32_32x32x16_bf16 v[0:15], v[142:145], v[158:161], v[0:15]
	v_mfma_f32_32x32x16_bf16 v[48:63], v[150:153], v[154:157], v[48:63]
	v_mfma_f32_32x32x16_bf16 v[32:47], v[150:153], v[162:165], v[32:47]
	s_waitcnt lgkmcnt(0)
	v_mfma_f32_32x32x16_bf16 v[16:31], v[166:169], v[154:157], v[16:31]
	ds_read_b128 v[142:145], v64 offset:36928
	ds_read_b128 v[146:149], v65 offset:55360
	ds_read_b128 v[150:153], v64 offset:36960
	ds_read_b128 v[154:157], v65 offset:55392
	v_mfma_f32_32x32x16_bf16 v[0:15], v[166:169], v[162:165], v[0:15]
	ds_read_b128 v[158:161], v65 offset:59968
	ds_read_b128 v[162:165], v65 offset:60000
	s_waitcnt lgkmcnt(4)
	v_mfma_f32_32x32x16_bf16 v[48:63], v[142:145], v[146:149], v[48:63]
	s_waitcnt lgkmcnt(1)
	v_mfma_f32_32x32x16_bf16 v[32:47], v[142:145], v[158:161], v[32:47]
	ds_read_b128 v[142:145], v64 offset:41536
	ds_read_b128 v[166:169], v64 offset:41568
	ds_write_b128 v66, v[86:89]
	ds_write_b128 v66, v[90:93] offset:18432
	s_waitcnt vmcnt(13)
	ds_write_b128 v66, v[118:121] offset:4608
	s_waitcnt vmcnt(12)
	ds_write_b128 v66, v[122:125] offset:23040
	s_waitcnt vmcnt(11)
	ds_write_b128 v66, v[126:129] offset:9216
	s_waitcnt vmcnt(10)
	ds_write_b128 v66, v[130:133] offset:27648
	s_waitcnt vmcnt(9)
	ds_write_b128 v66, v[134:137] offset:13824
	s_waitcnt vmcnt(8)
	ds_write_b128 v66, v[138:141] offset:32256
	global_load_dwordx4 v[86:89], v68, s[66:67] offset:512
	global_load_dwordx4 v[90:93], v69, s[80:81] offset:512
	global_load_dwordx4 v[118:121], v70, s[66:67] offset:512
	global_load_dwordx4 v[122:125], v71, s[80:81] offset:512
	global_load_dwordx4 v[126:129], v72, s[66:67] offset:512
	global_load_dwordx4 v[130:133], v73, s[80:81] offset:512
	global_load_dwordx4 v[134:137], v75, s[66:67] offset:512
	global_load_dwordx4 v[138:141], v76, s[80:81] offset:512
	s_waitcnt lgkmcnt(0)
	s_barrier
	v_mfma_f32_32x32x16_bf16 v[16:31], v[142:145], v[146:149], v[16:31]
	v_mfma_f32_32x32x16_bf16 v[0:15], v[142:145], v[158:161], v[0:15]
	v_mfma_f32_32x32x16_bf16 v[48:63], v[150:153], v[154:157], v[48:63]
	v_mfma_f32_32x32x16_bf16 v[32:47], v[150:153], v[162:165], v[32:47]
	v_mfma_f32_32x32x16_bf16 v[16:31], v[166:169], v[154:157], v[16:31]
	ds_read_b128 v[142:145], v64
	ds_read_b128 v[146:149], v65 offset:18432
	ds_read_b128 v[150:153], v64 offset:32
	ds_read_b128 v[154:157], v65 offset:18464
	v_mfma_f32_32x32x16_bf16 v[0:15], v[166:169], v[162:165], v[0:15]
	ds_read_b128 v[158:161], v65 offset:23040
	ds_read_b128 v[162:165], v65 offset:23072
	s_waitcnt lgkmcnt(4)
	v_mfma_f32_32x32x16_bf16 v[48:63], v[142:145], v[146:149], v[48:63]
	s_waitcnt lgkmcnt(1)
	v_mfma_f32_32x32x16_bf16 v[32:47], v[142:145], v[158:161], v[32:47]
	ds_read_b128 v[142:145], v64 offset:4608
	ds_read_b128 v[166:169], v64 offset:4640
	s_waitcnt lgkmcnt(1)
	v_mfma_f32_32x32x16_bf16 v[16:31], v[142:145], v[146:149], v[16:31]
	v_mfma_f32_32x32x16_bf16 v[0:15], v[142:145], v[158:161], v[0:15]
	v_mfma_f32_32x32x16_bf16 v[48:63], v[150:153], v[154:157], v[48:63]
	v_mfma_f32_32x32x16_bf16 v[32:47], v[150:153], v[162:165], v[32:47]
	s_waitcnt lgkmcnt(0)
	v_mfma_f32_32x32x16_bf16 v[16:31], v[166:169], v[154:157], v[16:31]
	ds_read_b128 v[142:145], v64 offset:64
	ds_read_b128 v[146:149], v65 offset:18496
	ds_read_b128 v[150:153], v64 offset:96
	ds_read_b128 v[154:157], v65 offset:18528
	v_mfma_f32_32x32x16_bf16 v[0:15], v[166:169], v[162:165], v[0:15]
	ds_read_b128 v[158:161], v65 offset:23104
	ds_read_b128 v[162:165], v65 offset:23136
	s_waitcnt lgkmcnt(4)
	v_mfma_f32_32x32x16_bf16 v[48:63], v[142:145], v[146:149], v[48:63]
	s_waitcnt lgkmcnt(1)
	v_mfma_f32_32x32x16_bf16 v[32:47], v[142:145], v[158:161], v[32:47]
	ds_read_b128 v[142:145], v64 offset:4672
	ds_read_b128 v[166:169], v64 offset:4704
	s_waitcnt vmcnt(15)
	ds_write_b128 v66, v[78:81] offset:36864
	s_waitcnt vmcnt(14)
	ds_write_b128 v66, v[82:85] offset:55296
	s_waitcnt vmcnt(13)
	ds_write_b128 v66, v[94:97] offset:41472
	s_waitcnt vmcnt(12)
	ds_write_b128 v66, v[98:101] offset:59904
	s_waitcnt vmcnt(11)
	ds_write_b128 v66, v[102:105] offset:46080
	s_waitcnt vmcnt(10)
	ds_write_b128 v66, v[106:109] offset:64512
	s_waitcnt vmcnt(9)
	ds_write_b128 v66, v[110:113] offset:50688
	s_waitcnt vmcnt(8)
	ds_write_b128 v67, v[114:117] offset:13824
	global_load_dwordx4 v[78:81], v68, s[66:67] offset:640
	global_load_dwordx4 v[82:85], v69, s[80:81] offset:640
	global_load_dwordx4 v[94:97], v70, s[66:67] offset:640
	global_load_dwordx4 v[98:101], v71, s[80:81] offset:640
	global_load_dwordx4 v[102:105], v72, s[66:67] offset:640
	global_load_dwordx4 v[106:109], v73, s[80:81] offset:640
	global_load_dwordx4 v[110:113], v75, s[66:67] offset:640
	global_load_dwordx4 v[114:117], v76, s[80:81] offset:640
	s_waitcnt lgkmcnt(0)
	s_barrier
; template <bool SWAP, bool SS>
; __device__ __forceinline__ void gemm_main(const u16* __restrict__ A, int lda, int M, int m0,
;                                           const u16* __restrict__ Bt, int ldb, int n0, int K,
;                                           char* smraw, f32x16 (&acc)[2][2]) {
;     ...
;   auto gload = [&](u32x4 (&ga)[4], u32x4 (&gb)[4], int kt) {
; #pragma unroll
;     for (int j = 0; j < 4; ++j) { ga[j] = *(const u32x4*)(Ab + (aoff[j] + (unsigned)kt * 128u)); gb[j] = *(const u32x4*)(Bb + (boff[j] + (unsigned)kt * 128u)); }
;   };
;   auto lwrite = [&](const u32x4 (&ga)[4], const u32x4 (&gb)[4], int buf) {
;     u16* As = sm + buf * (2 * 128 * TSTR);
;     u16* Bs = As + 128 * TSTR;
; #pragma unroll
;     for (int j = 0; j < 4; ++j) {
;       *(u32x4*)(As + (lrow + 32 * j) * TSTR + kc * 8) = ga[j];
;       *(u32x4*)(Bs + (lrow + 32 * j) * TSTR + kc * 8) = gb[j];
;       if (SS) ss[j] += sumsq8(ga[j]);
;     }
;   };
;   auto compute = [&](int buf) {
;     const u16* As = sm + buf * (2 * 128 * TSTR);
;     const u16* Bs = As + 128 * TSTR;
; #pragma unroll
;     for (int ks = 0; ks < 4; ++ks) {
;       bf16x8 af[2], bf[2];
; #pragma unroll
;       for (int i = 0; i < 2; ++i) af[i] = *(const bf16x8*)(As + (wm * 64 + i * 32 + lc) * TSTR + ks * 16 + hf * 8);
; #pragma unroll
;       for (int j = 0; j < 2; ++j) bf[j] = *(const bf16x8*)(Bs + (wn * 64 + j * 32 + lc) * TSTR + ks * 16 + hf * 8);
; #pragma unroll
;       for (int i = 0; i < 2; ++i)
; #pragma unroll
;         for (int j = 0; j < 2; ++j)
;           acc[i][j] = SWAP ? mfma32(bf[j], af[i], acc[i][j]) : mfma32(af[i], bf[j], acc[i][j]);
;     }
;   };
;   u32x4 ga0[4], gb0[4], ga1[4], gb1[4];
;   gload(ga0, gb0, 0);
;   if (nk > 1) gload(ga1, gb1, 1);
;   lwrite(ga0, gb0, 0);
;   if (nk > 2) gload(ga0, gb0, 2);
;   __syncthreads();
;   for (int kt = 0; kt < nk; kt += 2) {
;     compute(0);
;     if (kt + 1 < nk) lwrite(ga1, gb1, 1);
;     if (kt + 3 < nk) gload(ga1, gb1, kt + 3);
;     __syncthreads();
;     if (kt + 1 < nk) {
;       compute(1);
;       if (kt + 2 < nk) lwrite(ga0, gb0, 0);
;       if (kt + 4 < nk) gload(ga0, gb0, kt + 4);
;       __syncthreads();
;     }
	v_mfma_f32_32x32x16_bf16 v[16:31], v[142:145], v[146:149], v[16:31]
	v_mfma_f32_32x32x16_bf16 v[0:15], v[142:145], v[158:161], v[0:15]
	v_mfma_f32_32x32x16_bf16 v[48:63], v[150:153], v[154:157], v[48:63]
	v_mfma_f32_32x32x16_bf16 v[32:47], v[150:153], v[162:165], v[32:47]
	v_mfma_f32_32x32x16_bf16 v[16:31], v[166:169], v[154:157], v[16:31]
	ds_read_b128 v[142:145], v64 offset:36864
	ds_read_b128 v[146:149], v65 offset:55296
	ds_read_b128 v[150:153], v64 offset:36896
	ds_read_b128 v[154:157], v65 offset:55328
	v_mfma_f32_32x32x16_bf16 v[0:15], v[166:169], v[162:165], v[0:15]
	ds_read_b128 v[158:161], v65 offset:59904
	ds_read_b128 v[162:165], v65 offset:59936
	s_waitcnt lgkmcnt(4)
	v_mfma_f32_32x32x16_bf16 v[48:63], v[142:145], v[146:149], v[48:63]
	s_waitcnt lgkmcnt(1)
	v_mfma_f32_32x32x16_bf16 v[32:47], v[142:145], v[158:161], v[32:47]
	ds_read_b128 v[142:145], v64 offset:41472
	ds_read_b128 v[166:169], v64 offset:41504
	s_waitcnt lgkmcnt(1)
	v_mfma_f32_32x32x16_bf16 v[16:31], v[142:145], v[146:149], v[16:31]
	v_mfma_f32_32x32x16_bf16 v[0:15], v[142:145], v[158:161], v[0:15]
	v_mfma_f32_32x32x16_bf16 v[48:63], v[150:153], v[154:157], v[48:63]
	v_mfma_f32_32x32x16_bf16 v[32:47], v[150:153], v[162:165], v[32:47]
	s_waitcnt lgkmcnt(0)
	v_mfma_f32_32x32x16_bf16 v[16:31], v[166:169], v[154:157], v[16:31]
	ds_read_b128 v[142:145], v64 offset:36928
	ds_read_b128 v[146:149], v65 offset:55360
	ds_read_b128 v[150:153], v64 offset:36960
	ds_read_b128 v[154:157], v65 offset:55392
	v_mfma_f32_32x32x16_bf16 v[0:15], v[166:169], v[162:165], v[0:15]
	ds_read_b128 v[158:161], v65 offset:59968
	ds_read_b128 v[162:165], v65 offset:60000
	s_waitcnt lgkmcnt(4)
	v_mfma_f32_32x32x16_bf16 v[48:63], v[142:145], v[146:149], v[48:63]
	s_waitcnt lgkmcnt(1)
	v_mfma_f32_32x32x16_bf16 v[32:47], v[142:145], v[158:161], v[32:47]
	ds_read_b128 v[142:145], v64 offset:41536
	ds_read_b128 v[166:169], v64 offset:41568
	s_waitcnt vmcnt(15)
	ds_write_b128 v66, v[86:89]
	s_waitcnt vmcnt(14)
	ds_write_b128 v66, v[90:93] offset:18432
	s_waitcnt vmcnt(13)
	ds_write_b128 v66, v[118:121] offset:4608
	s_waitcnt vmcnt(12)
	ds_write_b128 v66, v[122:125] offset:23040
	s_waitcnt vmcnt(11)
	ds_write_b128 v66, v[126:129] offset:9216
	s_waitcnt vmcnt(10)
	ds_write_b128 v66, v[130:133] offset:27648
	s_waitcnt vmcnt(9)
	ds_write_b128 v66, v[134:137] offset:13824
	s_waitcnt vmcnt(8)
	ds_write_b128 v66, v[138:141] offset:32256
	global_load_dwordx4 v[86:89], v68, s[66:67] offset:768
	global_load_dwordx4 v[90:93], v69, s[80:81] offset:768
	global_load_dwordx4 v[118:121], v70, s[66:67] offset:768
	global_load_dwordx4 v[122:125], v71, s[80:81] offset:768
	global_load_dwordx4 v[126:129], v72, s[66:67] offset:768
	global_load_dwordx4 v[130:133], v73, s[80:81] offset:768
	global_load_dwordx4 v[134:137], v75, s[66:67] offset:768
	global_load_dwordx4 v[138:141], v76, s[80:81] offset:768
	s_waitcnt lgkmcnt(0)
	s_barrier
	v_mfma_f32_32x32x16_bf16 v[16:31], v[142:145], v[146:149], v[16:31]
	v_mfma_f32_32x32x16_bf16 v[0:15], v[142:145], v[158:161], v[0:15]
	v_mfma_f32_32x32x16_bf16 v[48:63], v[150:153], v[154:157], v[48:63]
	v_mfma_f32_32x32x16_bf16 v[32:47], v[150:153], v[162:165], v[32:47]
	v_mfma_f32_32x32x16_bf16 v[16:31], v[166:169], v[154:157], v[16:31]
	ds_read_b128 v[142:145], v64
	ds_read_b128 v[146:149], v65 offset:18432
	ds_read_b128 v[150:153], v64 offset:32
	ds_read_b128 v[154:157], v65 offset:18464
	v_mfma_f32_32x32x16_bf16 v[0:15], v[166:169], v[162:165], v[0:15]
	ds_read_b128 v[158:161], v65 offset:23040
	ds_read_b128 v[162:165], v65 offset:23072
	s_waitcnt lgkmcnt(4)
	v_mfma_f32_32x32x16_bf16 v[48:63], v[142:145], v[146:149], v[48:63]
	s_waitcnt lgkmcnt(1)
	v_mfma_f32_32x32x16_bf16 v[32:47], v[142:145], v[158:161], v[32:47]
	ds_read_b128 v[142:145], v64 offset:4608
	ds_read_b128 v[166:169], v64 offset:4640
	s_waitcnt lgkmcnt(1)
	v_mfma_f32_32x32x16_bf16 v[16:31], v[142:145], v[146:149], v[16:31]
	v_mfma_f32_32x32x16_bf16 v[0:15], v[142:145], v[158:161], v[0:15]
	v_mfma_f32_32x32x16_bf16 v[48:63], v[150:153], v[154:157], v[48:63]
	v_mfma_f32_32x32x16_bf16 v[32:47], v[150:153], v[162:165], v[32:47]
	s_waitcnt lgkmcnt(0)
	v_mfma_f32_32x32x16_bf16 v[16:31], v[166:169], v[154:157], v[16:31]
	ds_read_b128 v[142:145], v64 offset:64
	ds_read_b128 v[146:149], v65 offset:18496
	ds_read_b128 v[150:153], v64 offset:96
	ds_read_b128 v[154:157], v65 offset:18528
	v_mfma_f32_32x32x16_bf16 v[0:15], v[166:169], v[162:165], v[0:15]
	ds_read_b128 v[158:161], v65 offset:23104
	ds_read_b128 v[162:165], v65 offset:23136
	s_waitcnt lgkmcnt(4)
	v_mfma_f32_32x32x16_bf16 v[48:63], v[142:145], v[146:149], v[48:63]
	s_waitcnt lgkmcnt(1)
	v_mfma_f32_32x32x16_bf16 v[32:47], v[142:145], v[158:161], v[32:47]
	ds_read_b128 v[142:145], v64 offset:4672
	ds_read_b128 v[166:169], v64 offset:4704
	s_waitcnt vmcnt(15)
	ds_write_b128 v66, v[78:81] offset:36864
	s_waitcnt vmcnt(14)
	ds_write_b128 v66, v[82:85] offset:55296
	s_waitcnt vmcnt(13)
	ds_write_b128 v66, v[94:97] offset:41472
	s_waitcnt vmcnt(12)
	ds_write_b128 v66, v[98:101] offset:59904
	s_waitcnt vmcnt(11)
	ds_write_b128 v66, v[102:105] offset:46080
	s_waitcnt vmcnt(10)
	ds_write_b128 v66, v[106:109] offset:64512
	s_waitcnt vmcnt(9)
	ds_write_b128 v66, v[110:113] offset:50688
	s_waitcnt vmcnt(8)
	ds_write_b128 v67, v[114:117] offset:13824
	global_load_dwordx4 v[78:81], v68, s[66:67] offset:896
	global_load_dwordx4 v[82:85], v69, s[80:81] offset:896
	global_load_dwordx4 v[94:97], v70, s[66:67] offset:896
	global_load_dwordx4 v[98:101], v71, s[80:81] offset:896
	global_load_dwordx4 v[102:105], v72, s[66:67] offset:896
	global_load_dwordx4 v[106:109], v73, s[80:81] offset:896
	global_load_dwordx4 v[110:113], v75, s[66:67] offset:896
	global_load_dwordx4 v[114:117], v76, s[80:81] offset:896
	s_waitcnt lgkmcnt(0)
	s_barrier
; template <bool SWAP, bool SS>
; __device__ __forceinline__ void gemm_main(const u16* __restrict__ A, int lda, int M, int m0,
;                                           const u16* __restrict__ Bt, int ldb, int n0, int K,
;                                           char* smraw, f32x16 (&acc)[2][2]) {
;     ...
;   auto gload = [&](u32x4 (&ga)[4], u32x4 (&gb)[4], int kt) {
; #pragma unroll
;     for (int j = 0; j < 4; ++j) { ga[j] = *(const u32x4*)(Ab + (aoff[j] + (unsigned)kt * 128u)); gb[j] = *(const u32x4*)(Bb + (boff[j] + (unsigned)kt * 128u)); }
;   };
;   auto lwrite = [&](const u32x4 (&ga)[4], const u32x4 (&gb)[4], int buf) {
;     u16* As = sm + buf * (2 * 128 * TSTR);
;     u16* Bs = As + 128 * TSTR;
; #pragma unroll
;     for (int j = 0; j < 4; ++j) {
;       *(u32x4*)(As + (lrow + 32 * j) * TSTR + kc * 8) = ga[j];
;       *(u32x4*)(Bs + (lrow + 32 * j) * TSTR + kc * 8) = gb[j];
;       if (SS) ss[j] += sumsq8(ga[j]);
;     }
;   };
;   auto compute = [&](int buf) {
;     const u16* As = sm + buf * (2 * 128 * TSTR);
;     const u16* Bs = As + 128 * TSTR;
; #pragma unroll
;     for (int ks = 0; ks < 4; ++ks) {
;       bf16x8 af[2], bf[2];
; #pragma unroll
;       for (int i = 0; i < 2; ++i) af[i] = *(const bf16x8*)(As + (wm * 64 + i * 32 + lc) * TSTR + ks * 16 + hf * 8);
; #pragma unroll
;       for (int j = 0; j < 2; ++j) bf[j] = *(const bf16x8*)(Bs + (wn * 64 + j * 32 + lc) * TSTR + ks * 16 + hf * 8);
; #pragma unroll
;       for (int i = 0; i < 2; ++i)
; #pragma unroll
;         for (int j = 0; j < 2; ++j)
;           acc[i][j] = SWAP ? mfma32(bf[j], af[i], acc[i][j]) : mfma32(af[i], bf[j], acc[i][j]);
;     }
;   };
;   u32x4 ga0[4], gb0[4], ga1[4], gb1[4];
;   gload(ga0, gb0, 0);
;   if (nk > 1) gload(ga1, gb1, 1);
;   lwrite(ga0, gb0, 0);
;   if (nk > 2) gload(ga0, gb0, 2);
;   __syncthreads();
;   for (int kt = 0; kt < nk; kt += 2) {
;     compute(0);
;     if (kt + 1 < nk) lwrite(ga1, gb1, 1);
;     if (kt + 3 < nk) gload(ga1, gb1, kt + 3);
;     __syncthreads();
;     if (kt + 1 < nk) {
;       compute(1);
;       if (kt + 2 < nk) lwrite(ga0, gb0, 0);
;       if (kt + 4 < nk) gload(ga0, gb0, kt + 4);
;       __syncthreads();
;     }
	v_mfma_f32_32x32x16_bf16 v[16:31], v[142:145], v[146:149], v[16:31]
	v_mfma_f32_32x32x16_bf16 v[0:15], v[142:145], v[158:161], v[0:15]
	v_mfma_f32_32x32x16_bf16 v[48:63], v[150:153], v[154:157], v[48:63]
	v_mfma_f32_32x32x16_bf16 v[32:47], v[150:153], v[162:165], v[32:47]
	v_mfma_f32_32x32x16_bf16 v[16:31], v[166:169], v[154:157], v[16:31]
	ds_read_b128 v[142:145], v64 offset:36864
	ds_read_b128 v[146:149], v65 offset:55296
	ds_read_b128 v[150:153], v64 offset:36896
	ds_read_b128 v[154:157], v65 offset:55328
	v_mfma_f32_32x32x16_bf16 v[0:15], v[166:169], v[162:165], v[0:15]
	ds_read_b128 v[158:161], v65 offset:59904
	ds_read_b128 v[162:165], v65 offset:59936
	s_waitcnt lgkmcnt(4)
	v_mfma_f32_32x32x16_bf16 v[48:63], v[142:145], v[146:149], v[48:63]
	s_waitcnt lgkmcnt(1)
	v_mfma_f32_32x32x16_bf16 v[32:47], v[142:145], v[158:161], v[32:47]
	ds_read_b128 v[142:145], v64 offset:41472
	ds_read_b128 v[166:169], v64 offset:41504
	s_waitcnt lgkmcnt(1)
	v_mfma_f32_32x32x16_bf16 v[16:31], v[142:145], v[146:149], v[16:31]
	v_mfma_f32_32x32x16_bf16 v[0:15], v[142:145], v[158:161], v[0:15]
	v_mfma_f32_32x32x16_bf16 v[48:63], v[150:153], v[154:157], v[48:63]
	v_mfma_f32_32x32x16_bf16 v[32:47], v[150:153], v[162:165], v[32:47]
	s_waitcnt lgkmcnt(0)
	v_mfma_f32_32x32x16_bf16 v[16:31], v[166:169], v[154:157], v[16:31]
	ds_read_b128 v[142:145], v64 offset:36928
	ds_read_b128 v[146:149], v65 offset:55360
	ds_read_b128 v[150:153], v64 offset:36960
	ds_read_b128 v[154:157], v65 offset:55392
	v_mfma_f32_32x32x16_bf16 v[0:15], v[166:169], v[162:165], v[0:15]
	ds_read_b128 v[158:161], v65 offset:59968
	ds_read_b128 v[162:165], v65 offset:60000
	s_waitcnt lgkmcnt(4)
	v_mfma_f32_32x32x16_bf16 v[48:63], v[142:145], v[146:149], v[48:63]
	s_waitcnt lgkmcnt(1)
	v_mfma_f32_32x32x16_bf16 v[32:47], v[142:145], v[158:161], v[32:47]
	ds_read_b128 v[142:145], v64 offset:41536
	ds_read_b128 v[166:169], v64 offset:41568
	s_waitcnt vmcnt(15)
	ds_write_b128 v66, v[86:89]
	s_waitcnt vmcnt(14)
	ds_write_b128 v66, v[90:93] offset:18432
	s_waitcnt vmcnt(13)
	ds_write_b128 v66, v[118:121] offset:4608
	s_waitcnt vmcnt(12)
	ds_write_b128 v66, v[122:125] offset:23040
	s_waitcnt vmcnt(11)
	ds_write_b128 v66, v[126:129] offset:9216
	s_waitcnt vmcnt(10)
	ds_write_b128 v66, v[130:133] offset:27648
	s_waitcnt vmcnt(9)
	ds_write_b128 v66, v[134:137] offset:13824
	s_waitcnt vmcnt(8)
	ds_write_b128 v66, v[138:141] offset:32256
	global_load_dwordx4 v[86:89], v68, s[66:67] offset:1024
	global_load_dwordx4 v[90:93], v69, s[80:81] offset:1024
	global_load_dwordx4 v[118:121], v70, s[66:67] offset:1024
	global_load_dwordx4 v[122:125], v71, s[80:81] offset:1024
	global_load_dwordx4 v[126:129], v72, s[66:67] offset:1024
	global_load_dwordx4 v[130:133], v73, s[80:81] offset:1024
	global_load_dwordx4 v[134:137], v75, s[66:67] offset:1024
	global_load_dwordx4 v[138:141], v76, s[80:81] offset:1024
	s_waitcnt lgkmcnt(0)
	s_barrier
	v_mfma_f32_32x32x16_bf16 v[16:31], v[142:145], v[146:149], v[16:31]
	v_mfma_f32_32x32x16_bf16 v[0:15], v[142:145], v[158:161], v[0:15]
	v_mfma_f32_32x32x16_bf16 v[48:63], v[150:153], v[154:157], v[48:63]
	v_mfma_f32_32x32x16_bf16 v[32:47], v[150:153], v[162:165], v[32:47]
	v_mfma_f32_32x32x16_bf16 v[16:31], v[166:169], v[154:157], v[16:31]
	ds_read_b128 v[142:145], v64
	ds_read_b128 v[146:149], v65 offset:18432
	ds_read_b128 v[150:153], v64 offset:32
	ds_read_b128 v[154:157], v65 offset:18464
	v_mfma_f32_32x32x16_bf16 v[0:15], v[166:169], v[162:165], v[0:15]
	ds_read_b128 v[158:161], v65 offset:23040
	ds_read_b128 v[162:165], v65 offset:23072
	s_waitcnt lgkmcnt(4)
	v_mfma_f32_32x32x16_bf16 v[48:63], v[142:145], v[146:149], v[48:63]
	s_waitcnt lgkmcnt(1)
	v_mfma_f32_32x32x16_bf16 v[32:47], v[142:145], v[158:161], v[32:47]
	ds_read_b128 v[142:145], v64 offset:4608
	ds_read_b128 v[166:169], v64 offset:4640
	s_waitcnt lgkmcnt(1)
	v_mfma_f32_32x32x16_bf16 v[16:31], v[142:145], v[146:149], v[16:31]
	v_mfma_f32_32x32x16_bf16 v[0:15], v[142:145], v[158:161], v[0:15]
	v_mfma_f32_32x32x16_bf16 v[48:63], v[150:153], v[154:157], v[48:63]
	v_mfma_f32_32x32x16_bf16 v[32:47], v[150:153], v[162:165], v[32:47]
	s_waitcnt lgkmcnt(0)
	v_mfma_f32_32x32x16_bf16 v[16:31], v[166:169], v[154:157], v[16:31]
	ds_read_b128 v[142:145], v64 offset:64
	ds_read_b128 v[146:149], v65 offset:18496
	ds_read_b128 v[150:153], v64 offset:96
	ds_read_b128 v[154:157], v65 offset:18528
	v_mfma_f32_32x32x16_bf16 v[0:15], v[166:169], v[162:165], v[0:15]
	ds_read_b128 v[158:161], v65 offset:23104
	ds_read_b128 v[162:165], v65 offset:23136
	s_waitcnt lgkmcnt(4)
	v_mfma_f32_32x32x16_bf16 v[48:63], v[142:145], v[146:149], v[48:63]
	s_waitcnt lgkmcnt(1)
	v_mfma_f32_32x32x16_bf16 v[32:47], v[142:145], v[158:161], v[32:47]
	ds_read_b128 v[142:145], v64 offset:4672
	ds_read_b128 v[166:169], v64 offset:4704
	s_waitcnt vmcnt(15)
	ds_write_b128 v66, v[78:81] offset:36864
	s_waitcnt vmcnt(14)
	ds_write_b128 v66, v[82:85] offset:55296
	s_waitcnt vmcnt(13)
	ds_write_b128 v66, v[94:97] offset:41472
	s_waitcnt vmcnt(12)
	ds_write_b128 v66, v[98:101] offset:59904
	s_waitcnt vmcnt(11)
	ds_write_b128 v66, v[102:105] offset:46080
	s_waitcnt vmcnt(10)
	ds_write_b128 v66, v[106:109] offset:64512
	s_waitcnt vmcnt(9)
	ds_write_b128 v66, v[110:113] offset:50688
	s_waitcnt vmcnt(8)
	ds_write_b128 v67, v[114:117] offset:13824
	global_load_dwordx4 v[78:81], v68, s[66:67] offset:1152
	global_load_dwordx4 v[82:85], v69, s[80:81] offset:1152
	global_load_dwordx4 v[94:97], v70, s[66:67] offset:1152
	global_load_dwordx4 v[98:101], v71, s[80:81] offset:1152
	global_load_dwordx4 v[102:105], v72, s[66:67] offset:1152
	global_load_dwordx4 v[106:109], v73, s[80:81] offset:1152
	global_load_dwordx4 v[110:113], v75, s[66:67] offset:1152
	global_load_dwordx4 v[114:117], v76, s[80:81] offset:1152
	s_waitcnt lgkmcnt(0)
	s_barrier
; template <bool SWAP, bool SS>
; __device__ __forceinline__ void gemm_main(const u16* __restrict__ A, int lda, int M, int m0,
;                                           const u16* __restrict__ Bt, int ldb, int n0, int K,
;                                           char* smraw, f32x16 (&acc)[2][2]) {
;     ...
;   auto gload = [&](u32x4 (&ga)[4], u32x4 (&gb)[4], int kt) {
; #pragma unroll
;     for (int j = 0; j < 4; ++j) { ga[j] = *(const u32x4*)(Ab + (aoff[j] + (unsigned)kt * 128u)); gb[j] = *(const u32x4*)(Bb + (boff[j] + (unsigned)kt * 128u)); }
;   };
;   auto lwrite = [&](const u32x4 (&ga)[4], const u32x4 (&gb)[4], int buf) {
;     u16* As = sm + buf * (2 * 128 * TSTR);
;     u16* Bs = As + 128 * TSTR;
; #pragma unroll
;     for (int j = 0; j < 4; ++j) {
;       *(u32x4*)(As + (lrow + 32 * j) * TSTR + kc * 8) = ga[j];
;       *(u32x4*)(Bs + (lrow + 32 * j) * TSTR + kc * 8) = gb[j];
;       if (SS) ss[j] += sumsq8(ga[j]);
;     }
;   };
;   auto compute = [&](int buf) {
;     const u16* As = sm + buf * (2 * 128 * TSTR);
;     const u16* Bs = As + 128 * TSTR;
; #pragma unroll
;     for (int ks = 0; ks < 4; ++ks) {
;       bf16x8 af[2], bf[2];
; #pragma unroll
;       for (int i = 0; i < 2; ++i) af[i] = *(const bf16x8*)(As + (wm * 64 + i * 32 + lc) * TSTR + ks * 16 + hf * 8);
; #pragma unroll
;       for (int j = 0; j < 2; ++j) bf[j] = *(const bf16x8*)(Bs + (wn * 64 + j * 32 + lc) * TSTR + ks * 16 + hf * 8);
; #pragma unroll
;       for (int i = 0; i < 2; ++i)
; #pragma unroll
;         for (int j = 0; j < 2; ++j)
;           acc[i][j] = SWAP ? mfma32(bf[j], af[i], acc[i][j]) : mfma32(af[i], bf[j], acc[i][j]);
;     }
;   };
;   u32x4 ga0[4], gb0[4], ga1[4], gb1[4];
;   gload(ga0, gb0, 0);
;   if (nk > 1) gload(ga1, gb1, 1);
;   lwrite(ga0, gb0, 0);
;   if (nk > 2) gload(ga0, gb0, 2);
;   __syncthreads();
;   for (int kt = 0; kt < nk; kt += 2) {
;     compute(0);
;     if (kt + 1 < nk) lwrite(ga1, gb1, 1);
;     if (kt + 3 < nk) gload(ga1, gb1, kt + 3);
;     __syncthreads();
;     if (kt + 1 < nk) {
;       compute(1);
;       if (kt + 2 < nk) lwrite(ga0, gb0, 0);
;       if (kt + 4 < nk) gload(ga0, gb0, kt + 4);
;       __syncthreads();
;     }
	v_mfma_f32_32x32x16_bf16 v[16:31], v[142:145], v[146:149], v[16:31]
	v_mfma_f32_32x32x16_bf16 v[0:15], v[142:145], v[158:161], v[0:15]
	v_mfma_f32_32x32x16_bf16 v[48:63], v[150:153], v[154:157], v[48:63]
	v_mfma_f32_32x32x16_bf16 v[32:47], v[150:153], v[162:165], v[32:47]
	v_mfma_f32_32x32x16_bf16 v[16:31], v[166:169], v[154:157], v[16:31]
	ds_read_b128 v[142:145], v64 offset:36864
	ds_read_b128 v[146:149], v65 offset:55296
	ds_read_b128 v[150:153], v64 offset:36896
	ds_read_b128 v[154:157], v65 offset:55328
	v_mfma_f32_32x32x16_bf16 v[0:15], v[166:169], v[162:165], v[0:15]
	ds_read_b128 v[158:161], v65 offset:59904
	ds_read_b128 v[162:165], v65 offset:59936
	s_waitcnt lgkmcnt(4)
	v_mfma_f32_32x32x16_bf16 v[48:63], v[142:145], v[146:149], v[48:63]
	s_waitcnt lgkmcnt(1)
	v_mfma_f32_32x32x16_bf16 v[32:47], v[142:145], v[158:161], v[32:47]
	ds_read_b128 v[142:145], v64 offset:41472
	ds_read_b128 v[166:169], v64 offset:41504
	s_waitcnt lgkmcnt(1)
	v_mfma_f32_32x32x16_bf16 v[16:31], v[142:145], v[146:149], v[16:31]
	v_mfma_f32_32x32x16_bf16 v[0:15], v[142:145], v[158:161], v[0:15]
	v_mfma_f32_32x32x16_bf16 v[48:63], v[150:153], v[154:157], v[48:63]
	v_mfma_f32_32x32x16_bf16 v[32:47], v[150:153], v[162:165], v[32:47]
	s_waitcnt lgkmcnt(0)
	v_mfma_f32_32x32x16_bf16 v[16:31], v[166:169], v[154:157], v[16:31]
	ds_read_b128 v[142:145], v64 offset:36928
	ds_read_b128 v[146:149], v65 offset:55360
	ds_read_b128 v[150:153], v64 offset:36960
	ds_read_b128 v[154:157], v65 offset:55392
	v_mfma_f32_32x32x16_bf16 v[0:15], v[166:169], v[162:165], v[0:15]
	ds_read_b128 v[158:161], v65 offset:59968
	ds_read_b128 v[162:165], v65 offset:60000
	s_waitcnt lgkmcnt(4)
	v_mfma_f32_32x32x16_bf16 v[48:63], v[142:145], v[146:149], v[48:63]
	s_waitcnt lgkmcnt(1)
	v_mfma_f32_32x32x16_bf16 v[32:47], v[142:145], v[158:161], v[32:47]
	ds_read_b128 v[142:145], v64 offset:41536
	ds_read_b128 v[166:169], v64 offset:41568
	s_waitcnt vmcnt(15)
	ds_write_b128 v66, v[86:89]
	s_waitcnt vmcnt(14)
	ds_write_b128 v66, v[90:93] offset:18432
	s_waitcnt vmcnt(13)
	ds_write_b128 v66, v[118:121] offset:4608
	s_waitcnt vmcnt(12)
	ds_write_b128 v66, v[122:125] offset:23040
	s_waitcnt vmcnt(11)
	ds_write_b128 v66, v[126:129] offset:9216
	s_waitcnt vmcnt(10)
	ds_write_b128 v66, v[130:133] offset:27648
	s_waitcnt vmcnt(9)
	ds_write_b128 v66, v[134:137] offset:13824
	s_waitcnt vmcnt(8)
	ds_write_b128 v66, v[138:141] offset:32256
	global_load_dwordx4 v[86:89], v68, s[66:67] offset:1280
	global_load_dwordx4 v[90:93], v69, s[80:81] offset:1280
	global_load_dwordx4 v[118:121], v70, s[66:67] offset:1280
	global_load_dwordx4 v[122:125], v71, s[80:81] offset:1280
	global_load_dwordx4 v[126:129], v72, s[66:67] offset:1280
	global_load_dwordx4 v[130:133], v73, s[80:81] offset:1280
	global_load_dwordx4 v[134:137], v75, s[66:67] offset:1280
	global_load_dwordx4 v[138:141], v76, s[80:81] offset:1280
	s_waitcnt lgkmcnt(0)
	s_barrier
	v_mfma_f32_32x32x16_bf16 v[16:31], v[142:145], v[146:149], v[16:31]
	v_mfma_f32_32x32x16_bf16 v[0:15], v[142:145], v[158:161], v[0:15]
	v_mfma_f32_32x32x16_bf16 v[48:63], v[150:153], v[154:157], v[48:63]
	v_mfma_f32_32x32x16_bf16 v[32:47], v[150:153], v[162:165], v[32:47]
	v_mfma_f32_32x32x16_bf16 v[16:31], v[166:169], v[154:157], v[16:31]
	ds_read_b128 v[142:145], v64
	ds_read_b128 v[146:149], v65 offset:18432
	ds_read_b128 v[150:153], v64 offset:32
	ds_read_b128 v[154:157], v65 offset:18464
	v_mfma_f32_32x32x16_bf16 v[0:15], v[166:169], v[162:165], v[0:15]
	ds_read_b128 v[158:161], v65 offset:23040
	ds_read_b128 v[162:165], v65 offset:23072
	s_waitcnt lgkmcnt(4)
	v_mfma_f32_32x32x16_bf16 v[48:63], v[142:145], v[146:149], v[48:63]
	s_waitcnt lgkmcnt(1)
	v_mfma_f32_32x32x16_bf16 v[32:47], v[142:145], v[158:161], v[32:47]
	ds_read_b128 v[142:145], v64 offset:4608
	ds_read_b128 v[166:169], v64 offset:4640
	s_waitcnt lgkmcnt(1)
	v_mfma_f32_32x32x16_bf16 v[16:31], v[142:145], v[146:149], v[16:31]
	v_mfma_f32_32x32x16_bf16 v[0:15], v[142:145], v[158:161], v[0:15]
	v_mfma_f32_32x32x16_bf16 v[48:63], v[150:153], v[154:157], v[48:63]
	v_mfma_f32_32x32x16_bf16 v[32:47], v[150:153], v[162:165], v[32:47]
	s_waitcnt lgkmcnt(0)
	v_mfma_f32_32x32x16_bf16 v[16:31], v[166:169], v[154:157], v[16:31]
	ds_read_b128 v[142:145], v64 offset:64
	ds_read_b128 v[146:149], v65 offset:18496
	ds_read_b128 v[150:153], v64 offset:96
	ds_read_b128 v[154:157], v65 offset:18528
	v_mfma_f32_32x32x16_bf16 v[0:15], v[166:169], v[162:165], v[0:15]
	ds_read_b128 v[158:161], v65 offset:23104
	ds_read_b128 v[162:165], v65 offset:23136
	s_waitcnt lgkmcnt(4)
	v_mfma_f32_32x32x16_bf16 v[48:63], v[142:145], v[146:149], v[48:63]
	s_waitcnt lgkmcnt(1)
	v_mfma_f32_32x32x16_bf16 v[32:47], v[142:145], v[158:161], v[32:47]
	ds_read_b128 v[142:145], v64 offset:4672
	ds_read_b128 v[166:169], v64 offset:4704
	s_waitcnt vmcnt(15)
	ds_write_b128 v66, v[78:81] offset:36864
	s_waitcnt vmcnt(14)
	ds_write_b128 v66, v[82:85] offset:55296
	s_waitcnt vmcnt(13)
	ds_write_b128 v66, v[94:97] offset:41472
	s_waitcnt vmcnt(12)
	ds_write_b128 v66, v[98:101] offset:59904
	s_waitcnt vmcnt(11)
	ds_write_b128 v66, v[102:105] offset:46080
	s_waitcnt vmcnt(10)
	ds_write_b128 v66, v[106:109] offset:64512
	s_waitcnt vmcnt(9)
	ds_write_b128 v66, v[110:113] offset:50688
	s_waitcnt vmcnt(8)
	ds_write_b128 v67, v[114:117] offset:13824
	global_load_dwordx4 v[78:81], v68, s[66:67] offset:1408
	global_load_dwordx4 v[82:85], v69, s[80:81] offset:1408
	global_load_dwordx4 v[94:97], v70, s[66:67] offset:1408
	global_load_dwordx4 v[98:101], v71, s[80:81] offset:1408
	global_load_dwordx4 v[102:105], v72, s[66:67] offset:1408
	global_load_dwordx4 v[106:109], v73, s[80:81] offset:1408
	global_load_dwordx4 v[110:113], v75, s[66:67] offset:1408
	global_load_dwordx4 v[114:117], v76, s[80:81] offset:1408
	s_waitcnt lgkmcnt(0)
	s_barrier
; template <bool SWAP, bool SS>
; __device__ __forceinline__ void gemm_main(const u16* __restrict__ A, int lda, int M, int m0,
;                                           const u16* __restrict__ Bt, int ldb, int n0, int K,
;                                           char* smraw, f32x16 (&acc)[2][2]) {
;     ...
;   auto gload = [&](u32x4 (&ga)[4], u32x4 (&gb)[4], int kt) {
; #pragma unroll
;     for (int j = 0; j < 4; ++j) { ga[j] = *(const u32x4*)(Ab + (aoff[j] + (unsigned)kt * 128u)); gb[j] = *(const u32x4*)(Bb + (boff[j] + (unsigned)kt * 128u)); }
;   };
;   auto lwrite = [&](const u32x4 (&ga)[4], const u32x4 (&gb)[4], int buf) {
;     u16* As = sm + buf * (2 * 128 * TSTR);
;     u16* Bs = As + 128 * TSTR;
; #pragma unroll
;     for (int j = 0; j < 4; ++j) {
;       *(u32x4*)(As + (lrow + 32 * j) * TSTR + kc * 8) = ga[j];
;       *(u32x4*)(Bs + (lrow + 32 * j) * TSTR + kc * 8) = gb[j];
;       if (SS) ss[j] += sumsq8(ga[j]);
;     }
;   };
;   auto compute = [&](int buf) {
;     const u16* As = sm + buf * (2 * 128 * TSTR);
;     const u16* Bs = As + 128 * TSTR;
; #pragma unroll
;     for (int ks = 0; ks < 4; ++ks) {
;       bf16x8 af[2], bf[2];
; #pragma unroll
;       for (int i = 0; i < 2; ++i) af[i] = *(const bf16x8*)(As + (wm * 64 + i * 32 + lc) * TSTR + ks * 16 + hf * 8);
; #pragma unroll
;       for (int j = 0; j < 2; ++j) bf[j] = *(const bf16x8*)(Bs + (wn * 64 + j * 32 + lc) * TSTR + ks * 16 + hf * 8);
; #pragma unroll
;       for (int i = 0; i < 2; ++i)
; #pragma unroll
;         for (int j = 0; j < 2; ++j)
;           acc[i][j] = SWAP ? mfma32(bf[j], af[i], acc[i][j]) : mfma32(af[i], bf[j], acc[i][j]);
;     }
;   };
;   u32x4 ga0[4], gb0[4], ga1[4], gb1[4];
;   gload(ga0, gb0, 0);
;   if (nk > 1) gload(ga1, gb1, 1);
;   lwrite(ga0, gb0, 0);
;   if (nk > 2) gload(ga0, gb0, 2);
;   __syncthreads();
;   for (int kt = 0; kt < nk; kt += 2) {
;     compute(0);
;     if (kt + 1 < nk) lwrite(ga1, gb1, 1);
;     if (kt + 3 < nk) gload(ga1, gb1, kt + 3);
;     __syncthreads();
;     if (kt + 1 < nk) {
;       compute(1);
;       if (kt + 2 < nk) lwrite(ga0, gb0, 0);
;       if (kt + 4 < nk) gload(ga0, gb0, kt + 4);
;       __syncthreads();
;     }
	v_mfma_f32_32x32x16_bf16 v[16:31], v[142:145], v[146:149], v[16:31]
	v_mfma_f32_32x32x16_bf16 v[0:15], v[142:145], v[158:161], v[0:15]
	v_mfma_f32_32x32x16_bf16 v[48:63], v[150:153], v[154:157], v[48:63]
	v_mfma_f32_32x32x16_bf16 v[32:47], v[150:153], v[162:165], v[32:47]
	v_mfma_f32_32x32x16_bf16 v[16:31], v[166:169], v[154:157], v[16:31]
	ds_read_b128 v[142:145], v64 offset:36864
	ds_read_b128 v[146:149], v65 offset:55296
	ds_read_b128 v[150:153], v64 offset:36896
	ds_read_b128 v[154:157], v65 offset:55328
	v_mfma_f32_32x32x16_bf16 v[0:15], v[166:169], v[162:165], v[0:15]
	ds_read_b128 v[158:161], v65 offset:59904
	ds_read_b128 v[162:165], v65 offset:59936
	s_waitcnt lgkmcnt(4)
	v_mfma_f32_32x32x16_bf16 v[48:63], v[142:145], v[146:149], v[48:63]
	s_waitcnt lgkmcnt(1)
	v_mfma_f32_32x32x16_bf16 v[32:47], v[142:145], v[158:161], v[32:47]
	ds_read_b128 v[142:145], v64 offset:41472
	ds_read_b128 v[166:169], v64 offset:41504
	s_waitcnt lgkmcnt(1)
	v_mfma_f32_32x32x16_bf16 v[16:31], v[142:145], v[146:149], v[16:31]
	v_mfma_f32_32x32x16_bf16 v[0:15], v[142:145], v[158:161], v[0:15]
	v_mfma_f32_32x32x16_bf16 v[48:63], v[150:153], v[154:157], v[48:63]
	v_mfma_f32_32x32x16_bf16 v[32:47], v[150:153], v[162:165], v[32:47]
	s_waitcnt lgkmcnt(0)
	v_mfma_f32_32x32x16_bf16 v[16:31], v[166:169], v[154:157], v[16:31]
	ds_read_b128 v[142:145], v64 offset:36928
	ds_read_b128 v[146:149], v65 offset:55360
	ds_read_b128 v[150:153], v64 offset:36960
	ds_read_b128 v[154:157], v65 offset:55392
	v_mfma_f32_32x32x16_bf16 v[0:15], v[166:169], v[162:165], v[0:15]
	ds_read_b128 v[158:161], v65 offset:59968
	ds_read_b128 v[162:165], v65 offset:60000
	s_waitcnt lgkmcnt(4)
	v_mfma_f32_32x32x16_bf16 v[48:63], v[142:145], v[146:149], v[48:63]
	s_waitcnt lgkmcnt(1)
	v_mfma_f32_32x32x16_bf16 v[32:47], v[142:145], v[158:161], v[32:47]
	ds_read_b128 v[142:145], v64 offset:41536
	ds_read_b128 v[166:169], v64 offset:41568
	s_waitcnt vmcnt(15)
	ds_write_b128 v66, v[86:89]
	s_waitcnt vmcnt(14)
	ds_write_b128 v66, v[90:93] offset:18432
	s_waitcnt vmcnt(13)
	ds_write_b128 v66, v[118:121] offset:4608
	s_waitcnt vmcnt(12)
	ds_write_b128 v66, v[122:125] offset:23040
	s_waitcnt vmcnt(11)
	ds_write_b128 v66, v[126:129] offset:9216
	s_waitcnt vmcnt(10)
	ds_write_b128 v66, v[130:133] offset:27648
	s_waitcnt vmcnt(9)
	ds_write_b128 v66, v[134:137] offset:13824
	s_waitcnt vmcnt(8)
	ds_write_b128 v66, v[138:141] offset:32256
	global_load_dwordx4 v[86:89], v68, s[66:67] offset:1536
	global_load_dwordx4 v[90:93], v69, s[80:81] offset:1536
	global_load_dwordx4 v[118:121], v70, s[66:67] offset:1536
	global_load_dwordx4 v[122:125], v71, s[80:81] offset:1536
	global_load_dwordx4 v[126:129], v72, s[66:67] offset:1536
	global_load_dwordx4 v[130:133], v73, s[80:81] offset:1536
	global_load_dwordx4 v[134:137], v75, s[66:67] offset:1536
	global_load_dwordx4 v[138:141], v76, s[80:81] offset:1536
	s_waitcnt lgkmcnt(0)
	s_barrier
	v_mfma_f32_32x32x16_bf16 v[16:31], v[142:145], v[146:149], v[16:31]
	v_mfma_f32_32x32x16_bf16 v[0:15], v[142:145], v[158:161], v[0:15]
	v_mfma_f32_32x32x16_bf16 v[48:63], v[150:153], v[154:157], v[48:63]
	v_mfma_f32_32x32x16_bf16 v[32:47], v[150:153], v[162:165], v[32:47]
	v_mfma_f32_32x32x16_bf16 v[16:31], v[166:169], v[154:157], v[16:31]
	ds_read_b128 v[142:145], v64
	ds_read_b128 v[146:149], v65 offset:18432
	ds_read_b128 v[150:153], v64 offset:32
	ds_read_b128 v[154:157], v65 offset:18464
	v_mfma_f32_32x32x16_bf16 v[0:15], v[166:169], v[162:165], v[0:15]
	ds_read_b128 v[158:161], v65 offset:23040
	ds_read_b128 v[162:165], v65 offset:23072
	s_waitcnt lgkmcnt(4)
	v_mfma_f32_32x32x16_bf16 v[48:63], v[142:145], v[146:149], v[48:63]
	s_waitcnt lgkmcnt(1)
	v_mfma_f32_32x32x16_bf16 v[32:47], v[142:145], v[158:161], v[32:47]
	ds_read_b128 v[142:145], v64 offset:4608
	ds_read_b128 v[166:169], v64 offset:4640
	s_waitcnt lgkmcnt(1)
	v_mfma_f32_32x32x16_bf16 v[16:31], v[142:145], v[146:149], v[16:31]
	v_mfma_f32_32x32x16_bf16 v[0:15], v[142:145], v[158:161], v[0:15]
	v_mfma_f32_32x32x16_bf16 v[48:63], v[150:153], v[154:157], v[48:63]
	v_mfma_f32_32x32x16_bf16 v[32:47], v[150:153], v[162:165], v[32:47]
	s_waitcnt lgkmcnt(0)
	v_mfma_f32_32x32x16_bf16 v[16:31], v[166:169], v[154:157], v[16:31]
	ds_read_b128 v[142:145], v64 offset:64
	ds_read_b128 v[146:149], v65 offset:18496
	ds_read_b128 v[150:153], v64 offset:96
	ds_read_b128 v[154:157], v65 offset:18528
	v_mfma_f32_32x32x16_bf16 v[0:15], v[166:169], v[162:165], v[0:15]
	ds_read_b128 v[158:161], v65 offset:23104
	ds_read_b128 v[162:165], v65 offset:23136
	s_waitcnt lgkmcnt(4)
	v_mfma_f32_32x32x16_bf16 v[48:63], v[142:145], v[146:149], v[48:63]
	s_waitcnt lgkmcnt(1)
	v_mfma_f32_32x32x16_bf16 v[32:47], v[142:145], v[158:161], v[32:47]
	ds_read_b128 v[142:145], v64 offset:4672
	ds_read_b128 v[166:169], v64 offset:4704
	s_waitcnt vmcnt(15)
	ds_write_b128 v66, v[78:81] offset:36864
	s_waitcnt vmcnt(14)
	ds_write_b128 v66, v[82:85] offset:55296
	s_waitcnt vmcnt(13)
	ds_write_b128 v66, v[94:97] offset:41472
	s_waitcnt vmcnt(12)
	ds_write_b128 v66, v[98:101] offset:59904
	s_waitcnt vmcnt(11)
	ds_write_b128 v66, v[102:105] offset:46080
	s_waitcnt vmcnt(10)
	ds_write_b128 v66, v[106:109] offset:64512
	s_waitcnt vmcnt(9)
	ds_write_b128 v66, v[110:113] offset:50688
	s_waitcnt vmcnt(8)
	ds_write_b128 v67, v[114:117] offset:13824
	global_load_dwordx4 v[78:81], v68, s[66:67] offset:1664
	global_load_dwordx4 v[82:85], v69, s[80:81] offset:1664
	global_load_dwordx4 v[94:97], v70, s[66:67] offset:1664
	global_load_dwordx4 v[98:101], v71, s[80:81] offset:1664
	global_load_dwordx4 v[102:105], v72, s[66:67] offset:1664
	global_load_dwordx4 v[106:109], v73, s[80:81] offset:1664
	global_load_dwordx4 v[110:113], v75, s[66:67] offset:1664
	global_load_dwordx4 v[114:117], v76, s[80:81] offset:1664
	s_waitcnt lgkmcnt(0)
	s_barrier
; template <bool SWAP, bool SS>
; __device__ __forceinline__ void gemm_main(const u16* __restrict__ A, int lda, int M, int m0,
;                                           const u16* __restrict__ Bt, int ldb, int n0, int K,
;                                           char* smraw, f32x16 (&acc)[2][2]) {
;     ...
;   auto gload = [&](u32x4 (&ga)[4], u32x4 (&gb)[4], int kt) {
; #pragma unroll
;     for (int j = 0; j < 4; ++j) { ga[j] = *(const u32x4*)(Ab + (aoff[j] + (unsigned)kt * 128u)); gb[j] = *(const u32x4*)(Bb + (boff[j] + (unsigned)kt * 128u)); }
;   };
;   auto lwrite = [&](const u32x4 (&ga)[4], const u32x4 (&gb)[4], int buf) {
;     u16* As = sm + buf * (2 * 128 * TSTR);
;     u16* Bs = As + 128 * TSTR;
; #pragma unroll
;     for (int j = 0; j < 4; ++j) {
;       *(u32x4*)(As + (lrow + 32 * j) * TSTR + kc * 8) = ga[j];
;       *(u32x4*)(Bs + (lrow + 32 * j) * TSTR + kc * 8) = gb[j];
;       if (SS) ss[j] += sumsq8(ga[j]);
;     }
;   };
;   auto compute = [&](int buf) {
;     const u16* As = sm + buf * (2 * 128 * TSTR);
;     const u16* Bs = As + 128 * TSTR;
; #pragma unroll
;     for (int ks = 0; ks < 4; ++ks) {
;       bf16x8 af[2], bf[2];
; #pragma unroll
;       for (int i = 0; i < 2; ++i) af[i] = *(const bf16x8*)(As + (wm * 64 + i * 32 + lc) * TSTR + ks * 16 + hf * 8);
; #pragma unroll
;       for (int j = 0; j < 2; ++j) bf[j] = *(const bf16x8*)(Bs + (wn * 64 + j * 32 + lc) * TSTR + ks * 16 + hf * 8);
; #pragma unroll
;       for (int i = 0; i < 2; ++i)
; #pragma unroll
;         for (int j = 0; j < 2; ++j)
;           acc[i][j] = SWAP ? mfma32(bf[j], af[i], acc[i][j]) : mfma32(af[i], bf[j], acc[i][j]);
;     }
;   };
;   u32x4 ga0[4], gb0[4], ga1[4], gb1[4];
;   gload(ga0, gb0, 0);
;   if (nk > 1) gload(ga1, gb1, 1);
;   lwrite(ga0, gb0, 0);
;   if (nk > 2) gload(ga0, gb0, 2);
;   __syncthreads();
;   for (int kt = 0; kt < nk; kt += 2) {
;     compute(0);
;     if (kt + 1 < nk) lwrite(ga1, gb1, 1);
;     if (kt + 3 < nk) gload(ga1, gb1, kt + 3);
;     __syncthreads();
;     if (kt + 1 < nk) {
;       compute(1);
;       if (kt + 2 < nk) lwrite(ga0, gb0, 0);
;       if (kt + 4 < nk) gload(ga0, gb0, kt + 4);
;       __syncthreads();
;     }
	v_mfma_f32_32x32x16_bf16 v[16:31], v[142:145], v[146:149], v[16:31]
	v_mfma_f32_32x32x16_bf16 v[0:15], v[142:145], v[158:161], v[0:15]
	v_mfma_f32_32x32x16_bf16 v[48:63], v[150:153], v[154:157], v[48:63]
	v_mfma_f32_32x32x16_bf16 v[32:47], v[150:153], v[162:165], v[32:47]
	v_mfma_f32_32x32x16_bf16 v[16:31], v[166:169], v[154:157], v[16:31]
	ds_read_b128 v[142:145], v64 offset:36864
	ds_read_b128 v[146:149], v65 offset:55296
	ds_read_b128 v[150:153], v64 offset:36896
	ds_read_b128 v[154:157], v65 offset:55328
	v_mfma_f32_32x32x16_bf16 v[0:15], v[166:169], v[162:165], v[0:15]
	ds_read_b128 v[158:161], v65 offset:59904
	ds_read_b128 v[162:165], v65 offset:59936
	s_waitcnt lgkmcnt(4)
	v_mfma_f32_32x32x16_bf16 v[48:63], v[142:145], v[146:149], v[48:63]
	s_waitcnt lgkmcnt(1)
	v_mfma_f32_32x32x16_bf16 v[32:47], v[142:145], v[158:161], v[32:47]
	ds_read_b128 v[142:145], v64 offset:41472
	ds_read_b128 v[166:169], v64 offset:41504
	s_waitcnt lgkmcnt(1)
	v_mfma_f32_32x32x16_bf16 v[16:31], v[142:145], v[146:149], v[16:31]
	v_mfma_f32_32x32x16_bf16 v[0:15], v[142:145], v[158:161], v[0:15]
	v_mfma_f32_32x32x16_bf16 v[48:63], v[150:153], v[154:157], v[48:63]
	v_mfma_f32_32x32x16_bf16 v[32:47], v[150:153], v[162:165], v[32:47]
	s_waitcnt lgkmcnt(0)
	v_mfma_f32_32x32x16_bf16 v[16:31], v[166:169], v[154:157], v[16:31]
	ds_read_b128 v[142:145], v64 offset:36928
	ds_read_b128 v[146:149], v65 offset:55360
	ds_read_b128 v[150:153], v64 offset:36960
	ds_read_b128 v[154:157], v65 offset:55392
	v_mfma_f32_32x32x16_bf16 v[0:15], v[166:169], v[162:165], v[0:15]
	ds_read_b128 v[158:161], v65 offset:59968
	ds_read_b128 v[162:165], v65 offset:60000
	s_waitcnt lgkmcnt(4)
	v_mfma_f32_32x32x16_bf16 v[48:63], v[142:145], v[146:149], v[48:63]
	s_waitcnt lgkmcnt(1)
	v_mfma_f32_32x32x16_bf16 v[32:47], v[142:145], v[158:161], v[32:47]
	ds_read_b128 v[142:145], v64 offset:41536
	ds_read_b128 v[166:169], v64 offset:41568
	s_waitcnt vmcnt(15)
	ds_write_b128 v66, v[86:89]
	s_waitcnt vmcnt(14)
	ds_write_b128 v66, v[90:93] offset:18432
	s_waitcnt vmcnt(13)
	ds_write_b128 v66, v[118:121] offset:4608
	s_waitcnt vmcnt(12)
	ds_write_b128 v66, v[122:125] offset:23040
	s_waitcnt vmcnt(11)
	ds_write_b128 v66, v[126:129] offset:9216
	s_waitcnt vmcnt(10)
	ds_write_b128 v66, v[130:133] offset:27648
	s_waitcnt vmcnt(9)
	ds_write_b128 v66, v[134:137] offset:13824
	s_waitcnt vmcnt(8)
	ds_write_b128 v66, v[138:141] offset:32256
	global_load_dwordx4 v[86:89], v68, s[66:67] offset:1792
	global_load_dwordx4 v[90:93], v69, s[80:81] offset:1792
	global_load_dwordx4 v[118:121], v70, s[66:67] offset:1792
	global_load_dwordx4 v[122:125], v71, s[80:81] offset:1792
	global_load_dwordx4 v[126:129], v72, s[66:67] offset:1792
	global_load_dwordx4 v[130:133], v73, s[80:81] offset:1792
	global_load_dwordx4 v[134:137], v75, s[66:67] offset:1792
	global_load_dwordx4 v[138:141], v76, s[80:81] offset:1792
	s_waitcnt lgkmcnt(0)
	s_barrier
	v_mfma_f32_32x32x16_bf16 v[16:31], v[142:145], v[146:149], v[16:31]
	v_mfma_f32_32x32x16_bf16 v[0:15], v[142:145], v[158:161], v[0:15]
	v_mfma_f32_32x32x16_bf16 v[48:63], v[150:153], v[154:157], v[48:63]
	v_mfma_f32_32x32x16_bf16 v[32:47], v[150:153], v[162:165], v[32:47]
	v_mfma_f32_32x32x16_bf16 v[16:31], v[166:169], v[154:157], v[16:31]
	ds_read_b128 v[142:145], v64
	ds_read_b128 v[146:149], v65 offset:18432
	ds_read_b128 v[150:153], v64 offset:32
	ds_read_b128 v[154:157], v65 offset:18464
	v_mfma_f32_32x32x16_bf16 v[0:15], v[166:169], v[162:165], v[0:15]
	ds_read_b128 v[158:161], v65 offset:23040
	ds_read_b128 v[162:165], v65 offset:23072
	s_waitcnt lgkmcnt(4)
	v_mfma_f32_32x32x16_bf16 v[48:63], v[142:145], v[146:149], v[48:63]
	s_waitcnt lgkmcnt(1)
	v_mfma_f32_32x32x16_bf16 v[32:47], v[142:145], v[158:161], v[32:47]
	ds_read_b128 v[142:145], v64 offset:4608
	ds_read_b128 v[166:169], v64 offset:4640
	s_waitcnt lgkmcnt(1)
	v_mfma_f32_32x32x16_bf16 v[16:31], v[142:145], v[146:149], v[16:31]
	v_mfma_f32_32x32x16_bf16 v[0:15], v[142:145], v[158:161], v[0:15]
	v_mfma_f32_32x32x16_bf16 v[48:63], v[150:153], v[154:157], v[48:63]
	v_mfma_f32_32x32x16_bf16 v[32:47], v[150:153], v[162:165], v[32:47]
	s_waitcnt lgkmcnt(0)
	v_mfma_f32_32x32x16_bf16 v[16:31], v[166:169], v[154:157], v[16:31]
	ds_read_b128 v[142:145], v64 offset:64
	ds_read_b128 v[146:149], v65 offset:18496
	ds_read_b128 v[150:153], v64 offset:96
	ds_read_b128 v[154:157], v65 offset:18528
	v_mfma_f32_32x32x16_bf16 v[0:15], v[166:169], v[162:165], v[0:15]
	ds_read_b128 v[158:161], v65 offset:23104
	ds_read_b128 v[162:165], v65 offset:23136
	s_waitcnt lgkmcnt(4)
	v_mfma_f32_32x32x16_bf16 v[48:63], v[142:145], v[146:149], v[48:63]
	s_waitcnt lgkmcnt(1)
	v_mfma_f32_32x32x16_bf16 v[32:47], v[142:145], v[158:161], v[32:47]
	ds_read_b128 v[142:145], v64 offset:4672
	ds_read_b128 v[166:169], v64 offset:4704
	s_waitcnt vmcnt(15)
	ds_write_b128 v66, v[78:81] offset:36864
	s_waitcnt vmcnt(14)
	ds_write_b128 v66, v[82:85] offset:55296
	s_waitcnt vmcnt(13)
	ds_write_b128 v66, v[94:97] offset:41472
	s_waitcnt vmcnt(12)
	ds_write_b128 v66, v[98:101] offset:59904
	s_waitcnt vmcnt(11)
	ds_write_b128 v66, v[102:105] offset:46080
	s_waitcnt vmcnt(10)
	ds_write_b128 v66, v[106:109] offset:64512
	s_waitcnt vmcnt(9)
	ds_write_b128 v66, v[110:113] offset:50688
	s_waitcnt vmcnt(8)
	ds_write_b128 v67, v[114:117] offset:13824
	global_load_dwordx4 v[78:81], v68, s[66:67] offset:1920
	global_load_dwordx4 v[82:85], v69, s[80:81] offset:1920
	global_load_dwordx4 v[94:97], v70, s[66:67] offset:1920
	s_nop 0
	global_load_dwordx4 v[68:71], v71, s[80:81] offset:1920
	s_nop 0
	global_load_dwordx4 v[98:101], v72, s[66:67] offset:1920
	global_load_dwordx4 v[102:105], v73, s[80:81] offset:1920
	global_load_dwordx4 v[106:109], v75, s[66:67] offset:1920
	global_load_dwordx4 v[110:113], v76, s[80:81] offset:1920
	s_waitcnt lgkmcnt(0)
	s_barrier
; template <bool SWAP, bool SS>
; __device__ __forceinline__ void gemm_main(const u16* __restrict__ A, int lda, int M, int m0,
;                                           const u16* __restrict__ Bt, int ldb, int n0, int K,
;                                           char* smraw, f32x16 (&acc)[2][2]) {
;     ...
;   auto gload = [&](u32x4 (&ga)[4], u32x4 (&gb)[4], int kt) {
; #pragma unroll
;     for (int j = 0; j < 4; ++j) { ga[j] = *(const u32x4*)(Ab + (aoff[j] + (unsigned)kt * 128u)); gb[j] = *(const u32x4*)(Bb + (boff[j] + (unsigned)kt * 128u)); }
;   };
;   auto lwrite = [&](const u32x4 (&ga)[4], const u32x4 (&gb)[4], int buf) {
;     u16* As = sm + buf * (2 * 128 * TSTR);
;     u16* Bs = As + 128 * TSTR;
; #pragma unroll
;     for (int j = 0; j < 4; ++j) {
;       *(u32x4*)(As + (lrow + 32 * j) * TSTR + kc * 8) = ga[j];
;       *(u32x4*)(Bs + (lrow + 32 * j) * TSTR + kc * 8) = gb[j];
;       if (SS) ss[j] += sumsq8(ga[j]);
;     }
;   };
;   auto compute = [&](int buf) {
;     const u16* As = sm + buf * (2 * 128 * TSTR);
;     const u16* Bs = As + 128 * TSTR;
; #pragma unroll
;     for (int ks = 0; ks < 4; ++ks) {
;       bf16x8 af[2], bf[2];
; #pragma unroll
;       for (int i = 0; i < 2; ++i) af[i] = *(const bf16x8*)(As + (wm * 64 + i * 32 + lc) * TSTR + ks * 16 + hf * 8);
; #pragma unroll
;       for (int j = 0; j < 2; ++j) bf[j] = *(const bf16x8*)(Bs + (wn * 64 + j * 32 + lc) * TSTR + ks * 16 + hf * 8);
; #pragma unroll
;       for (int i = 0; i < 2; ++i)
; #pragma unroll
;         for (int j = 0; j < 2; ++j)
;           acc[i][j] = SWAP ? mfma32(bf[j], af[i], acc[i][j]) : mfma32(af[i], bf[j], acc[i][j]);
;     }
;   };
;   u32x4 ga0[4], gb0[4], ga1[4], gb1[4];
;   gload(ga0, gb0, 0);
;   if (nk > 1) gload(ga1, gb1, 1);
;   lwrite(ga0, gb0, 0);
;   if (nk > 2) gload(ga0, gb0, 2);
;   __syncthreads();
;   for (int kt = 0; kt < nk; kt += 2) {
;     compute(0);
;     if (kt + 1 < nk) lwrite(ga1, gb1, 1);
;     if (kt + 3 < nk) gload(ga1, gb1, kt + 3);
;     __syncthreads();
;     if (kt + 1 < nk) {
;       compute(1);
;       if (kt + 2 < nk) lwrite(ga0, gb0, 0);
;       if (kt + 4 < nk) gload(ga0, gb0, kt + 4);
;       __syncthreads();
;     }
	v_mfma_f32_32x32x16_bf16 v[16:31], v[142:145], v[146:149], v[16:31]
	v_mfma_f32_32x32x16_bf16 v[0:15], v[142:145], v[158:161], v[0:15]
	v_mfma_f32_32x32x16_bf16 v[48:63], v[150:153], v[154:157], v[48:63]
	v_mfma_f32_32x32x16_bf16 v[32:47], v[150:153], v[162:165], v[32:47]
	ds_read_b128 v[114:117], v64 offset:36864
	ds_read_b128 v[142:145], v65 offset:55296
	ds_read_b128 v[146:149], v64 offset:36896
	ds_read_b128 v[150:153], v65 offset:55328
	v_mfma_f32_32x32x16_bf16 v[16:31], v[166:169], v[154:157], v[16:31]
	ds_read_b128 v[154:157], v65 offset:59904
	ds_read_b128 v[158:161], v65 offset:59936
	v_mfma_f32_32x32x16_bf16 v[0:15], v[166:169], v[162:165], v[0:15]
	s_waitcnt lgkmcnt(4)
	v_mfma_f32_32x32x16_bf16 v[48:63], v[114:117], v[142:145], v[48:63]
	s_waitcnt lgkmcnt(1)
	v_mfma_f32_32x32x16_bf16 v[32:47], v[114:117], v[154:157], v[32:47]
	ds_read_b128 v[114:117], v64 offset:41472
	ds_read_b128 v[162:165], v64 offset:41504
	s_waitcnt lgkmcnt(1)
	v_mfma_f32_32x32x16_bf16 v[16:31], v[114:117], v[142:145], v[16:31]
	v_mfma_f32_32x32x16_bf16 v[0:15], v[114:117], v[154:157], v[0:15]
	v_mfma_f32_32x32x16_bf16 v[48:63], v[146:149], v[150:153], v[48:63]
	v_mfma_f32_32x32x16_bf16 v[32:47], v[146:149], v[158:161], v[32:47]
	s_waitcnt lgkmcnt(0)
	v_mfma_f32_32x32x16_bf16 v[16:31], v[162:165], v[150:153], v[16:31]
	ds_read_b128 v[114:117], v64 offset:36928
	ds_read_b128 v[142:145], v65 offset:55360
	ds_read_b128 v[146:149], v64 offset:36960
	ds_read_b128 v[150:153], v65 offset:55392
	v_mfma_f32_32x32x16_bf16 v[0:15], v[162:165], v[158:161], v[0:15]
	ds_read_b128 v[154:157], v65 offset:59968
	ds_read_b128 v[158:161], v65 offset:60000
	s_waitcnt lgkmcnt(4)
	v_mfma_f32_32x32x16_bf16 v[48:63], v[114:117], v[142:145], v[48:63]
	s_waitcnt lgkmcnt(1)
	v_mfma_f32_32x32x16_bf16 v[32:47], v[114:117], v[154:157], v[32:47]
	ds_read_b128 v[114:117], v64 offset:41536
	ds_read_b128 v[162:165], v64 offset:41568
	s_waitcnt vmcnt(15)
	ds_write_b128 v66, v[86:89]
	s_waitcnt vmcnt(14)
	ds_write_b128 v66, v[90:93] offset:18432
	s_waitcnt vmcnt(13)
	ds_write_b128 v66, v[118:121] offset:4608
	s_waitcnt vmcnt(12)
	ds_write_b128 v66, v[122:125] offset:23040
	s_waitcnt vmcnt(11)
	ds_write_b128 v66, v[126:129] offset:9216
	s_waitcnt vmcnt(10)
	ds_write_b128 v66, v[130:133] offset:27648
	s_waitcnt vmcnt(9)
	ds_write_b128 v66, v[134:137] offset:13824
	s_waitcnt vmcnt(8)
	ds_write_b128 v66, v[138:141] offset:32256
	s_waitcnt lgkmcnt(0)
	s_barrier
	v_mfma_f32_32x32x16_bf16 v[16:31], v[114:117], v[142:145], v[16:31]
	v_mfma_f32_32x32x16_bf16 v[0:15], v[114:117], v[154:157], v[0:15]
	ds_read_b128 v[86:89], v64
	ds_read_b128 v[90:93], v65 offset:18432
	ds_read_b128 v[114:117], v64 offset:32
	ds_read_b128 v[118:121], v65 offset:18464
	ds_read_b128 v[122:125], v65 offset:23040
	ds_read_b128 v[126:129], v65 offset:23072
	v_mfma_f32_32x32x16_bf16 v[48:63], v[146:149], v[150:153], v[48:63]
	v_mfma_f32_32x32x16_bf16 v[32:47], v[146:149], v[158:161], v[32:47]
	v_mfma_f32_32x32x16_bf16 v[16:31], v[162:165], v[150:153], v[16:31]
	v_mfma_f32_32x32x16_bf16 v[0:15], v[162:165], v[158:161], v[0:15]
	s_waitcnt lgkmcnt(4)
	v_mfma_f32_32x32x16_bf16 v[48:63], v[86:89], v[90:93], v[48:63]
	s_waitcnt lgkmcnt(1)
	v_mfma_f32_32x32x16_bf16 v[32:47], v[86:89], v[122:125], v[32:47]
	ds_read_b128 v[86:89], v64 offset:4608
	ds_read_b128 v[130:133], v64 offset:4640
	s_waitcnt lgkmcnt(1)
	v_mfma_f32_32x32x16_bf16 v[16:31], v[86:89], v[90:93], v[16:31]
	v_mfma_f32_32x32x16_bf16 v[0:15], v[86:89], v[122:125], v[0:15]
	v_mfma_f32_32x32x16_bf16 v[48:63], v[114:117], v[118:121], v[48:63]
	v_mfma_f32_32x32x16_bf16 v[32:47], v[114:117], v[126:129], v[32:47]
	s_waitcnt lgkmcnt(0)
	v_mfma_f32_32x32x16_bf16 v[16:31], v[130:133], v[118:121], v[16:31]
	ds_read_b128 v[86:89], v64 offset:64
	ds_read_b128 v[90:93], v65 offset:18496
	ds_read_b128 v[114:117], v64 offset:96
	ds_read_b128 v[118:121], v65 offset:18528
	v_mfma_f32_32x32x16_bf16 v[0:15], v[130:133], v[126:129], v[0:15]
	ds_read_b128 v[122:125], v65 offset:23104
	ds_read_b128 v[126:129], v65 offset:23136
	s_waitcnt lgkmcnt(4)
	v_mfma_f32_32x32x16_bf16 v[48:63], v[86:89], v[90:93], v[48:63]
	s_waitcnt lgkmcnt(1)
	v_mfma_f32_32x32x16_bf16 v[32:47], v[86:89], v[122:125], v[32:47]
	ds_read_b128 v[86:89], v64 offset:4672
	ds_read_b128 v[130:133], v64 offset:4704
	s_waitcnt vmcnt(7)
	ds_write_b128 v66, v[78:81] offset:36864
	s_waitcnt vmcnt(6)
	ds_write_b128 v66, v[82:85] offset:55296
	s_waitcnt vmcnt(5)
	ds_write_b128 v66, v[94:97] offset:41472
	s_waitcnt vmcnt(4)
	ds_write_b128 v66, v[68:71] offset:59904
	s_waitcnt vmcnt(3)
	ds_write_b128 v66, v[98:101] offset:46080
	s_waitcnt vmcnt(2)
	ds_write_b128 v66, v[102:105] offset:64512
	s_waitcnt vmcnt(1)
	ds_write_b128 v66, v[106:109] offset:50688
	s_waitcnt vmcnt(0)
	ds_write_b128 v67, v[110:113] offset:13824
	s_waitcnt lgkmcnt(0)
	s_barrier
; __device__ __forceinline__ int tid_opaque() { int t = threadIdx.x; asm volatile("" : "+v"(t)); return t; }
; __device__ __forceinline__ int crow(int r, int hf) { return (r & 3) + 8 * (r >> 2) + 4 * hf; }
; template <bool SWAP, bool SS>
; __device__ __forceinline__ void gemm_main(const u16* __restrict__ A, int lda, int M, int m0,
;                                           const u16* __restrict__ Bt, int ldb, int n0, int K,
;                                           char* smraw, f32x16 (&acc)[2][2]) {
;     ...
;   auto compute = [&](int buf) {
;     const u16* As = sm + buf * (2 * 128 * TSTR);
;     const u16* Bs = As + 128 * TSTR;
; #pragma unroll
;     for (int ks = 0; ks < 4; ++ks) {
;       bf16x8 af[2], bf[2];
; #pragma unroll
;       for (int i = 0; i < 2; ++i) af[i] = *(const bf16x8*)(As + (wm * 64 + i * 32 + lc) * TSTR + ks * 16 + hf * 8);
; #pragma unroll
;       for (int j = 0; j < 2; ++j) bf[j] = *(const bf16x8*)(Bs + (wn * 64 + j * 32 + lc) * TSTR + ks * 16 + hf * 8);
; #pragma unroll
;       for (int i = 0; i < 2; ++i)
; #pragma unroll
;         for (int j = 0; j < 2; ++j)
;           acc[i][j] = SWAP ? mfma32(bf[j], af[i], acc[i][j]) : mfma32(af[i], bf[j], acc[i][j]);
;     }
;   };
; template <bool FIRST>
; __device__ __forceinline__ void residual_epilogue(const Params& p, f32x16 (&acc)[2][2], int m0, int ncolbase) {
;   const int tid = tid_opaque(), w = tid >> 6, l = tid & 63, lc = l & 31, hf = l >> 5;
;   const int wm = w >> 1, wn = w & 1;
; #pragma unroll
;   for (int i = 0; i < 2; ++i)
; #pragma unroll
;     for (int r = 0; r < 16; ++r) {
;       const int t = m0 + wm * 64 + i * 32 + crow(r, hf);
;       if (t < T) {
;         float* hp = hrow(p, t);
;         const float* hsrc = hp;
;         if (FIRST) { const int b = t / L, pp = t - b * L; hsrc = pp < NM ? p.meta + (size_t)pp * D : p.x + (size_t)(b * SEQ + pp - NM) * D; }
; #pragma unroll
;         for (int j = 0; j < 2; ++j) {
;           const int n = ncolbase + wn * 64 + j * 32 + lc;
;           float v = hsrc[n] + acc[i][j][r];
	ds_read_b128 v[66:69], v64 offset:36864
	ds_read_b128 v[70:73], v65 offset:55296
	ds_read_b128 v[76:79], v64 offset:36896
	ds_read_b128 v[80:83], v65 offset:55328
	v_mfma_f32_32x32x16_bf16 v[16:31], v[86:89], v[90:93], v[16:31]
	v_mfma_f32_32x32x16_bf16 v[0:15], v[86:89], v[122:125], v[0:15]
	ds_read_b128 v[84:87], v65 offset:59904
	ds_read_b128 v[88:91], v65 offset:59936
	v_mfma_f32_32x32x16_bf16 v[48:63], v[114:117], v[118:121], v[48:63]
	v_mfma_f32_32x32x16_bf16 v[32:47], v[114:117], v[126:129], v[32:47]
	v_mfma_f32_32x32x16_bf16 v[16:31], v[130:133], v[118:121], v[16:31]
	v_mfma_f32_32x32x16_bf16 v[0:15], v[130:133], v[126:129], v[0:15]
	s_waitcnt lgkmcnt(4)
	v_mfma_f32_32x32x16_bf16 v[48:63], v[66:69], v[70:73], v[48:63]
	s_waitcnt lgkmcnt(1)
	v_mfma_f32_32x32x16_bf16 v[32:47], v[66:69], v[84:87], v[32:47]
	ds_read_b128 v[66:69], v64 offset:41472
	ds_read_b128 v[92:95], v64 offset:41504
	s_waitcnt lgkmcnt(1)
	v_mfma_f32_32x32x16_bf16 v[16:31], v[66:69], v[70:73], v[16:31]
	v_mfma_f32_32x32x16_bf16 v[0:15], v[66:69], v[84:87], v[0:15]
	v_mfma_f32_32x32x16_bf16 v[48:63], v[76:79], v[80:83], v[48:63]
	v_mfma_f32_32x32x16_bf16 v[32:47], v[76:79], v[88:91], v[32:47]
	s_waitcnt lgkmcnt(0)
	v_mfma_f32_32x32x16_bf16 v[16:31], v[92:95], v[80:83], v[16:31]
	ds_read_b128 v[66:69], v64 offset:36928
	ds_read_b128 v[70:73], v65 offset:55360
	ds_read_b128 v[76:79], v64 offset:36960
	ds_read_b128 v[80:83], v65 offset:55392
	v_mfma_f32_32x32x16_bf16 v[0:15], v[92:95], v[88:91], v[0:15]
	ds_read_b128 v[84:87], v65 offset:59968
	ds_read_b128 v[88:91], v65 offset:60000
	s_waitcnt lgkmcnt(4)
	v_mfma_f32_32x32x16_bf16 v[48:63], v[66:69], v[70:73], v[48:63]
	s_waitcnt lgkmcnt(1)
	v_mfma_f32_32x32x16_bf16 v[32:47], v[66:69], v[84:87], v[32:47]
	ds_read_b128 v[66:69], v64 offset:41536
	ds_read_b128 v[92:95], v64 offset:41568
	v_mov_b32_e32 v64, v189
	s_waitcnt lgkmcnt(0)
	s_barrier
	v_mfma_f32_32x32x16_bf16 v[16:31], v[66:69], v[70:73], v[16:31]
	v_mfma_f32_32x32x16_bf16 v[0:15], v[66:69], v[84:87], v[0:15]
	v_mfma_f32_32x32x16_bf16 v[48:63], v[76:79], v[80:83], v[48:63]
	v_mfma_f32_32x32x16_bf16 v[32:47], v[76:79], v[88:91], v[32:47]
	v_mfma_f32_32x32x16_bf16 v[16:31], v[92:95], v[80:83], v[16:31]
	v_mfma_f32_32x32x16_bf16 v[0:15], v[92:95], v[88:91], v[0:15]
	v_and_b32_e32 v172, 31, v189
	v_bfe_u32 v173, v189, 5, 1
	v_bfe_u32 v174, v189, 6, 1
	v_bfe_u32 v175, v189, 7, 1
	v_lshl_add_u32 v172, v174, 6, v172
	s_sub_i32 s17, s8, s0
	v_lshlrev_b32_e32 v175, 6, v175
	v_add_u32_e32 v172, s17, v172
	v_lshl_add_u32 v171, v173, 2, v175
	v_add_u32_e32 v171, s1, v171
	v_lshlrev_b32_e32 v168, 2, v172
	v_mov_b32_e32 v169, 0
	v_lshlrev_b32_e32 v170, 1, v172
	v_readfirstlane_b32 s17, v171
	s_mov_b32 s27, 0x8040
	s_cmp_ge_u32 s17, s27
	s_cbranch_scc1 .Lmy_epi_done_wo
	s_mov_b32 s16, 0x7fc02
	s_movk_i32 s26, 0xdff0
	v_readlane_b32 s18, v254, 42
	v_readlane_b32 s19, v254, 43
	v_readlane_b32 s20, v254, 44
	v_readlane_b32 s21, v254, 45
	v_readlane_b32 s22, v254, 30
	v_readlane_b32 s23, v254, 31
	v_readlane_b32 s24, v254, 32
	v_readlane_b32 s25, v254, 33
	v_mov_b32_e32 v177, 0
	v_mov_b32_e32 v179, 0
	v_mov_b32_e32 v81, 0
	v_mov_b32_e32 v83, 0
	v_mov_b32_e32 v75, 0
	s_sub_u32 s18, s18, 0x10000
	s_subb_u32 s19, s19, 0
	s_sub_u32 s22, s22, 0x10000
	s_subb_u32 s23, s23, 0
	v_mov_b32_e32 v160, s22
	v_mov_b32_e32 v161, s23
	v_mov_b32_e32 v162, s24
	v_mov_b32_e32 v163, s25
	v_lshl_add_u64 v[160:161], v[168:169], 0, v[160:161]
	v_lshl_add_u64 v[162:163], v[168:169], 0, v[162:163]
	v_mov_b32_e32 v164, s18
	v_mov_b32_e32 v165, s19
	v_mov_b32_e32 v166, s20
	v_mov_b32_e32 v167, s21
	v_lshl_add_u64 v[164:165], v[168:169], 0, v[164:165]
	v_lshl_add_u64 v[166:167], v[168:169], 0, v[166:167]
	v_add_u32_e32 v172, 0, v171
	v_mul_hi_u32 v173, v172, s16
	v_mad_i32_i24 v174, v173, s26, v172
	v_cmp_gt_u32_e32 vcc, 16, v174
	v_lshlrev_b32_e32 v190, 12, v174
	v_lshl_add_u32 v175, v173, 25, v190
	v_lshl_add_u32 v188, v173, 16, v190
	v_cndmask_b32_e32 v176, v175, v188, vcc
	v_cndmask_b32_e32 v180, v160, v162, vcc
	v_cndmask_b32_e32 v181, v161, v163, vcc
	v_cndmask_b32_e32 v178, v175, v190, vcc
	v_cndmask_b32_e32 v182, v164, v166, vcc
	v_cndmask_b32_e32 v183, v165, v167, vcc
	v_lshl_add_u64 v[96:97], v[176:177], 0, v[180:181]
	v_lshl_add_u64 v[184:185], v[178:179], 0, v[182:183]
	global_load_dword v192, v[184:185], off
	global_load_dword v193, v[184:185], off offset:128
	v_add_u32_e32 v76, 1, v171
	v_mul_hi_u32 v77, v76, s16
	v_mad_i32_i24 v78, v77, s26, v76
	v_cmp_gt_u32_e32 vcc, 16, v78
	v_lshlrev_b32_e32 v93, 12, v78
	v_lshl_add_u32 v79, v77, 25, v93
	v_lshl_add_u32 v92, v77, 16, v93
	v_cndmask_b32_e32 v80, v79, v92, vcc
	v_cndmask_b32_e32 v84, v160, v162, vcc
	v_cndmask_b32_e32 v85, v161, v163, vcc
	v_cndmask_b32_e32 v82, v79, v93, vcc
	v_cndmask_b32_e32 v86, v164, v166, vcc
	v_cndmask_b32_e32 v87, v165, v167, vcc
	v_lshl_add_u64 v[98:99], v[80:81], 0, v[84:85]
	v_lshl_add_u64 v[88:89], v[82:83], 0, v[86:87]
	global_load_dword v194, v[88:89], off
	global_load_dword v195, v[88:89], off offset:128
	v_add_u32_e32 v172, 2, v171
	v_mul_hi_u32 v173, v172, s16
	v_mad_i32_i24 v174, v173, s26, v172
	v_cmp_gt_u32_e32 vcc, 16, v174
	v_lshlrev_b32_e32 v190, 12, v174
	v_lshl_add_u32 v175, v173, 25, v190
	v_lshl_add_u32 v188, v173, 16, v190
	v_cndmask_b32_e32 v176, v175, v188, vcc
	v_cndmask_b32_e32 v180, v160, v162, vcc
	v_cndmask_b32_e32 v181, v161, v163, vcc
	v_cndmask_b32_e32 v178, v175, v190, vcc
	v_cndmask_b32_e32 v182, v164, v166, vcc
	v_cndmask_b32_e32 v183, v165, v167, vcc
	v_lshl_add_u64 v[100:101], v[176:177], 0, v[180:181]
	v_lshl_add_u64 v[184:185], v[178:179], 0, v[182:183]
	global_load_dword v196, v[184:185], off
; __device__ __forceinline__ int tid_opaque() { int t = threadIdx.x; asm volatile("" : "+v"(t)); return t; }
; __device__ __forceinline__ int crow(int r, int hf) { return (r & 3) + 8 * (r >> 2) + 4 * hf; }
; template <bool FIRST>
; __device__ __forceinline__ void residual_epilogue(const Params& p, f32x16 (&acc)[2][2], int m0, int ncolbase) {
;   const int tid = tid_opaque(), w = tid >> 6, l = tid & 63, lc = l & 31, hf = l >> 5;
;   const int wm = w >> 1, wn = w & 1;
; #pragma unroll
;   for (int i = 0; i < 2; ++i)
; #pragma unroll
;     for (int r = 0; r < 16; ++r) {
;       const int t = m0 + wm * 64 + i * 32 + crow(r, hf);
;       if (t < T) {
;         float* hp = hrow(p, t);
;         const float* hsrc = hp;
;         if (FIRST) { const int b = t / L, pp = t - b * L; hsrc = pp < NM ? p.meta + (size_t)pp * D : p.x + (size_t)(b * SEQ + pp - NM) * D; }
; #pragma unroll
;         for (int j = 0; j < 2; ++j) {
;           const int n = ncolbase + wn * 64 + j * 32 + lc;
;           float v = hsrc[n] + acc[i][j][r];
	global_load_dword v197, v[184:185], off offset:128
	v_add_u32_e32 v76, 3, v171
	v_mul_hi_u32 v77, v76, s16
	v_mad_i32_i24 v78, v77, s26, v76
	v_cmp_gt_u32_e32 vcc, 16, v78
	v_lshlrev_b32_e32 v93, 12, v78
	v_lshl_add_u32 v79, v77, 25, v93
	v_lshl_add_u32 v92, v77, 16, v93
	v_cndmask_b32_e32 v80, v79, v92, vcc
	v_cndmask_b32_e32 v84, v160, v162, vcc
	v_cndmask_b32_e32 v85, v161, v163, vcc
	v_cndmask_b32_e32 v82, v79, v93, vcc
	v_cndmask_b32_e32 v86, v164, v166, vcc
	v_cndmask_b32_e32 v87, v165, v167, vcc
	v_lshl_add_u64 v[102:103], v[80:81], 0, v[84:85]
	v_lshl_add_u64 v[88:89], v[82:83], 0, v[86:87]
	global_load_dword v198, v[88:89], off
	global_load_dword v199, v[88:89], off offset:128
	v_add_u32_e32 v172, 8, v171
	v_mul_hi_u32 v173, v172, s16
	v_mad_i32_i24 v174, v173, s26, v172
	v_cmp_gt_u32_e32 vcc, 16, v174
	v_lshlrev_b32_e32 v190, 12, v174
	v_lshl_add_u32 v175, v173, 25, v190
	v_lshl_add_u32 v188, v173, 16, v190
	v_cndmask_b32_e32 v176, v175, v188, vcc
	v_cndmask_b32_e32 v180, v160, v162, vcc
	v_cndmask_b32_e32 v181, v161, v163, vcc
	v_cndmask_b32_e32 v178, v175, v190, vcc
	v_cndmask_b32_e32 v182, v164, v166, vcc
	v_cndmask_b32_e32 v183, v165, v167, vcc
	v_lshl_add_u64 v[104:105], v[176:177], 0, v[180:181]
	v_lshl_add_u64 v[184:185], v[178:179], 0, v[182:183]
	global_load_dword v200, v[184:185], off
	global_load_dword v201, v[184:185], off offset:128
	v_add_u32_e32 v76, 9, v171
	v_mul_hi_u32 v77, v76, s16
	v_mad_i32_i24 v78, v77, s26, v76
	v_cmp_gt_u32_e32 vcc, 16, v78
	v_lshlrev_b32_e32 v93, 12, v78
	v_lshl_add_u32 v79, v77, 25, v93
	v_lshl_add_u32 v92, v77, 16, v93
	v_cndmask_b32_e32 v80, v79, v92, vcc
	v_cndmask_b32_e32 v84, v160, v162, vcc
	v_cndmask_b32_e32 v85, v161, v163, vcc
	v_cndmask_b32_e32 v82, v79, v93, vcc
	v_cndmask_b32_e32 v86, v164, v166, vcc
	v_cndmask_b32_e32 v87, v165, v167, vcc
	v_lshl_add_u64 v[106:107], v[80:81], 0, v[84:85]
	v_lshl_add_u64 v[88:89], v[82:83], 0, v[86:87]
	global_load_dword v202, v[88:89], off
	global_load_dword v203, v[88:89], off offset:128
	v_add_u32_e32 v172, 10, v171
	v_mul_hi_u32 v173, v172, s16
	v_mad_i32_i24 v174, v173, s26, v172
	v_cmp_gt_u32_e32 vcc, 16, v174
	v_lshlrev_b32_e32 v190, 12, v174
	v_lshl_add_u32 v175, v173, 25, v190
	v_lshl_add_u32 v188, v173, 16, v190
	v_cndmask_b32_e32 v176, v175, v188, vcc
	v_cndmask_b32_e32 v180, v160, v162, vcc
	v_cndmask_b32_e32 v181, v161, v163, vcc
	v_cndmask_b32_e32 v178, v175, v190, vcc
	v_cndmask_b32_e32 v182, v164, v166, vcc
	v_cndmask_b32_e32 v183, v165, v167, vcc
	v_lshl_add_u64 v[108:109], v[176:177], 0, v[180:181]
	v_lshl_add_u64 v[184:185], v[178:179], 0, v[182:183]
	global_load_dword v204, v[184:185], off
	global_load_dword v205, v[184:185], off offset:128
	v_add_u32_e32 v76, 11, v171
	v_mul_hi_u32 v77, v76, s16
	v_mad_i32_i24 v78, v77, s26, v76
	v_cmp_gt_u32_e32 vcc, 16, v78
	v_lshlrev_b32_e32 v93, 12, v78
	v_lshl_add_u32 v79, v77, 25, v93
	v_lshl_add_u32 v92, v77, 16, v93
	v_cndmask_b32_e32 v80, v79, v92, vcc
	v_cndmask_b32_e32 v84, v160, v162, vcc
	v_cndmask_b32_e32 v85, v161, v163, vcc
	v_cndmask_b32_e32 v82, v79, v93, vcc
	v_cndmask_b32_e32 v86, v164, v166, vcc
	v_cndmask_b32_e32 v87, v165, v167, vcc
	v_lshl_add_u64 v[110:111], v[80:81], 0, v[84:85]
	v_lshl_add_u64 v[88:89], v[82:83], 0, v[86:87]
	global_load_dword v206, v[88:89], off
	global_load_dword v207, v[88:89], off offset:128
	v_add_u32_e32 v172, 16, v171
	v_mul_hi_u32 v173, v172, s16
	v_mad_i32_i24 v174, v173, s26, v172
	v_cmp_gt_u32_e32 vcc, 16, v174
	v_lshlrev_b32_e32 v190, 12, v174
	v_lshl_add_u32 v175, v173, 25, v190
	v_lshl_add_u32 v188, v173, 16, v190
	v_cndmask_b32_e32 v176, v175, v188, vcc
	v_cndmask_b32_e32 v180, v160, v162, vcc
	v_cndmask_b32_e32 v181, v161, v163, vcc
	v_cndmask_b32_e32 v178, v175, v190, vcc
	v_cndmask_b32_e32 v182, v164, v166, vcc
	v_cndmask_b32_e32 v183, v165, v167, vcc
	v_lshl_add_u64 v[112:113], v[176:177], 0, v[180:181]
	v_lshl_add_u64 v[184:185], v[178:179], 0, v[182:183]
	global_load_dword v208, v[184:185], off
	global_load_dword v209, v[184:185], off offset:128
	v_add_u32_e32 v76, 17, v171
	v_mul_hi_u32 v77, v76, s16
	v_mad_i32_i24 v78, v77, s26, v76
	v_cmp_gt_u32_e32 vcc, 16, v78
	v_lshlrev_b32_e32 v93, 12, v78
	v_lshl_add_u32 v79, v77, 25, v93
	v_lshl_add_u32 v92, v77, 16, v93
	v_cndmask_b32_e32 v80, v79, v92, vcc
	v_cndmask_b32_e32 v84, v160, v162, vcc
	v_cndmask_b32_e32 v85, v161, v163, vcc
	v_cndmask_b32_e32 v82, v79, v93, vcc
	v_cndmask_b32_e32 v86, v164, v166, vcc
	v_cndmask_b32_e32 v87, v165, v167, vcc
	v_lshl_add_u64 v[114:115], v[80:81], 0, v[84:85]
	v_lshl_add_u64 v[88:89], v[82:83], 0, v[86:87]
	global_load_dword v210, v[88:89], off
	global_load_dword v211, v[88:89], off offset:128
	v_add_u32_e32 v172, 18, v171
	v_mul_hi_u32 v173, v172, s16
	v_mad_i32_i24 v174, v173, s26, v172
	v_cmp_gt_u32_e32 vcc, 16, v174
	v_lshlrev_b32_e32 v190, 12, v174
	v_lshl_add_u32 v175, v173, 25, v190
	v_lshl_add_u32 v188, v173, 16, v190
	v_cndmask_b32_e32 v176, v175, v188, vcc
	v_cndmask_b32_e32 v180, v160, v162, vcc
	v_cndmask_b32_e32 v181, v161, v163, vcc
	v_cndmask_b32_e32 v178, v175, v190, vcc
	v_cndmask_b32_e32 v182, v164, v166, vcc
	v_cndmask_b32_e32 v183, v165, v167, vcc
	v_lshl_add_u64 v[116:117], v[176:177], 0, v[180:181]
	v_lshl_add_u64 v[184:185], v[178:179], 0, v[182:183]
	global_load_dword v212, v[184:185], off
	global_load_dword v213, v[184:185], off offset:128
	v_add_u32_e32 v76, 19, v171
	v_mul_hi_u32 v77, v76, s16
	v_mad_i32_i24 v78, v77, s26, v76
	v_cmp_gt_u32_e32 vcc, 16, v78
	v_lshlrev_b32_e32 v93, 12, v78
	v_lshl_add_u32 v79, v77, 25, v93
	v_lshl_add_u32 v92, v77, 16, v93
	v_cndmask_b32_e32 v80, v79, v92, vcc
; __device__ __forceinline__ int tid_opaque() { int t = threadIdx.x; asm volatile("" : "+v"(t)); return t; }
; __device__ __forceinline__ int crow(int r, int hf) { return (r & 3) + 8 * (r >> 2) + 4 * hf; }
; template <bool FIRST>
; __device__ __forceinline__ void residual_epilogue(const Params& p, f32x16 (&acc)[2][2], int m0, int ncolbase) {
;   const int tid = tid_opaque(), w = tid >> 6, l = tid & 63, lc = l & 31, hf = l >> 5;
;   const int wm = w >> 1, wn = w & 1;
; #pragma unroll
;   for (int i = 0; i < 2; ++i)
; #pragma unroll
;     for (int r = 0; r < 16; ++r) {
;       const int t = m0 + wm * 64 + i * 32 + crow(r, hf);
;       if (t < T) {
;         float* hp = hrow(p, t);
;         const float* hsrc = hp;
;         if (FIRST) { const int b = t / L, pp = t - b * L; hsrc = pp < NM ? p.meta + (size_t)pp * D : p.x + (size_t)(b * SEQ + pp - NM) * D; }
; #pragma unroll
;         for (int j = 0; j < 2; ++j) {
;           const int n = ncolbase + wn * 64 + j * 32 + lc;
;           float v = hsrc[n] + acc[i][j][r];
	v_cndmask_b32_e32 v84, v160, v162, vcc
	v_cndmask_b32_e32 v85, v161, v163, vcc
	v_cndmask_b32_e32 v82, v79, v93, vcc
	v_cndmask_b32_e32 v86, v164, v166, vcc
	v_cndmask_b32_e32 v87, v165, v167, vcc
	v_lshl_add_u64 v[118:119], v[80:81], 0, v[84:85]
	v_lshl_add_u64 v[88:89], v[82:83], 0, v[86:87]
	global_load_dword v214, v[88:89], off
	global_load_dword v215, v[88:89], off offset:128
	v_add_u32_e32 v172, 24, v171
	v_mul_hi_u32 v173, v172, s16
	v_mad_i32_i24 v174, v173, s26, v172
	v_cmp_gt_u32_e32 vcc, 16, v174
	v_lshlrev_b32_e32 v190, 12, v174
	v_lshl_add_u32 v175, v173, 25, v190
	v_lshl_add_u32 v188, v173, 16, v190
	v_cndmask_b32_e32 v176, v175, v188, vcc
	v_cndmask_b32_e32 v180, v160, v162, vcc
	v_cndmask_b32_e32 v181, v161, v163, vcc
	v_cndmask_b32_e32 v178, v175, v190, vcc
	v_cndmask_b32_e32 v182, v164, v166, vcc
	v_cndmask_b32_e32 v183, v165, v167, vcc
	v_lshl_add_u64 v[120:121], v[176:177], 0, v[180:181]
	v_lshl_add_u64 v[184:185], v[178:179], 0, v[182:183]
	global_load_dword v216, v[184:185], off
	global_load_dword v217, v[184:185], off offset:128
	v_add_u32_e32 v76, 25, v171
	v_mul_hi_u32 v77, v76, s16
	v_mad_i32_i24 v78, v77, s26, v76
	v_cmp_gt_u32_e32 vcc, 16, v78
	v_lshlrev_b32_e32 v93, 12, v78
	v_lshl_add_u32 v79, v77, 25, v93
	v_lshl_add_u32 v92, v77, 16, v93
	v_cndmask_b32_e32 v80, v79, v92, vcc
	v_cndmask_b32_e32 v84, v160, v162, vcc
	v_cndmask_b32_e32 v85, v161, v163, vcc
	v_cndmask_b32_e32 v82, v79, v93, vcc
	v_cndmask_b32_e32 v86, v164, v166, vcc
	v_cndmask_b32_e32 v87, v165, v167, vcc
	v_lshl_add_u64 v[122:123], v[80:81], 0, v[84:85]
	v_lshl_add_u64 v[88:89], v[82:83], 0, v[86:87]
	global_load_dword v218, v[88:89], off
	global_load_dword v219, v[88:89], off offset:128
	v_add_u32_e32 v172, 26, v171
	v_mul_hi_u32 v173, v172, s16
	v_mad_i32_i24 v174, v173, s26, v172
	v_cmp_gt_u32_e32 vcc, 16, v174
	v_lshlrev_b32_e32 v190, 12, v174
	v_lshl_add_u32 v175, v173, 25, v190
	v_lshl_add_u32 v188, v173, 16, v190
	v_cndmask_b32_e32 v176, v175, v188, vcc
	v_cndmask_b32_e32 v180, v160, v162, vcc
	v_cndmask_b32_e32 v181, v161, v163, vcc
	v_cndmask_b32_e32 v178, v175, v190, vcc
	v_cndmask_b32_e32 v182, v164, v166, vcc
	v_cndmask_b32_e32 v183, v165, v167, vcc
	v_lshl_add_u64 v[124:125], v[176:177], 0, v[180:181]
	v_lshl_add_u64 v[184:185], v[178:179], 0, v[182:183]
	global_load_dword v220, v[184:185], off
	global_load_dword v221, v[184:185], off offset:128
	v_add_u32_e32 v76, 27, v171
	v_mul_hi_u32 v77, v76, s16
	v_mad_i32_i24 v78, v77, s26, v76
	v_cmp_gt_u32_e32 vcc, 16, v78
	v_lshlrev_b32_e32 v93, 12, v78
	v_lshl_add_u32 v79, v77, 25, v93
	v_lshl_add_u32 v92, v77, 16, v93
	v_cndmask_b32_e32 v80, v79, v92, vcc
	v_cndmask_b32_e32 v84, v160, v162, vcc
	v_cndmask_b32_e32 v85, v161, v163, vcc
	v_cndmask_b32_e32 v82, v79, v93, vcc
	v_cndmask_b32_e32 v86, v164, v166, vcc
	v_cndmask_b32_e32 v87, v165, v167, vcc
	v_lshl_add_u64 v[126:127], v[80:81], 0, v[84:85]
	v_lshl_add_u64 v[88:89], v[82:83], 0, v[86:87]
	global_load_dword v222, v[88:89], off
	global_load_dword v223, v[88:89], off offset:128
	v_add_u32_e32 v172, 32, v171
	v_mul_hi_u32 v173, v172, s16
	v_mad_i32_i24 v174, v173, s26, v172
	v_cmp_gt_u32_e32 vcc, 16, v174
	v_lshlrev_b32_e32 v190, 12, v174
	v_lshl_add_u32 v175, v173, 25, v190
	v_lshl_add_u32 v188, v173, 16, v190
	v_cndmask_b32_e32 v176, v175, v188, vcc
	v_cndmask_b32_e32 v180, v160, v162, vcc
	v_cndmask_b32_e32 v181, v161, v163, vcc
	v_cndmask_b32_e32 v178, v175, v190, vcc
	v_cndmask_b32_e32 v182, v164, v166, vcc
	v_cndmask_b32_e32 v183, v165, v167, vcc
	v_lshl_add_u64 v[128:129], v[176:177], 0, v[180:181]
	v_lshl_add_u64 v[184:185], v[178:179], 0, v[182:183]
	global_load_dword v224, v[184:185], off
	global_load_dword v225, v[184:185], off offset:128
	v_add_u32_e32 v76, 33, v171
	v_mul_hi_u32 v77, v76, s16
	v_mad_i32_i24 v78, v77, s26, v76
	v_cmp_gt_u32_e32 vcc, 16, v78
	v_lshlrev_b32_e32 v93, 12, v78
	v_lshl_add_u32 v79, v77, 25, v93
	v_lshl_add_u32 v92, v77, 16, v93
	v_cndmask_b32_e32 v80, v79, v92, vcc
	v_cndmask_b32_e32 v84, v160, v162, vcc
	v_cndmask_b32_e32 v85, v161, v163, vcc
	v_cndmask_b32_e32 v82, v79, v93, vcc
	v_cndmask_b32_e32 v86, v164, v166, vcc
	v_cndmask_b32_e32 v87, v165, v167, vcc
	v_lshl_add_u64 v[130:131], v[80:81], 0, v[84:85]
	v_lshl_add_u64 v[88:89], v[82:83], 0, v[86:87]
	global_load_dword v226, v[88:89], off
	global_load_dword v227, v[88:89], off offset:128
	v_add_u32_e32 v172, 34, v171
	v_mul_hi_u32 v173, v172, s16
	v_mad_i32_i24 v174, v173, s26, v172
	v_cmp_gt_u32_e32 vcc, 16, v174
	v_lshlrev_b32_e32 v190, 12, v174
	v_lshl_add_u32 v175, v173, 25, v190
	v_lshl_add_u32 v188, v173, 16, v190
	v_cndmask_b32_e32 v176, v175, v188, vcc
	v_cndmask_b32_e32 v180, v160, v162, vcc
	v_cndmask_b32_e32 v181, v161, v163, vcc
	v_cndmask_b32_e32 v178, v175, v190, vcc
	v_cndmask_b32_e32 v182, v164, v166, vcc
	v_cndmask_b32_e32 v183, v165, v167, vcc
	v_lshl_add_u64 v[132:133], v[176:177], 0, v[180:181]
	v_lshl_add_u64 v[184:185], v[178:179], 0, v[182:183]
	global_load_dword v228, v[184:185], off
	global_load_dword v229, v[184:185], off offset:128
	v_add_u32_e32 v76, 35, v171
	v_mul_hi_u32 v77, v76, s16
	v_mad_i32_i24 v78, v77, s26, v76
	v_cmp_gt_u32_e32 vcc, 16, v78
	v_lshlrev_b32_e32 v93, 12, v78
	v_lshl_add_u32 v79, v77, 25, v93
	v_lshl_add_u32 v92, v77, 16, v93
	v_cndmask_b32_e32 v80, v79, v92, vcc
	v_cndmask_b32_e32 v84, v160, v162, vcc
	v_cndmask_b32_e32 v85, v161, v163, vcc
	v_cndmask_b32_e32 v82, v79, v93, vcc
	v_cndmask_b32_e32 v86, v164, v166, vcc
	v_cndmask_b32_e32 v87, v165, v167, vcc
	v_lshl_add_u64 v[134:135], v[80:81], 0, v[84:85]
	v_lshl_add_u64 v[88:89], v[82:83], 0, v[86:87]
	global_load_dword v230, v[88:89], off
; __device__ __forceinline__ int tid_opaque() { int t = threadIdx.x; asm volatile("" : "+v"(t)); return t; }
; __device__ __forceinline__ int crow(int r, int hf) { return (r & 3) + 8 * (r >> 2) + 4 * hf; }
; template <bool FIRST>
; __device__ __forceinline__ void residual_epilogue(const Params& p, f32x16 (&acc)[2][2], int m0, int ncolbase) {
;   const int tid = tid_opaque(), w = tid >> 6, l = tid & 63, lc = l & 31, hf = l >> 5;
;   const int wm = w >> 1, wn = w & 1;
; #pragma unroll
;   for (int i = 0; i < 2; ++i)
; #pragma unroll
;     for (int r = 0; r < 16; ++r) {
;       const int t = m0 + wm * 64 + i * 32 + crow(r, hf);
;       if (t < T) {
;         float* hp = hrow(p, t);
;         const float* hsrc = hp;
;         if (FIRST) { const int b = t / L, pp = t - b * L; hsrc = pp < NM ? p.meta + (size_t)pp * D : p.x + (size_t)(b * SEQ + pp - NM) * D; }
; #pragma unroll
;         for (int j = 0; j < 2; ++j) {
;           const int n = ncolbase + wn * 64 + j * 32 + lc;
;           float v = hsrc[n] + acc[i][j][r];
	global_load_dword v231, v[88:89], off offset:128
	v_add_u32_e32 v172, 40, v171
	v_mul_hi_u32 v173, v172, s16
	v_mad_i32_i24 v174, v173, s26, v172
	v_cmp_gt_u32_e32 vcc, 16, v174
	v_lshlrev_b32_e32 v190, 12, v174
	v_lshl_add_u32 v175, v173, 25, v190
	v_lshl_add_u32 v188, v173, 16, v190
	v_cndmask_b32_e32 v176, v175, v188, vcc
	v_cndmask_b32_e32 v180, v160, v162, vcc
	v_cndmask_b32_e32 v181, v161, v163, vcc
	v_cndmask_b32_e32 v178, v175, v190, vcc
	v_cndmask_b32_e32 v182, v164, v166, vcc
	v_cndmask_b32_e32 v183, v165, v167, vcc
	v_lshl_add_u64 v[136:137], v[176:177], 0, v[180:181]
	v_lshl_add_u64 v[184:185], v[178:179], 0, v[182:183]
	global_load_dword v232, v[184:185], off
	global_load_dword v233, v[184:185], off offset:128
	v_add_u32_e32 v76, 41, v171
	v_mul_hi_u32 v77, v76, s16
	v_mad_i32_i24 v78, v77, s26, v76
	v_cmp_gt_u32_e32 vcc, 16, v78
	v_lshlrev_b32_e32 v93, 12, v78
	v_lshl_add_u32 v79, v77, 25, v93
	v_lshl_add_u32 v92, v77, 16, v93
	v_cndmask_b32_e32 v80, v79, v92, vcc
	v_cndmask_b32_e32 v84, v160, v162, vcc
	v_cndmask_b32_e32 v85, v161, v163, vcc
	v_cndmask_b32_e32 v82, v79, v93, vcc
	v_cndmask_b32_e32 v86, v164, v166, vcc
	v_cndmask_b32_e32 v87, v165, v167, vcc
	v_lshl_add_u64 v[138:139], v[80:81], 0, v[84:85]
	v_lshl_add_u64 v[88:89], v[82:83], 0, v[86:87]
	global_load_dword v234, v[88:89], off
	global_load_dword v235, v[88:89], off offset:128
	v_add_u32_e32 v172, 42, v171
	v_mul_hi_u32 v173, v172, s16
	v_mad_i32_i24 v174, v173, s26, v172
	v_cmp_gt_u32_e32 vcc, 16, v174
	v_lshlrev_b32_e32 v190, 12, v174
	v_lshl_add_u32 v175, v173, 25, v190
	v_lshl_add_u32 v188, v173, 16, v190
	v_cndmask_b32_e32 v176, v175, v188, vcc
	v_cndmask_b32_e32 v180, v160, v162, vcc
	v_cndmask_b32_e32 v181, v161, v163, vcc
	v_cndmask_b32_e32 v178, v175, v190, vcc
	v_cndmask_b32_e32 v182, v164, v166, vcc
	v_cndmask_b32_e32 v183, v165, v167, vcc
	v_lshl_add_u64 v[140:141], v[176:177], 0, v[180:181]
	v_lshl_add_u64 v[184:185], v[178:179], 0, v[182:183]
	global_load_dword v236, v[184:185], off
	global_load_dword v237, v[184:185], off offset:128
	v_add_u32_e32 v76, 43, v171
	v_mul_hi_u32 v77, v76, s16
	v_mad_i32_i24 v78, v77, s26, v76
	v_cmp_gt_u32_e32 vcc, 16, v78
	v_lshlrev_b32_e32 v93, 12, v78
	v_lshl_add_u32 v79, v77, 25, v93
	v_lshl_add_u32 v92, v77, 16, v93
	v_cndmask_b32_e32 v80, v79, v92, vcc
	v_cndmask_b32_e32 v84, v160, v162, vcc
	v_cndmask_b32_e32 v85, v161, v163, vcc
	v_cndmask_b32_e32 v82, v79, v93, vcc
	v_cndmask_b32_e32 v86, v164, v166, vcc
	v_cndmask_b32_e32 v87, v165, v167, vcc
	v_lshl_add_u64 v[142:143], v[80:81], 0, v[84:85]
	v_lshl_add_u64 v[88:89], v[82:83], 0, v[86:87]
	global_load_dword v238, v[88:89], off
	global_load_dword v239, v[88:89], off offset:128
	v_add_u32_e32 v172, 48, v171
	v_mul_hi_u32 v173, v172, s16
	v_mad_i32_i24 v174, v173, s26, v172
	v_cmp_gt_u32_e32 vcc, 16, v174
	v_lshlrev_b32_e32 v190, 12, v174
	v_lshl_add_u32 v175, v173, 25, v190
	v_lshl_add_u32 v188, v173, 16, v190
	v_cndmask_b32_e32 v176, v175, v188, vcc
	v_cndmask_b32_e32 v180, v160, v162, vcc
	v_cndmask_b32_e32 v181, v161, v163, vcc
	v_cndmask_b32_e32 v178, v175, v190, vcc
	v_cndmask_b32_e32 v182, v164, v166, vcc
	v_cndmask_b32_e32 v183, v165, v167, vcc
	v_lshl_add_u64 v[144:145], v[176:177], 0, v[180:181]
	v_lshl_add_u64 v[184:185], v[178:179], 0, v[182:183]
	global_load_dword v240, v[184:185], off
	global_load_dword v241, v[184:185], off offset:128
	v_add_u32_e32 v76, 49, v171
	v_mul_hi_u32 v77, v76, s16
	v_mad_i32_i24 v78, v77, s26, v76
	v_cmp_gt_u32_e32 vcc, 16, v78
	v_lshlrev_b32_e32 v93, 12, v78
	v_lshl_add_u32 v79, v77, 25, v93
	v_lshl_add_u32 v92, v77, 16, v93
	v_cndmask_b32_e32 v80, v79, v92, vcc
	v_cndmask_b32_e32 v84, v160, v162, vcc
	v_cndmask_b32_e32 v85, v161, v163, vcc
	v_cndmask_b32_e32 v82, v79, v93, vcc
	v_cndmask_b32_e32 v86, v164, v166, vcc
	v_cndmask_b32_e32 v87, v165, v167, vcc
	v_lshl_add_u64 v[146:147], v[80:81], 0, v[84:85]
	v_lshl_add_u64 v[88:89], v[82:83], 0, v[86:87]
	global_load_dword v242, v[88:89], off
	global_load_dword v243, v[88:89], off offset:128
	v_add_u32_e32 v172, 50, v171
	v_mul_hi_u32 v173, v172, s16
	v_mad_i32_i24 v174, v173, s26, v172
	v_cmp_gt_u32_e32 vcc, 16, v174
	v_lshlrev_b32_e32 v190, 12, v174
	v_lshl_add_u32 v175, v173, 25, v190
	v_lshl_add_u32 v188, v173, 16, v190
	v_cndmask_b32_e32 v176, v175, v188, vcc
	v_cndmask_b32_e32 v180, v160, v162, vcc
	v_cndmask_b32_e32 v181, v161, v163, vcc
	v_cndmask_b32_e32 v178, v175, v190, vcc
	v_cndmask_b32_e32 v182, v164, v166, vcc
	v_cndmask_b32_e32 v183, v165, v167, vcc
	v_lshl_add_u64 v[148:149], v[176:177], 0, v[180:181]
	v_lshl_add_u64 v[184:185], v[178:179], 0, v[182:183]
	global_load_dword v244, v[184:185], off
	global_load_dword v245, v[184:185], off offset:128
	v_add_u32_e32 v76, 51, v171
	v_mul_hi_u32 v77, v76, s16
	v_mad_i32_i24 v78, v77, s26, v76
	v_cmp_gt_u32_e32 vcc, 16, v78
	v_lshlrev_b32_e32 v93, 12, v78
	v_lshl_add_u32 v79, v77, 25, v93
	v_lshl_add_u32 v92, v77, 16, v93
	v_cndmask_b32_e32 v80, v79, v92, vcc
	v_cndmask_b32_e32 v84, v160, v162, vcc
	v_cndmask_b32_e32 v85, v161, v163, vcc
	v_cndmask_b32_e32 v82, v79, v93, vcc
	v_cndmask_b32_e32 v86, v164, v166, vcc
	v_cndmask_b32_e32 v87, v165, v167, vcc
	v_lshl_add_u64 v[150:151], v[80:81], 0, v[84:85]
	v_lshl_add_u64 v[88:89], v[82:83], 0, v[86:87]
	global_load_dword v246, v[88:89], off
	global_load_dword v247, v[88:89], off offset:128
	v_add_u32_e32 v172, 56, v171
	v_mul_hi_u32 v173, v172, s16
	v_mad_i32_i24 v174, v173, s26, v172
	v_cmp_gt_u32_e32 vcc, 16, v174
	v_lshlrev_b32_e32 v190, 12, v174
	v_lshl_add_u32 v175, v173, 25, v190
	v_lshl_add_u32 v188, v173, 16, v190
	v_cndmask_b32_e32 v176, v175, v188, vcc
; __device__ __forceinline__ int tid_opaque() { int t = threadIdx.x; asm volatile("" : "+v"(t)); return t; }
; __device__ __forceinline__ int crow(int r, int hf) { return (r & 3) + 8 * (r >> 2) + 4 * hf; }
; template <bool FIRST>
; __device__ __forceinline__ void residual_epilogue(const Params& p, f32x16 (&acc)[2][2], int m0, int ncolbase) {
;   const int tid = tid_opaque(), w = tid >> 6, l = tid & 63, lc = l & 31, hf = l >> 5;
;   const int wm = w >> 1, wn = w & 1;
; #pragma unroll
;   for (int i = 0; i < 2; ++i)
; #pragma unroll
;     for (int r = 0; r < 16; ++r) {
;       const int t = m0 + wm * 64 + i * 32 + crow(r, hf);
;       if (t < T) {
;         float* hp = hrow(p, t);
;         const float* hsrc = hp;
;         if (FIRST) { const int b = t / L, pp = t - b * L; hsrc = pp < NM ? p.meta + (size_t)pp * D : p.x + (size_t)(b * SEQ + pp - NM) * D; }
; #pragma unroll
;         for (int j = 0; j < 2; ++j) {
;           const int n = ncolbase + wn * 64 + j * 32 + lc;
;           float v = hsrc[n] + acc[i][j][r];
	v_cndmask_b32_e32 v180, v160, v162, vcc
	v_cndmask_b32_e32 v181, v161, v163, vcc
	v_cndmask_b32_e32 v178, v175, v190, vcc
	v_cndmask_b32_e32 v182, v164, v166, vcc
	v_cndmask_b32_e32 v183, v165, v167, vcc
	v_lshl_add_u64 v[152:153], v[176:177], 0, v[180:181]
	v_lshl_add_u64 v[184:185], v[178:179], 0, v[182:183]
	global_load_dword v248, v[184:185], off
	global_load_dword v249, v[184:185], off offset:128
	v_add_u32_e32 v76, 57, v171
	v_mul_hi_u32 v77, v76, s16
	v_mad_i32_i24 v78, v77, s26, v76
	v_cmp_gt_u32_e32 vcc, 16, v78
	v_lshlrev_b32_e32 v93, 12, v78
	v_lshl_add_u32 v79, v77, 25, v93
	v_lshl_add_u32 v92, v77, 16, v93
	v_cndmask_b32_e32 v80, v79, v92, vcc
	v_cndmask_b32_e32 v84, v160, v162, vcc
	v_cndmask_b32_e32 v85, v161, v163, vcc
	v_cndmask_b32_e32 v82, v79, v93, vcc
	v_cndmask_b32_e32 v86, v164, v166, vcc
	v_cndmask_b32_e32 v87, v165, v167, vcc
	v_lshl_add_u64 v[154:155], v[80:81], 0, v[84:85]
	v_lshl_add_u64 v[88:89], v[82:83], 0, v[86:87]
	global_load_dword v250, v[88:89], off
	global_load_dword v251, v[88:89], off offset:128
	v_add_u32_e32 v172, 58, v171
	v_mul_hi_u32 v173, v172, s16
	v_mad_i32_i24 v174, v173, s26, v172
	v_cmp_gt_u32_e32 vcc, 16, v174
	v_lshlrev_b32_e32 v190, 12, v174
	v_lshl_add_u32 v175, v173, 25, v190
	v_lshl_add_u32 v188, v173, 16, v190
	v_cndmask_b32_e32 v176, v175, v188, vcc
	v_cndmask_b32_e32 v180, v160, v162, vcc
	v_cndmask_b32_e32 v181, v161, v163, vcc
	v_cndmask_b32_e32 v178, v175, v190, vcc
	v_cndmask_b32_e32 v182, v164, v166, vcc
	v_cndmask_b32_e32 v183, v165, v167, vcc
	v_lshl_add_u64 v[156:157], v[176:177], 0, v[180:181]
	v_lshl_add_u64 v[184:185], v[178:179], 0, v[182:183]
	global_load_dword v252, v[184:185], off
	global_load_dword v253, v[184:185], off offset:128
	v_add_u32_e32 v76, 59, v171
	v_mul_hi_u32 v77, v76, s16
	v_mad_i32_i24 v78, v77, s26, v76
	v_cmp_gt_u32_e32 vcc, 16, v78
	v_lshlrev_b32_e32 v93, 12, v78
	v_lshl_add_u32 v79, v77, 25, v93
	v_lshl_add_u32 v92, v77, 16, v93
	v_cndmask_b32_e32 v80, v79, v92, vcc
	v_cndmask_b32_e32 v84, v160, v162, vcc
	v_cndmask_b32_e32 v85, v161, v163, vcc
	v_cndmask_b32_e32 v82, v79, v93, vcc
	v_cndmask_b32_e32 v86, v164, v166, vcc
	v_cndmask_b32_e32 v87, v165, v167, vcc
	v_lshl_add_u64 v[158:159], v[80:81], 0, v[84:85]
	v_lshl_add_u64 v[88:89], v[82:83], 0, v[86:87]
	global_load_dword v186, v[88:89], off
	global_load_dword v187, v[88:89], off offset:128
	s_waitcnt vmcnt(62)
	v_add_f32_e32 v48, v48, v192
	v_add_f32_e32 v32, v32, v193
	s_waitcnt vmcnt(60)
	v_add_f32_e32 v49, v49, v194
	v_add_f32_e32 v33, v33, v195
	s_waitcnt vmcnt(58)
	v_add_f32_e32 v50, v50, v196
	v_add_f32_e32 v34, v34, v197
	s_waitcnt vmcnt(56)
	v_add_f32_e32 v51, v51, v198
	v_add_f32_e32 v35, v35, v199
	s_waitcnt vmcnt(54)
	v_add_f32_e32 v52, v52, v200
	v_add_f32_e32 v36, v36, v201
	s_waitcnt vmcnt(52)
	v_add_f32_e32 v53, v53, v202
	v_add_f32_e32 v37, v37, v203
	s_waitcnt vmcnt(50)
	v_add_f32_e32 v54, v54, v204
	v_add_f32_e32 v38, v38, v205
	s_waitcnt vmcnt(48)
	v_add_f32_e32 v55, v55, v206
	v_add_f32_e32 v39, v39, v207
	s_waitcnt vmcnt(46)
	v_add_f32_e32 v56, v56, v208
	v_add_f32_e32 v40, v40, v209
	s_waitcnt vmcnt(44)
	v_add_f32_e32 v57, v57, v210
	v_add_f32_e32 v41, v41, v211
	s_waitcnt vmcnt(42)
	v_add_f32_e32 v58, v58, v212
	v_add_f32_e32 v42, v42, v213
	s_waitcnt vmcnt(40)
	v_add_f32_e32 v59, v59, v214
	v_add_f32_e32 v43, v43, v215
	s_waitcnt vmcnt(38)
	v_add_f32_e32 v60, v60, v216
	v_add_f32_e32 v44, v44, v217
	s_waitcnt vmcnt(36)
	v_add_f32_e32 v61, v61, v218
	v_add_f32_e32 v45, v45, v219
	s_waitcnt vmcnt(34)
	v_add_f32_e32 v62, v62, v220
	v_add_f32_e32 v46, v46, v221
	s_waitcnt vmcnt(32)
	v_add_f32_e32 v63, v63, v222
	v_add_f32_e32 v47, v47, v223
	s_waitcnt vmcnt(30)
	v_add_f32_e32 v16, v16, v224
	v_add_f32_e32 v0, v0, v225
	s_waitcnt vmcnt(28)
	v_add_f32_e32 v17, v17, v226
	v_add_f32_e32 v1, v1, v227
	s_waitcnt vmcnt(26)
	v_add_f32_e32 v18, v18, v228
	v_add_f32_e32 v2, v2, v229
	s_waitcnt vmcnt(24)
	v_add_f32_e32 v19, v19, v230
	v_add_f32_e32 v3, v3, v231
	s_waitcnt vmcnt(22)
	v_add_f32_e32 v20, v20, v232
	v_add_f32_e32 v4, v4, v233
	s_waitcnt vmcnt(20)
	v_add_f32_e32 v21, v21, v234
	v_add_f32_e32 v5, v5, v235
	s_waitcnt vmcnt(18)
	v_add_f32_e32 v22, v22, v236
	v_add_f32_e32 v6, v6, v237
	s_waitcnt vmcnt(16)
	v_add_f32_e32 v23, v23, v238
	v_add_f32_e32 v7, v7, v239
	s_waitcnt vmcnt(14)
	v_add_f32_e32 v24, v24, v240
	v_add_f32_e32 v8, v8, v241
	s_waitcnt vmcnt(12)
	v_add_f32_e32 v25, v25, v242
	v_add_f32_e32 v9, v9, v243
	s_waitcnt vmcnt(10)
	v_add_f32_e32 v26, v26, v244
	v_add_f32_e32 v10, v10, v245
	s_waitcnt vmcnt(8)
	v_add_f32_e32 v27, v27, v246
	v_add_f32_e32 v11, v11, v247
	s_waitcnt vmcnt(6)
	v_add_f32_e32 v28, v28, v248
	v_add_f32_e32 v12, v12, v249
	s_waitcnt vmcnt(4)
	v_add_f32_e32 v29, v29, v250
	v_add_f32_e32 v13, v13, v251
	s_waitcnt vmcnt(2)
	v_add_f32_e32 v30, v30, v252
	v_add_f32_e32 v14, v14, v253
	s_waitcnt vmcnt(0)
; template <bool FIRST>
; __device__ __forceinline__ void residual_epilogue(const Params& p, f32x16 (&acc)[2][2], int m0, int ncolbase) {
;     ...
;         for (int j = 0; j < 2; ++j) {
;           const int n = ncolbase + wn * 64 + j * 32 + lc;
;           float v = hsrc[n] + acc[i][j][r];
;           hp[n] = v;
;           p.hb[(size_t)t * D + n] = (u16)(cvtpk(v, 0.f) & 0xffffu);
;         }
	v_add_f32_e32 v31, v31, v186
	v_add_f32_e32 v15, v15, v187
	global_store_dword v[96:97], v48, off
	global_store_dword v[96:97], v32, off offset:128
	v_cvt_pk_bf16_f32 v64, v48, v75
	v_cvt_pk_bf16_f32 v65, v32, v75
	v_add_u32_e32 v76, 0, v171
	v_lshl_add_u32 v77, v76, 11, v170
	global_store_short v77, v64, s[76:77]
	global_store_short v77, v65, s[76:77] offset:64
	global_store_dword v[98:99], v49, off
	global_store_dword v[98:99], v33, off offset:128
	v_cvt_pk_bf16_f32 v66, v49, v75
	v_cvt_pk_bf16_f32 v67, v33, v75
	v_add_u32_e32 v78, 1, v171
	v_lshl_add_u32 v79, v78, 11, v170
	global_store_short v79, v66, s[76:77]
	global_store_short v79, v67, s[76:77] offset:64
	global_store_dword v[100:101], v50, off
	global_store_dword v[100:101], v34, off offset:128
	v_cvt_pk_bf16_f32 v68, v50, v75
	v_cvt_pk_bf16_f32 v69, v34, v75
	v_add_u32_e32 v80, 2, v171
	v_lshl_add_u32 v81, v80, 11, v170
	global_store_short v81, v68, s[76:77]
	global_store_short v81, v69, s[76:77] offset:64
	global_store_dword v[102:103], v51, off
	global_store_dword v[102:103], v35, off offset:128
	v_cvt_pk_bf16_f32 v70, v51, v75
	v_cvt_pk_bf16_f32 v71, v35, v75
	v_add_u32_e32 v82, 3, v171
	v_lshl_add_u32 v83, v82, 11, v170
	global_store_short v83, v70, s[76:77]
	global_store_short v83, v71, s[76:77] offset:64
	global_store_dword v[104:105], v52, off
	global_store_dword v[104:105], v36, off offset:128
	v_cvt_pk_bf16_f32 v64, v52, v75
	v_cvt_pk_bf16_f32 v65, v36, v75
	v_add_u32_e32 v76, 8, v171
	v_lshl_add_u32 v77, v76, 11, v170
	global_store_short v77, v64, s[76:77]
	global_store_short v77, v65, s[76:77] offset:64
	global_store_dword v[106:107], v53, off
	global_store_dword v[106:107], v37, off offset:128
	v_cvt_pk_bf16_f32 v66, v53, v75
	v_cvt_pk_bf16_f32 v67, v37, v75
	v_add_u32_e32 v78, 9, v171
	v_lshl_add_u32 v79, v78, 11, v170
	global_store_short v79, v66, s[76:77]
	global_store_short v79, v67, s[76:77] offset:64
	global_store_dword v[108:109], v54, off
	global_store_dword v[108:109], v38, off offset:128
	v_cvt_pk_bf16_f32 v68, v54, v75
	v_cvt_pk_bf16_f32 v69, v38, v75
	v_add_u32_e32 v80, 10, v171
	v_lshl_add_u32 v81, v80, 11, v170
	global_store_short v81, v68, s[76:77]
	global_store_short v81, v69, s[76:77] offset:64
	global_store_dword v[110:111], v55, off
	global_store_dword v[110:111], v39, off offset:128
	v_cvt_pk_bf16_f32 v70, v55, v75
	v_cvt_pk_bf16_f32 v71, v39, v75
	v_add_u32_e32 v82, 11, v171
	v_lshl_add_u32 v83, v82, 11, v170
	global_store_short v83, v70, s[76:77]
	global_store_short v83, v71, s[76:77] offset:64
	global_store_dword v[112:113], v56, off
	global_store_dword v[112:113], v40, off offset:128
	v_cvt_pk_bf16_f32 v64, v56, v75
	v_cvt_pk_bf16_f32 v65, v40, v75
	v_add_u32_e32 v76, 16, v171
	v_lshl_add_u32 v77, v76, 11, v170
	global_store_short v77, v64, s[76:77]
	global_store_short v77, v65, s[76:77] offset:64
	global_store_dword v[114:115], v57, off
	global_store_dword v[114:115], v41, off offset:128
	v_cvt_pk_bf16_f32 v66, v57, v75
	v_cvt_pk_bf16_f32 v67, v41, v75
	v_add_u32_e32 v78, 17, v171
	v_lshl_add_u32 v79, v78, 11, v170
	global_store_short v79, v66, s[76:77]
	global_store_short v79, v67, s[76:77] offset:64
	global_store_dword v[116:117], v58, off
	global_store_dword v[116:117], v42, off offset:128
	v_cvt_pk_bf16_f32 v68, v58, v75
	v_cvt_pk_bf16_f32 v69, v42, v75
	v_add_u32_e32 v80, 18, v171
	v_lshl_add_u32 v81, v80, 11, v170
	global_store_short v81, v68, s[76:77]
	global_store_short v81, v69, s[76:77] offset:64
	global_store_dword v[118:119], v59, off
	global_store_dword v[118:119], v43, off offset:128
	v_cvt_pk_bf16_f32 v70, v59, v75
	v_cvt_pk_bf16_f32 v71, v43, v75
	v_add_u32_e32 v82, 19, v171
	v_lshl_add_u32 v83, v82, 11, v170
	global_store_short v83, v70, s[76:77]
	global_store_short v83, v71, s[76:77] offset:64
	global_store_dword v[120:121], v60, off
	global_store_dword v[120:121], v44, off offset:128
	v_cvt_pk_bf16_f32 v64, v60, v75
	v_cvt_pk_bf16_f32 v65, v44, v75
	v_add_u32_e32 v76, 24, v171
	v_lshl_add_u32 v77, v76, 11, v170
	global_store_short v77, v64, s[76:77]
	global_store_short v77, v65, s[76:77] offset:64
	global_store_dword v[122:123], v61, off
	global_store_dword v[122:123], v45, off offset:128
	v_cvt_pk_bf16_f32 v66, v61, v75
	v_cvt_pk_bf16_f32 v67, v45, v75
	v_add_u32_e32 v78, 25, v171
	v_lshl_add_u32 v79, v78, 11, v170
	global_store_short v79, v66, s[76:77]
	global_store_short v79, v67, s[76:77] offset:64
	global_store_dword v[124:125], v62, off
	global_store_dword v[124:125], v46, off offset:128
	v_cvt_pk_bf16_f32 v68, v62, v75
	v_cvt_pk_bf16_f32 v69, v46, v75
	v_add_u32_e32 v80, 26, v171
	v_lshl_add_u32 v81, v80, 11, v170
	global_store_short v81, v68, s[76:77]
	global_store_short v81, v69, s[76:77] offset:64
	global_store_dword v[126:127], v63, off
	global_store_dword v[126:127], v47, off offset:128
	v_cvt_pk_bf16_f32 v70, v63, v75
	v_cvt_pk_bf16_f32 v71, v47, v75
	v_add_u32_e32 v82, 27, v171
	v_lshl_add_u32 v83, v82, 11, v170
	global_store_short v83, v70, s[76:77]
	global_store_short v83, v71, s[76:77] offset:64
; template <bool FIRST>
; __device__ __forceinline__ void residual_epilogue(const Params& p, f32x16 (&acc)[2][2], int m0, int ncolbase) {
;     ...
;         for (int j = 0; j < 2; ++j) {
;           const int n = ncolbase + wn * 64 + j * 32 + lc;
;           float v = hsrc[n] + acc[i][j][r];
;           hp[n] = v;
;           p.hb[(size_t)t * D + n] = (u16)(cvtpk(v, 0.f) & 0xffffu);
;         }
	global_store_dword v[128:129], v16, off
	global_store_dword v[128:129], v0, off offset:128
	v_cvt_pk_bf16_f32 v64, v16, v75
	v_cvt_pk_bf16_f32 v65, v0, v75
	v_add_u32_e32 v76, 32, v171
	v_lshl_add_u32 v77, v76, 11, v170
	global_store_short v77, v64, s[76:77]
	global_store_short v77, v65, s[76:77] offset:64
	global_store_dword v[130:131], v17, off
	global_store_dword v[130:131], v1, off offset:128
	v_cvt_pk_bf16_f32 v66, v17, v75
	v_cvt_pk_bf16_f32 v67, v1, v75
	v_add_u32_e32 v78, 33, v171
	v_lshl_add_u32 v79, v78, 11, v170
	global_store_short v79, v66, s[76:77]
	global_store_short v79, v67, s[76:77] offset:64
	global_store_dword v[132:133], v18, off
	global_store_dword v[132:133], v2, off offset:128
	v_cvt_pk_bf16_f32 v68, v18, v75
	v_cvt_pk_bf16_f32 v69, v2, v75
	v_add_u32_e32 v80, 34, v171
	v_lshl_add_u32 v81, v80, 11, v170
	global_store_short v81, v68, s[76:77]
	global_store_short v81, v69, s[76:77] offset:64
	global_store_dword v[134:135], v19, off
	global_store_dword v[134:135], v3, off offset:128
	v_cvt_pk_bf16_f32 v70, v19, v75
	v_cvt_pk_bf16_f32 v71, v3, v75
	v_add_u32_e32 v82, 35, v171
	v_lshl_add_u32 v83, v82, 11, v170
	global_store_short v83, v70, s[76:77]
	global_store_short v83, v71, s[76:77] offset:64
	global_store_dword v[136:137], v20, off
	global_store_dword v[136:137], v4, off offset:128
	v_cvt_pk_bf16_f32 v64, v20, v75
	v_cvt_pk_bf16_f32 v65, v4, v75
	v_add_u32_e32 v76, 40, v171
	v_lshl_add_u32 v77, v76, 11, v170
	global_store_short v77, v64, s[76:77]
	global_store_short v77, v65, s[76:77] offset:64
	global_store_dword v[138:139], v21, off
	global_store_dword v[138:139], v5, off offset:128
	v_cvt_pk_bf16_f32 v66, v21, v75
	v_cvt_pk_bf16_f32 v67, v5, v75
	v_add_u32_e32 v78, 41, v171
	v_lshl_add_u32 v79, v78, 11, v170
	global_store_short v79, v66, s[76:77]
	global_store_short v79, v67, s[76:77] offset:64
	global_store_dword v[140:141], v22, off
	global_store_dword v[140:141], v6, off offset:128
	v_cvt_pk_bf16_f32 v68, v22, v75
	v_cvt_pk_bf16_f32 v69, v6, v75
	v_add_u32_e32 v80, 42, v171
	v_lshl_add_u32 v81, v80, 11, v170
	global_store_short v81, v68, s[76:77]
	global_store_short v81, v69, s[76:77] offset:64
	global_store_dword v[142:143], v23, off
	global_store_dword v[142:143], v7, off offset:128
	v_cvt_pk_bf16_f32 v70, v23, v75
	v_cvt_pk_bf16_f32 v71, v7, v75
	v_add_u32_e32 v82, 43, v171
	v_lshl_add_u32 v83, v82, 11, v170
	global_store_short v83, v70, s[76:77]
	global_store_short v83, v71, s[76:77] offset:64
	global_store_dword v[144:145], v24, off
	global_store_dword v[144:145], v8, off offset:128
	v_cvt_pk_bf16_f32 v64, v24, v75
	v_cvt_pk_bf16_f32 v65, v8, v75
	v_add_u32_e32 v76, 48, v171
	v_lshl_add_u32 v77, v76, 11, v170
	global_store_short v77, v64, s[76:77]
	global_store_short v77, v65, s[76:77] offset:64
	global_store_dword v[146:147], v25, off
	global_store_dword v[146:147], v9, off offset:128
	v_cvt_pk_bf16_f32 v66, v25, v75
	v_cvt_pk_bf16_f32 v67, v9, v75
	v_add_u32_e32 v78, 49, v171
	v_lshl_add_u32 v79, v78, 11, v170
	global_store_short v79, v66, s[76:77]
	global_store_short v79, v67, s[76:77] offset:64
	global_store_dword v[148:149], v26, off
	global_store_dword v[148:149], v10, off offset:128
	v_cvt_pk_bf16_f32 v68, v26, v75
	v_cvt_pk_bf16_f32 v69, v10, v75
	v_add_u32_e32 v80, 50, v171
	v_lshl_add_u32 v81, v80, 11, v170
	global_store_short v81, v68, s[76:77]
	global_store_short v81, v69, s[76:77] offset:64
	global_store_dword v[150:151], v27, off
	global_store_dword v[150:151], v11, off offset:128
	v_cvt_pk_bf16_f32 v70, v27, v75
	v_cvt_pk_bf16_f32 v71, v11, v75
	v_add_u32_e32 v82, 51, v171
	v_lshl_add_u32 v83, v82, 11, v170
	global_store_short v83, v70, s[76:77]
	global_store_short v83, v71, s[76:77] offset:64
	global_store_dword v[152:153], v28, off
	global_store_dword v[152:153], v12, off offset:128
	v_cvt_pk_bf16_f32 v64, v28, v75
	v_cvt_pk_bf16_f32 v65, v12, v75
	v_add_u32_e32 v76, 56, v171
	v_lshl_add_u32 v77, v76, 11, v170
	global_store_short v77, v64, s[76:77]
	global_store_short v77, v65, s[76:77] offset:64
	global_store_dword v[154:155], v29, off
	global_store_dword v[154:155], v13, off offset:128
	v_cvt_pk_bf16_f32 v66, v29, v75
	v_cvt_pk_bf16_f32 v67, v13, v75
	v_add_u32_e32 v78, 57, v171
	v_lshl_add_u32 v79, v78, 11, v170
	global_store_short v79, v66, s[76:77]
	global_store_short v79, v67, s[76:77] offset:64
	global_store_dword v[156:157], v30, off
	global_store_dword v[156:157], v14, off offset:128
	v_cvt_pk_bf16_f32 v68, v30, v75
	v_cvt_pk_bf16_f32 v69, v14, v75
	v_add_u32_e32 v80, 58, v171
	v_lshl_add_u32 v81, v80, 11, v170
	global_store_short v81, v68, s[76:77]
	global_store_short v81, v69, s[76:77] offset:64
	global_store_dword v[158:159], v31, off
	global_store_dword v[158:159], v15, off offset:128
	v_cvt_pk_bf16_f32 v70, v31, v75
	v_cvt_pk_bf16_f32 v71, v15, v75
	v_add_u32_e32 v82, 59, v171
	v_lshl_add_u32 v83, v82, 11, v170
	global_store_short v83, v70, s[76:77]
	global_store_short v83, v71, s[76:77] offset:64
.Lmy_epi_done_wo:
	s_branch .LBB0_321

; template <bool SWAP, bool SS>
; __device__ __forceinline__ void gemm_main(const u16* __restrict__ A, int lda, int M, int m0,
;                                           const u16* __restrict__ Bt, int ldb, int n0, int K,
;                                           char* smraw, f32x16 (&acc)[2][2]) {
;     ...
;   unsigned aoff[4], boff[4];
; #pragma unroll
;   for (int j = 0; j < 4; ++j) {
;     int r = lrow + 32 * j;
;     int ar = m0 + r; ar = ar < M ? ar : M - 1;
;     aoff[j] = ((unsigned)ar * (unsigned)lda + (unsigned)kc * 8u) * 2u;
;     boff[j] = ((unsigned)(n0 + r) * (unsigned)ldb + (unsigned)kc * 8u) * 2u;
;   }
; #pragma unroll
;   for (int i = 0; i < 2; ++i)
; #pragma unroll
;     for (int j = 0; j < 2; ++j)
; #pragma unroll
;       for (int r = 0; r < 16; ++r) acc[i][j][r] = 0.f;
;   float ss[4] = {0.f, 0.f, 0.f, 0.f};
;   const int nk = K / 64;
;   auto gload = [&](u32x4 (&ga)[4], u32x4 (&gb)[4], int kt) {
; #pragma unroll
;     for (int j = 0; j < 4; ++j) { ga[j] = *(const u32x4*)(Ab + (aoff[j] + (unsigned)kt * 128u)); gb[j] = *(const u32x4*)(Bb + (boff[j] + (unsigned)kt * 128u)); }
;   };
;   auto lwrite = [&](const u32x4 (&ga)[4], const u32x4 (&gb)[4], int buf) {
;     u16* As = sm + buf * (2 * 128 * TSTR);
;     u16* Bs = As + 128 * TSTR;
; #pragma unroll
;     for (int j = 0; j < 4; ++j) {
;       *(u32x4*)(As + (lrow + 32 * j) * TSTR + kc * 8) = ga[j];
;       *(u32x4*)(Bs + (lrow + 32 * j) * TSTR + kc * 8) = gb[j];
;       if (SS) ss[j] += sumsq8(ga[j]);
;     }
;   };
;   auto compute = [&](int buf) {
;     const u16* As = sm + buf * (2 * 128 * TSTR);
;     const u16* Bs = As + 128 * TSTR;
; #pragma unroll
;     for (int ks = 0; ks < 4; ++ks) {
;       bf16x8 af[2], bf[2];
; #pragma unroll
;       for (int i = 0; i < 2; ++i) af[i] = *(const bf16x8*)(As + (wm * 64 + i * 32 + lc) * TSTR + ks * 16 + hf * 8);
; #pragma unroll
;       for (int j = 0; j < 2; ++j) bf[j] = *(const bf16x8*)(Bs + (wn * 64 + j * 32 + lc) * TSTR + ks * 16 + hf * 8);
; #pragma unroll
; __device__ __forceinline__ void phase_poolgemm(const Params& p, char* smraw) {
;     ...
;   for (int tile = blockIdx.x; tile < MT * NT; tile += gridDim.x) {
;     const int mt = tile / NT, nt = tile - mt * NT;
;     const int g = nt >> 1, nh = nt & 1;
;     f32x16 acc[2][2];
;     gemm_main<false, false>(p.pooled + g * 256, D, T, mt * 128, p.PoolWT + (size_t)g * 65536, 256, nh * 128, 256, smraw, acc);
.LBB0_916:
	s_add_i32 s20, s20, s96
	s_add_i32 s3, s3, s10
	s_cmpk_lt_i32 s20, 0x808
	s_cbranch_scc0 .LBB0_1108
.LBB0_917:
	s_ashr_i32 s0, s20, 31
	s_lshr_b32 s0, s0, 29
	s_add_i32 s9, s20, s0
	s_and_b32 s0, s9, -8
	s_sub_i32 s0, s20, s0
	s_ashr_i32 s8, s0, 1
	s_lshl_b32 s0, s8, 8
	s_ashr_i32 s1, s0, 31
	s_lshl_b64 s[6:7], s[0:1], 1
	s_add_u32 s6, s62, s6
	s_addc_u32 s7, s63, s7
	s_lshl_b32 s1, s9, 4
	s_ashr_i32 s9, s8, 31
	v_mov_b32_e32 v33, v189
	s_and_b32 s1, s1, 0xffffff80
	s_lshl_b64 s[8:9], s[8:9], 17
	s_add_u32 s8, s84, s8
	v_ashrrev_i32_e32 v35, 3, v33
	v_lshlrev_b32_e32 v0, 4, v33
	v_and_b32_e32 v32, 0x70, v0
	v_add_u32_e32 v0, s1, v35
	s_addc_u32 s9, s85, s9
	s_and_b32 s21, s3, 0x80
	v_min_i32_e32 v0, 0x803f, v0
	v_lshl_or_b32 v73, v0, 11, v32
	v_add_u32_e32 v0, s21, v35
	v_lshl_or_b32 v162, v0, 9, v32
	v_add_u32_e32 v0, 32, v35
	v_add_u32_e32 v1, s1, v0
	v_add_u32_e32 v0, s21, v0
	v_min_i32_e32 v1, 0x803f, v1
	v_lshl_or_b32 v164, v0, 9, v32
	v_add_u32_e32 v0, 64, v35
	v_lshl_or_b32 v163, v1, 11, v32
	v_add_u32_e32 v1, s1, v0
	v_add_u32_e32 v0, s21, v0
	v_min_i32_e32 v1, 0x803f, v1
	v_lshl_or_b32 v166, v0, 9, v32
	v_add_u32_e32 v0, 0x60, v35
	v_lshl_or_b32 v165, v1, 11, v32
	v_add_u32_e32 v1, s1, v0
	v_min_i32_e32 v1, 0x803f, v1
	v_add_u32_e32 v0, s21, v0
	v_lshl_or_b32 v167, v1, 11, v32
	v_lshl_or_b32 v168, v0, 9, v32
	global_load_dwordx4 v[0:3], v73, s[6:7]
	global_load_dwordx4 v[4:7], v163, s[6:7]
	global_load_dwordx4 v[8:11], v165, s[6:7]
	global_load_dwordx4 v[12:15], v167, s[6:7]
	global_load_dwordx4 v[16:19], v162, s[8:9]
	global_load_dwordx4 v[20:23], v164, s[8:9]
	global_load_dwordx4 v[24:27], v166, s[8:9]
	global_load_dwordx4 v[28:31], v168, s[8:9]
	global_load_dwordx4 v[68:71], v73, s[6:7] offset:128
	global_load_dwordx4 v[74:77], v163, s[6:7] offset:128
	global_load_dwordx4 v[78:81], v165, s[6:7] offset:128
	global_load_dwordx4 v[82:85], v167, s[6:7] offset:128
	global_load_dwordx4 v[86:89], v73, s[6:7] offset:256
	global_load_dwordx4 v[90:93], v163, s[6:7] offset:256
	global_load_dwordx4 v[94:97], v165, s[6:7] offset:256
	global_load_dwordx4 v[98:101], v167, s[6:7] offset:256
	global_load_dwordx4 v[102:105], v162, s[8:9] offset:128
	global_load_dwordx4 v[106:109], v164, s[8:9] offset:128
	global_load_dwordx4 v[110:113], v166, s[8:9] offset:128
	global_load_dwordx4 v[114:117], v168, s[8:9] offset:128
	global_load_dwordx4 v[118:121], v162, s[8:9] offset:256
	global_load_dwordx4 v[122:125], v164, s[8:9] offset:256
	global_load_dwordx4 v[126:129], v166, s[8:9] offset:256
	global_load_dwordx4 v[130:133], v168, s[8:9] offset:256
	v_and_b32_e32 v34, 31, v33
	v_lshrrev_b32_e32 v36, 1, v33
	v_and_or_b32 v37, v36, s12, v34
	v_and_b32_e32 v34, 16, v36
	v_mad_u64_u32 v[66:67], s[22:23], v35, s11, v[32:33]
	v_mad_u64_u32 v[64:65], s[22:23], v37, s11, v[34:35]
	v_add_u32_e32 v67, 0xd800, v66
	s_waitcnt vmcnt(23)
	ds_write_b128 v66, v[0:3]
	s_waitcnt vmcnt(22)
	ds_write_b128 v66, v[4:7] offset:4608
	s_waitcnt vmcnt(21)
	ds_write_b128 v66, v[8:11] offset:9216
	s_waitcnt vmcnt(20)
	ds_write_b128 v66, v[12:15] offset:13824
	s_waitcnt vmcnt(19)
	ds_write_b128 v66, v[16:19] offset:18432
	s_waitcnt vmcnt(18)
	ds_write_b128 v66, v[20:23] offset:23040
	s_waitcnt vmcnt(17)
	ds_write_b128 v66, v[24:27] offset:27648
	s_waitcnt vmcnt(16)
	ds_write_b128 v66, v[28:31] offset:32256
	s_waitcnt lgkmcnt(0)
	s_barrier
	ds_read_b128 v[0:3], v64
	v_and_b32_e32 v4, 0x5f, v33
	v_mul_u32_u24_e32 v4, 0x48, v4
	v_lshl_add_u32 v65, v4, 1, v34
	ds_read_b128 v[4:7], v65 offset:18432
	ds_read_b128 v[134:137], v64 offset:32
	ds_read_b128 v[138:141], v65 offset:18464
	ds_read_b128 v[8:11], v65 offset:23040
	ds_read_b128 v[142:145], v65 offset:23072
	s_waitcnt lgkmcnt(4)
	v_mfma_f32_32x32x16_bf16 v[48:63], v[0:3], v[4:7], 0
	s_waitcnt lgkmcnt(1)
	v_mfma_f32_32x32x16_bf16 v[32:47], v[0:3], v[8:11], 0
	ds_read_b128 v[0:3], v64 offset:4608
	ds_read_b128 v[146:149], v64 offset:4640
	s_waitcnt lgkmcnt(1)
	v_mfma_f32_32x32x16_bf16 v[16:31], v[0:3], v[4:7], 0
	v_mfma_f32_32x32x16_bf16 v[0:15], v[0:3], v[8:11], 0
	v_mfma_f32_32x32x16_bf16 v[48:63], v[134:137], v[138:141], v[48:63]
	v_mfma_f32_32x32x16_bf16 v[32:47], v[134:137], v[142:145], v[32:47]
	s_waitcnt lgkmcnt(0)
	v_mfma_f32_32x32x16_bf16 v[16:31], v[146:149], v[138:141], v[16:31]
	v_mfma_f32_32x32x16_bf16 v[0:15], v[146:149], v[142:145], v[0:15]
	ds_read_b128 v[134:137], v64 offset:64
	ds_read_b128 v[138:141], v65 offset:18496
	ds_read_b128 v[142:145], v64 offset:96
	ds_read_b128 v[146:149], v65 offset:18528
	ds_read_b128 v[150:153], v65 offset:23104
	ds_read_b128 v[154:157], v65 offset:23136
	s_waitcnt lgkmcnt(4)
	v_mfma_f32_32x32x16_bf16 v[48:63], v[134:137], v[138:141], v[48:63]
	s_waitcnt lgkmcnt(1)
	v_mfma_f32_32x32x16_bf16 v[32:47], v[134:137], v[150:153], v[32:47]
	ds_read_b128 v[134:137], v64 offset:4672
	ds_read_b128 v[158:161], v64 offset:4704
	s_waitcnt vmcnt(15)
	ds_write_b128 v66, v[68:71] offset:36864
	s_waitcnt vmcnt(7)
	ds_write_b128 v66, v[102:105] offset:55296
	ds_write_b128 v66, v[74:77] offset:41472
	s_waitcnt vmcnt(6)
	ds_write_b128 v66, v[106:109] offset:59904
	ds_write_b128 v66, v[78:81] offset:46080
	s_waitcnt vmcnt(5)
	ds_write_b128 v66, v[110:113] offset:64512
	ds_write_b128 v66, v[82:85] offset:50688
	s_waitcnt vmcnt(4)
	ds_write_b128 v67, v[114:117] offset:13824
	global_load_dwordx4 v[68:71], v73, s[6:7] offset:384
	global_load_dwordx4 v[74:77], v162, s[8:9] offset:384
	global_load_dwordx4 v[78:81], v163, s[6:7] offset:384
	global_load_dwordx4 v[82:85], v164, s[8:9] offset:384
	global_load_dwordx4 v[102:105], v165, s[6:7] offset:384
	global_load_dwordx4 v[106:109], v166, s[8:9] offset:384
	global_load_dwordx4 v[110:113], v167, s[6:7] offset:384
	global_load_dwordx4 v[114:117], v168, s[8:9] offset:384
	s_waitcnt lgkmcnt(0)
	s_barrier
; template <bool SWAP, bool SS>
; __device__ __forceinline__ void gemm_main(const u16* __restrict__ A, int lda, int M, int m0,
;                                           const u16* __restrict__ Bt, int ldb, int n0, int K,
;                                           char* smraw, f32x16 (&acc)[2][2]) {
;     ...
;   auto gload = [&](u32x4 (&ga)[4], u32x4 (&gb)[4], int kt) {
; #pragma unroll
;     for (int j = 0; j < 4; ++j) { ga[j] = *(const u32x4*)(Ab + (aoff[j] + (unsigned)kt * 128u)); gb[j] = *(const u32x4*)(Bb + (boff[j] + (unsigned)kt * 128u)); }
;   };
;   auto lwrite = [&](const u32x4 (&ga)[4], const u32x4 (&gb)[4], int buf) {
;     u16* As = sm + buf * (2 * 128 * TSTR);
;     u16* Bs = As + 128 * TSTR;
; #pragma unroll
;     for (int j = 0; j < 4; ++j) {
;       *(u32x4*)(As + (lrow + 32 * j) * TSTR + kc * 8) = ga[j];
;       *(u32x4*)(Bs + (lrow + 32 * j) * TSTR + kc * 8) = gb[j];
;       if (SS) ss[j] += sumsq8(ga[j]);
;     }
;   };
;   auto compute = [&](int buf) {
;     const u16* As = sm + buf * (2 * 128 * TSTR);
;     const u16* Bs = As + 128 * TSTR;
; #pragma unroll
;     for (int ks = 0; ks < 4; ++ks) {
;       bf16x8 af[2], bf[2];
; #pragma unroll
;       for (int i = 0; i < 2; ++i) af[i] = *(const bf16x8*)(As + (wm * 64 + i * 32 + lc) * TSTR + ks * 16 + hf * 8);
; #pragma unroll
;       for (int j = 0; j < 2; ++j) bf[j] = *(const bf16x8*)(Bs + (wn * 64 + j * 32 + lc) * TSTR + ks * 16 + hf * 8);
; #pragma unroll
;       for (int i = 0; i < 2; ++i)
; #pragma unroll
;         for (int j = 0; j < 2; ++j)
;           acc[i][j] = SWAP ? mfma32(bf[j], af[i], acc[i][j]) : mfma32(af[i], bf[j], acc[i][j]);
;     }
;   };
;   u32x4 ga0[4], gb0[4], ga1[4], gb1[4];
;   gload(ga0, gb0, 0);
;   if (nk > 1) gload(ga1, gb1, 1);
;   lwrite(ga0, gb0, 0);
;   if (nk > 2) gload(ga0, gb0, 2);
;   __syncthreads();
;   for (int kt = 0; kt < nk; kt += 2) {
;     compute(0);
;     if (kt + 1 < nk) lwrite(ga1, gb1, 1);
;     if (kt + 3 < nk) gload(ga1, gb1, kt + 3);
;     __syncthreads();
;     if (kt + 1 < nk) {
;       compute(1);
;       if (kt + 2 < nk) lwrite(ga0, gb0, 0);
;       if (kt + 4 < nk) gload(ga0, gb0, kt + 4);
;       __syncthreads();
;     }
	v_mfma_f32_32x32x16_bf16 v[16:31], v[134:137], v[138:141], v[16:31]
	v_mfma_f32_32x32x16_bf16 v[0:15], v[134:137], v[150:153], v[0:15]
	v_mfma_f32_32x32x16_bf16 v[48:63], v[142:145], v[146:149], v[48:63]
	v_mfma_f32_32x32x16_bf16 v[32:47], v[142:145], v[154:157], v[32:47]
	v_mfma_f32_32x32x16_bf16 v[16:31], v[158:161], v[146:149], v[16:31]
	ds_read_b128 v[134:137], v64 offset:36864
	ds_read_b128 v[138:141], v65 offset:55296
	ds_read_b128 v[142:145], v64 offset:36896
	ds_read_b128 v[146:149], v65 offset:55328
	v_mfma_f32_32x32x16_bf16 v[0:15], v[158:161], v[154:157], v[0:15]
	ds_read_b128 v[150:153], v65 offset:59904
	ds_read_b128 v[154:157], v65 offset:59936
	s_waitcnt lgkmcnt(4)
	v_mfma_f32_32x32x16_bf16 v[48:63], v[134:137], v[138:141], v[48:63]
	s_waitcnt lgkmcnt(1)
	v_mfma_f32_32x32x16_bf16 v[32:47], v[134:137], v[150:153], v[32:47]
	ds_read_b128 v[134:137], v64 offset:41472
	ds_read_b128 v[158:161], v64 offset:41504
	s_waitcnt lgkmcnt(1)
	v_mfma_f32_32x32x16_bf16 v[16:31], v[134:137], v[138:141], v[16:31]
	v_mfma_f32_32x32x16_bf16 v[0:15], v[134:137], v[150:153], v[0:15]
	v_mfma_f32_32x32x16_bf16 v[48:63], v[142:145], v[146:149], v[48:63]
	v_mfma_f32_32x32x16_bf16 v[32:47], v[142:145], v[154:157], v[32:47]
	s_waitcnt lgkmcnt(0)
	v_mfma_f32_32x32x16_bf16 v[16:31], v[158:161], v[146:149], v[16:31]
	ds_read_b128 v[134:137], v64 offset:36928
	ds_read_b128 v[138:141], v65 offset:55360
	ds_read_b128 v[142:145], v64 offset:36960
	ds_read_b128 v[146:149], v65 offset:55392
	v_mfma_f32_32x32x16_bf16 v[0:15], v[158:161], v[154:157], v[0:15]
	ds_read_b128 v[150:153], v65 offset:59968
	ds_read_b128 v[154:157], v65 offset:60000
	s_waitcnt lgkmcnt(4)
	v_mfma_f32_32x32x16_bf16 v[48:63], v[134:137], v[138:141], v[48:63]
	s_waitcnt lgkmcnt(1)
	v_mfma_f32_32x32x16_bf16 v[32:47], v[134:137], v[150:153], v[32:47]
	ds_read_b128 v[134:137], v64 offset:41536
	ds_read_b128 v[158:161], v64 offset:41568
	ds_write_b128 v66, v[86:89]
	s_waitcnt vmcnt(11)
	ds_write_b128 v66, v[118:121] offset:18432
	ds_write_b128 v66, v[90:93] offset:4608
	s_waitcnt vmcnt(10)
	ds_write_b128 v66, v[122:125] offset:23040
	ds_write_b128 v66, v[94:97] offset:9216
	s_waitcnt vmcnt(9)
	ds_write_b128 v66, v[126:129] offset:27648
	ds_write_b128 v66, v[98:101] offset:13824
	s_waitcnt vmcnt(8)
	ds_write_b128 v66, v[130:133] offset:32256
	s_waitcnt lgkmcnt(0)
	s_barrier
	ds_read_b128 v[86:89], v64
	ds_read_b128 v[90:93], v65 offset:18432
	ds_read_b128 v[94:97], v64 offset:32
	ds_read_b128 v[98:101], v65 offset:18464
	ds_read_b128 v[118:121], v65 offset:23040
	ds_read_b128 v[122:125], v65 offset:23072
	v_mfma_f32_32x32x16_bf16 v[16:31], v[134:137], v[138:141], v[16:31]
	v_mfma_f32_32x32x16_bf16 v[0:15], v[134:137], v[150:153], v[0:15]
	v_mfma_f32_32x32x16_bf16 v[48:63], v[142:145], v[146:149], v[48:63]
	v_mfma_f32_32x32x16_bf16 v[32:47], v[142:145], v[154:157], v[32:47]
	v_mfma_f32_32x32x16_bf16 v[16:31], v[158:161], v[146:149], v[16:31]
	v_mfma_f32_32x32x16_bf16 v[0:15], v[158:161], v[154:157], v[0:15]
	s_waitcnt lgkmcnt(4)
	v_mfma_f32_32x32x16_bf16 v[48:63], v[86:89], v[90:93], v[48:63]
	s_waitcnt lgkmcnt(1)
	v_mfma_f32_32x32x16_bf16 v[32:47], v[86:89], v[118:121], v[32:47]
	ds_read_b128 v[86:89], v64 offset:4608
	ds_read_b128 v[126:129], v64 offset:4640
	s_waitcnt lgkmcnt(1)
	v_mfma_f32_32x32x16_bf16 v[16:31], v[86:89], v[90:93], v[16:31]
	v_mfma_f32_32x32x16_bf16 v[0:15], v[86:89], v[118:121], v[0:15]
	v_mfma_f32_32x32x16_bf16 v[48:63], v[94:97], v[98:101], v[48:63]
	v_mfma_f32_32x32x16_bf16 v[32:47], v[94:97], v[122:125], v[32:47]
	s_waitcnt lgkmcnt(0)
	v_mfma_f32_32x32x16_bf16 v[16:31], v[126:129], v[98:101], v[16:31]
	ds_read_b128 v[86:89], v64 offset:64
	ds_read_b128 v[90:93], v65 offset:18496
	ds_read_b128 v[94:97], v64 offset:96
	ds_read_b128 v[98:101], v65 offset:18528
	v_mfma_f32_32x32x16_bf16 v[0:15], v[126:129], v[122:125], v[0:15]
	ds_read_b128 v[118:121], v65 offset:23104
	ds_read_b128 v[122:125], v65 offset:23136
	s_waitcnt lgkmcnt(4)
	v_mfma_f32_32x32x16_bf16 v[48:63], v[86:89], v[90:93], v[48:63]
	s_waitcnt lgkmcnt(1)
	v_mfma_f32_32x32x16_bf16 v[32:47], v[86:89], v[118:121], v[32:47]
	ds_read_b128 v[86:89], v64 offset:4672
	ds_read_b128 v[126:129], v64 offset:4704
	s_waitcnt vmcnt(7)
	ds_write_b128 v66, v[68:71] offset:36864
	s_waitcnt vmcnt(6)
	ds_write_b128 v66, v[74:77] offset:55296
	s_waitcnt vmcnt(5)
	ds_write_b128 v66, v[78:81] offset:41472
	s_waitcnt vmcnt(4)
	ds_write_b128 v66, v[82:85] offset:59904
	s_waitcnt vmcnt(3)
	ds_write_b128 v66, v[102:105] offset:46080
	s_waitcnt vmcnt(2)
	ds_write_b128 v66, v[106:109] offset:64512
	s_waitcnt vmcnt(1)
	ds_write_b128 v66, v[110:113] offset:50688
	s_waitcnt vmcnt(0)
	ds_write_b128 v67, v[114:117] offset:13824
	s_waitcnt lgkmcnt(0)
	s_barrier
; __device__ __forceinline__ int tid_opaque() { int t = threadIdx.x; asm volatile("" : "+v"(t)); return t; }
; __device__ __forceinline__ int crow(int r, int hf) { return (r & 3) + 8 * (r >> 2) + 4 * hf; }
; template <bool SWAP, bool SS>
; __device__ __forceinline__ void gemm_main(const u16* __restrict__ A, int lda, int M, int m0,
;                                           const u16* __restrict__ Bt, int ldb, int n0, int K,
;                                           char* smraw, f32x16 (&acc)[2][2]) {
;     ...
;   auto compute = [&](int buf) {
;     const u16* As = sm + buf * (2 * 128 * TSTR);
;     const u16* Bs = As + 128 * TSTR;
; #pragma unroll
;     for (int ks = 0; ks < 4; ++ks) {
;       bf16x8 af[2], bf[2];
; #pragma unroll
;       for (int i = 0; i < 2; ++i) af[i] = *(const bf16x8*)(As + (wm * 64 + i * 32 + lc) * TSTR + ks * 16 + hf * 8);
; #pragma unroll
;       for (int j = 0; j < 2; ++j) bf[j] = *(const bf16x8*)(Bs + (wn * 64 + j * 32 + lc) * TSTR + ks * 16 + hf * 8);
; #pragma unroll
;       for (int i = 0; i < 2; ++i)
; #pragma unroll
;         for (int j = 0; j < 2; ++j)
;           acc[i][j] = SWAP ? mfma32(bf[j], af[i], acc[i][j]) : mfma32(af[i], bf[j], acc[i][j]);
;     }
;   };
; template <bool FIRST>
; __device__ __forceinline__ void residual_epilogue(const Params& p, f32x16 (&acc)[2][2], int m0, int ncolbase) {
;   const int tid = tid_opaque(), w = tid >> 6, l = tid & 63, lc = l & 31, hf = l >> 5;
;   const int wm = w >> 1, wn = w & 1;
; #pragma unroll
;   for (int i = 0; i < 2; ++i)
; #pragma unroll
;     for (int r = 0; r < 16; ++r) {
;       const int t = m0 + wm * 64 + i * 32 + crow(r, hf);
;       if (t < T) {
;         float* hp = hrow(p, t);
;         const float* hsrc = hp;
;         if (FIRST) { const int b = t / L, pp = t - b * L; hsrc = pp < NM ? p.meta + (size_t)pp * D : p.x + (size_t)(b * SEQ + pp - NM) * D; }
; #pragma unroll
;         for (int j = 0; j < 2; ++j) {
;           const int n = ncolbase + wn * 64 + j * 32 + lc;
;           float v = hsrc[n] + acc[i][j][r];
	ds_read_b128 v[66:69], v64 offset:36864
	ds_read_b128 v[74:77], v65 offset:55296
	ds_read_b128 v[78:81], v64 offset:36896
	ds_read_b128 v[82:85], v65 offset:55328
	v_mfma_f32_32x32x16_bf16 v[16:31], v[86:89], v[90:93], v[16:31]
	v_mfma_f32_32x32x16_bf16 v[0:15], v[86:89], v[118:121], v[0:15]
	ds_read_b128 v[86:89], v65 offset:59904
	ds_read_b128 v[90:93], v65 offset:59936
	v_mfma_f32_32x32x16_bf16 v[48:63], v[94:97], v[98:101], v[48:63]
	v_mfma_f32_32x32x16_bf16 v[32:47], v[94:97], v[122:125], v[32:47]
	v_mfma_f32_32x32x16_bf16 v[16:31], v[126:129], v[98:101], v[16:31]
	v_mfma_f32_32x32x16_bf16 v[0:15], v[126:129], v[122:125], v[0:15]
	s_waitcnt lgkmcnt(4)
	v_mfma_f32_32x32x16_bf16 v[48:63], v[66:69], v[74:77], v[48:63]
	s_waitcnt lgkmcnt(1)
	v_mfma_f32_32x32x16_bf16 v[32:47], v[66:69], v[86:89], v[32:47]
	ds_read_b128 v[66:69], v64 offset:41472
	ds_read_b128 v[94:97], v64 offset:41504
	s_waitcnt lgkmcnt(1)
	v_mfma_f32_32x32x16_bf16 v[16:31], v[66:69], v[74:77], v[16:31]
	v_mfma_f32_32x32x16_bf16 v[0:15], v[66:69], v[86:89], v[0:15]
	v_mfma_f32_32x32x16_bf16 v[48:63], v[78:81], v[82:85], v[48:63]
	v_mfma_f32_32x32x16_bf16 v[32:47], v[78:81], v[90:93], v[32:47]
	s_waitcnt lgkmcnt(0)
	v_mfma_f32_32x32x16_bf16 v[16:31], v[94:97], v[82:85], v[16:31]
	ds_read_b128 v[66:69], v64 offset:36928
	ds_read_b128 v[74:77], v65 offset:55360
	ds_read_b128 v[78:81], v64 offset:36960
	ds_read_b128 v[82:85], v65 offset:55392
	v_mfma_f32_32x32x16_bf16 v[0:15], v[94:97], v[90:93], v[0:15]
	ds_read_b128 v[86:89], v65 offset:59968
	ds_read_b128 v[90:93], v65 offset:60000
	s_waitcnt lgkmcnt(4)
	v_mfma_f32_32x32x16_bf16 v[48:63], v[66:69], v[74:77], v[48:63]
	s_waitcnt lgkmcnt(1)
	v_mfma_f32_32x32x16_bf16 v[32:47], v[66:69], v[86:89], v[32:47]
	ds_read_b128 v[66:69], v64 offset:41536
	ds_read_b128 v[94:97], v64 offset:41568
	v_mov_b32_e32 v64, v189
	s_waitcnt lgkmcnt(0)
	s_barrier
	v_mfma_f32_32x32x16_bf16 v[16:31], v[66:69], v[74:77], v[16:31]
	v_mfma_f32_32x32x16_bf16 v[0:15], v[66:69], v[86:89], v[0:15]
	v_mfma_f32_32x32x16_bf16 v[48:63], v[78:81], v[82:85], v[48:63]
	v_mfma_f32_32x32x16_bf16 v[32:47], v[78:81], v[90:93], v[32:47]
	v_mfma_f32_32x32x16_bf16 v[16:31], v[94:97], v[82:85], v[16:31]
	v_mfma_f32_32x32x16_bf16 v[0:15], v[94:97], v[90:93], v[0:15]
	v_and_b32_e32 v172, 31, v189
	v_bfe_u32 v173, v189, 5, 1
	v_bfe_u32 v174, v189, 6, 1
	v_bfe_u32 v175, v189, 7, 1
	v_lshl_add_u32 v172, v174, 6, v172
	s_or_b32 s37, s0, s21
	v_lshlrev_b32_e32 v175, 6, v175
	v_add_u32_e32 v172, s37, v172
	v_lshl_add_u32 v171, v173, 2, v175
	v_add_u32_e32 v171, s1, v171
	v_lshlrev_b32_e32 v168, 2, v172
	v_mov_b32_e32 v169, 0
	v_lshlrev_b32_e32 v170, 1, v172
	v_readfirstlane_b32 s37, v171
	s_mov_b32 s47, 0x8040
	s_cmp_ge_u32 s37, s47
	s_cbranch_scc1 .Lmy_epi_done_pg
	s_mov_b32 s36, 0x7fc02
	s_movk_i32 s46, 0xdff0
	v_readlane_b32 s42, v254, 30
	v_readlane_b32 s43, v254, 31
	v_readlane_b32 s44, v254, 32
	v_readlane_b32 s45, v254, 33
	v_mov_b32_e32 v177, 0
	v_mov_b32_e32 v179, 0
	v_mov_b32_e32 v81, 0
	v_mov_b32_e32 v83, 0
	v_mov_b32_e32 v75, 0
	s_sub_u32 s42, s42, 0x10000
	s_subb_u32 s43, s43, 0
	v_mov_b32_e32 v160, s42
	v_mov_b32_e32 v161, s43
	v_mov_b32_e32 v162, s44
	v_mov_b32_e32 v163, s45
	v_lshl_add_u64 v[160:161], v[168:169], 0, v[160:161]
	v_lshl_add_u64 v[162:163], v[168:169], 0, v[162:163]
	v_add_u32_e32 v172, 0, v171
	v_mul_hi_u32 v173, v172, s36
	v_mad_i32_i24 v174, v173, s46, v172
	v_cmp_gt_u32_e32 vcc, 16, v174
	v_lshlrev_b32_e32 v190, 12, v174
	v_lshl_add_u32 v175, v173, 25, v190
	v_lshl_add_u32 v188, v173, 16, v190
	v_cndmask_b32_e32 v176, v175, v188, vcc
	v_cndmask_b32_e32 v180, v160, v162, vcc
	v_cndmask_b32_e32 v181, v161, v163, vcc
	v_lshl_add_u64 v[96:97], v[176:177], 0, v[180:181]
	global_load_dword v192, v[96:97], off
	global_load_dword v193, v[96:97], off offset:128
	v_add_u32_e32 v76, 1, v171
	v_mul_hi_u32 v77, v76, s36
	v_mad_i32_i24 v78, v77, s46, v76
	v_cmp_gt_u32_e32 vcc, 16, v78
	v_lshlrev_b32_e32 v93, 12, v78
	v_lshl_add_u32 v79, v77, 25, v93
	v_lshl_add_u32 v92, v77, 16, v93
	v_cndmask_b32_e32 v80, v79, v92, vcc
	v_cndmask_b32_e32 v84, v160, v162, vcc
	v_cndmask_b32_e32 v85, v161, v163, vcc
	v_lshl_add_u64 v[98:99], v[80:81], 0, v[84:85]
	global_load_dword v194, v[98:99], off
	global_load_dword v195, v[98:99], off offset:128
	v_add_u32_e32 v172, 2, v171
	v_mul_hi_u32 v173, v172, s36
	v_mad_i32_i24 v174, v173, s46, v172
	v_cmp_gt_u32_e32 vcc, 16, v174
	v_lshlrev_b32_e32 v190, 12, v174
	v_lshl_add_u32 v175, v173, 25, v190
	v_lshl_add_u32 v188, v173, 16, v190
	v_cndmask_b32_e32 v176, v175, v188, vcc
	v_cndmask_b32_e32 v180, v160, v162, vcc
	v_cndmask_b32_e32 v181, v161, v163, vcc
	v_lshl_add_u64 v[100:101], v[176:177], 0, v[180:181]
	global_load_dword v196, v[100:101], off
	global_load_dword v197, v[100:101], off offset:128
	v_add_u32_e32 v76, 3, v171
	v_mul_hi_u32 v77, v76, s36
	v_mad_i32_i24 v78, v77, s46, v76
	v_cmp_gt_u32_e32 vcc, 16, v78
	v_lshlrev_b32_e32 v93, 12, v78
	v_lshl_add_u32 v79, v77, 25, v93
	v_lshl_add_u32 v92, v77, 16, v93
	v_cndmask_b32_e32 v80, v79, v92, vcc
	v_cndmask_b32_e32 v84, v160, v162, vcc
	v_cndmask_b32_e32 v85, v161, v163, vcc
	v_lshl_add_u64 v[102:103], v[80:81], 0, v[84:85]
	global_load_dword v198, v[102:103], off
	global_load_dword v199, v[102:103], off offset:128
	v_add_u32_e32 v172, 8, v171
	v_mul_hi_u32 v173, v172, s36
	v_mad_i32_i24 v174, v173, s46, v172
	v_cmp_gt_u32_e32 vcc, 16, v174
	v_lshlrev_b32_e32 v190, 12, v174
	v_lshl_add_u32 v175, v173, 25, v190
	v_lshl_add_u32 v188, v173, 16, v190
	v_cndmask_b32_e32 v176, v175, v188, vcc
	v_cndmask_b32_e32 v180, v160, v162, vcc
	v_cndmask_b32_e32 v181, v161, v163, vcc
; __device__ __forceinline__ int tid_opaque() { int t = threadIdx.x; asm volatile("" : "+v"(t)); return t; }
; __device__ __forceinline__ int crow(int r, int hf) { return (r & 3) + 8 * (r >> 2) + 4 * hf; }
; template <bool FIRST>
; __device__ __forceinline__ void residual_epilogue(const Params& p, f32x16 (&acc)[2][2], int m0, int ncolbase) {
;   const int tid = tid_opaque(), w = tid >> 6, l = tid & 63, lc = l & 31, hf = l >> 5;
;   const int wm = w >> 1, wn = w & 1;
; #pragma unroll
;   for (int i = 0; i < 2; ++i)
; #pragma unroll
;     for (int r = 0; r < 16; ++r) {
;       const int t = m0 + wm * 64 + i * 32 + crow(r, hf);
;       if (t < T) {
;         float* hp = hrow(p, t);
;         const float* hsrc = hp;
;         if (FIRST) { const int b = t / L, pp = t - b * L; hsrc = pp < NM ? p.meta + (size_t)pp * D : p.x + (size_t)(b * SEQ + pp - NM) * D; }
; #pragma unroll
;         for (int j = 0; j < 2; ++j) {
;           const int n = ncolbase + wn * 64 + j * 32 + lc;
;           float v = hsrc[n] + acc[i][j][r];
	v_lshl_add_u64 v[104:105], v[176:177], 0, v[180:181]
	global_load_dword v200, v[104:105], off
	global_load_dword v201, v[104:105], off offset:128
	v_add_u32_e32 v76, 9, v171
	v_mul_hi_u32 v77, v76, s36
	v_mad_i32_i24 v78, v77, s46, v76
	v_cmp_gt_u32_e32 vcc, 16, v78
	v_lshlrev_b32_e32 v93, 12, v78
	v_lshl_add_u32 v79, v77, 25, v93
	v_lshl_add_u32 v92, v77, 16, v93
	v_cndmask_b32_e32 v80, v79, v92, vcc
	v_cndmask_b32_e32 v84, v160, v162, vcc
	v_cndmask_b32_e32 v85, v161, v163, vcc
	v_lshl_add_u64 v[106:107], v[80:81], 0, v[84:85]
	global_load_dword v202, v[106:107], off
	global_load_dword v203, v[106:107], off offset:128
	v_add_u32_e32 v172, 10, v171
	v_mul_hi_u32 v173, v172, s36
	v_mad_i32_i24 v174, v173, s46, v172
	v_cmp_gt_u32_e32 vcc, 16, v174
	v_lshlrev_b32_e32 v190, 12, v174
	v_lshl_add_u32 v175, v173, 25, v190
	v_lshl_add_u32 v188, v173, 16, v190
	v_cndmask_b32_e32 v176, v175, v188, vcc
	v_cndmask_b32_e32 v180, v160, v162, vcc
	v_cndmask_b32_e32 v181, v161, v163, vcc
	v_lshl_add_u64 v[108:109], v[176:177], 0, v[180:181]
	global_load_dword v204, v[108:109], off
	global_load_dword v205, v[108:109], off offset:128
	v_add_u32_e32 v76, 11, v171
	v_mul_hi_u32 v77, v76, s36
	v_mad_i32_i24 v78, v77, s46, v76
	v_cmp_gt_u32_e32 vcc, 16, v78
	v_lshlrev_b32_e32 v93, 12, v78
	v_lshl_add_u32 v79, v77, 25, v93
	v_lshl_add_u32 v92, v77, 16, v93
	v_cndmask_b32_e32 v80, v79, v92, vcc
	v_cndmask_b32_e32 v84, v160, v162, vcc
	v_cndmask_b32_e32 v85, v161, v163, vcc
	v_lshl_add_u64 v[110:111], v[80:81], 0, v[84:85]
	global_load_dword v206, v[110:111], off
	global_load_dword v207, v[110:111], off offset:128
	v_add_u32_e32 v172, 16, v171
	v_mul_hi_u32 v173, v172, s36
	v_mad_i32_i24 v174, v173, s46, v172
	v_cmp_gt_u32_e32 vcc, 16, v174
	v_lshlrev_b32_e32 v190, 12, v174
	v_lshl_add_u32 v175, v173, 25, v190
	v_lshl_add_u32 v188, v173, 16, v190
	v_cndmask_b32_e32 v176, v175, v188, vcc
	v_cndmask_b32_e32 v180, v160, v162, vcc
	v_cndmask_b32_e32 v181, v161, v163, vcc
	v_lshl_add_u64 v[112:113], v[176:177], 0, v[180:181]
	global_load_dword v208, v[112:113], off
	global_load_dword v209, v[112:113], off offset:128
	v_add_u32_e32 v76, 17, v171
	v_mul_hi_u32 v77, v76, s36
	v_mad_i32_i24 v78, v77, s46, v76
	v_cmp_gt_u32_e32 vcc, 16, v78
	v_lshlrev_b32_e32 v93, 12, v78
	v_lshl_add_u32 v79, v77, 25, v93
	v_lshl_add_u32 v92, v77, 16, v93
	v_cndmask_b32_e32 v80, v79, v92, vcc
	v_cndmask_b32_e32 v84, v160, v162, vcc
	v_cndmask_b32_e32 v85, v161, v163, vcc
	v_lshl_add_u64 v[114:115], v[80:81], 0, v[84:85]
	global_load_dword v210, v[114:115], off
	global_load_dword v211, v[114:115], off offset:128
	v_add_u32_e32 v172, 18, v171
	v_mul_hi_u32 v173, v172, s36
	v_mad_i32_i24 v174, v173, s46, v172
	v_cmp_gt_u32_e32 vcc, 16, v174
	v_lshlrev_b32_e32 v190, 12, v174
	v_lshl_add_u32 v175, v173, 25, v190
	v_lshl_add_u32 v188, v173, 16, v190
	v_cndmask_b32_e32 v176, v175, v188, vcc
	v_cndmask_b32_e32 v180, v160, v162, vcc
	v_cndmask_b32_e32 v181, v161, v163, vcc
	v_lshl_add_u64 v[116:117], v[176:177], 0, v[180:181]
	global_load_dword v212, v[116:117], off
	global_load_dword v213, v[116:117], off offset:128
	v_add_u32_e32 v76, 19, v171
	v_mul_hi_u32 v77, v76, s36
	v_mad_i32_i24 v78, v77, s46, v76
	v_cmp_gt_u32_e32 vcc, 16, v78
	v_lshlrev_b32_e32 v93, 12, v78
	v_lshl_add_u32 v79, v77, 25, v93
	v_lshl_add_u32 v92, v77, 16, v93
	v_cndmask_b32_e32 v80, v79, v92, vcc
	v_cndmask_b32_e32 v84, v160, v162, vcc
	v_cndmask_b32_e32 v85, v161, v163, vcc
	v_lshl_add_u64 v[118:119], v[80:81], 0, v[84:85]
	global_load_dword v214, v[118:119], off
	global_load_dword v215, v[118:119], off offset:128
	v_add_u32_e32 v172, 24, v171
	v_mul_hi_u32 v173, v172, s36
	v_mad_i32_i24 v174, v173, s46, v172
	v_cmp_gt_u32_e32 vcc, 16, v174
	v_lshlrev_b32_e32 v190, 12, v174
	v_lshl_add_u32 v175, v173, 25, v190
	v_lshl_add_u32 v188, v173, 16, v190
	v_cndmask_b32_e32 v176, v175, v188, vcc
	v_cndmask_b32_e32 v180, v160, v162, vcc
	v_cndmask_b32_e32 v181, v161, v163, vcc
	v_lshl_add_u64 v[120:121], v[176:177], 0, v[180:181]
	global_load_dword v216, v[120:121], off
	global_load_dword v217, v[120:121], off offset:128
	v_add_u32_e32 v76, 25, v171
	v_mul_hi_u32 v77, v76, s36
	v_mad_i32_i24 v78, v77, s46, v76
	v_cmp_gt_u32_e32 vcc, 16, v78
	v_lshlrev_b32_e32 v93, 12, v78
	v_lshl_add_u32 v79, v77, 25, v93
	v_lshl_add_u32 v92, v77, 16, v93
	v_cndmask_b32_e32 v80, v79, v92, vcc
	v_cndmask_b32_e32 v84, v160, v162, vcc
	v_cndmask_b32_e32 v85, v161, v163, vcc
	v_lshl_add_u64 v[122:123], v[80:81], 0, v[84:85]
	global_load_dword v218, v[122:123], off
	global_load_dword v219, v[122:123], off offset:128
	v_add_u32_e32 v172, 26, v171
	v_mul_hi_u32 v173, v172, s36
	v_mad_i32_i24 v174, v173, s46, v172
	v_cmp_gt_u32_e32 vcc, 16, v174
	v_lshlrev_b32_e32 v190, 12, v174
	v_lshl_add_u32 v175, v173, 25, v190
	v_lshl_add_u32 v188, v173, 16, v190
	v_cndmask_b32_e32 v176, v175, v188, vcc
	v_cndmask_b32_e32 v180, v160, v162, vcc
	v_cndmask_b32_e32 v181, v161, v163, vcc
	v_lshl_add_u64 v[124:125], v[176:177], 0, v[180:181]
	global_load_dword v220, v[124:125], off
	global_load_dword v221, v[124:125], off offset:128
	v_add_u32_e32 v76, 27, v171
	v_mul_hi_u32 v77, v76, s36
	v_mad_i32_i24 v78, v77, s46, v76
	v_cmp_gt_u32_e32 vcc, 16, v78
	v_lshlrev_b32_e32 v93, 12, v78
	v_lshl_add_u32 v79, v77, 25, v93
	v_lshl_add_u32 v92, v77, 16, v93
	v_cndmask_b32_e32 v80, v79, v92, vcc
	v_cndmask_b32_e32 v84, v160, v162, vcc
	v_cndmask_b32_e32 v85, v161, v163, vcc
	v_lshl_add_u64 v[126:127], v[80:81], 0, v[84:85]
	global_load_dword v222, v[126:127], off
	global_load_dword v223, v[126:127], off offset:128
	v_add_u32_e32 v172, 32, v171
	v_mul_hi_u32 v173, v172, s36
; __device__ __forceinline__ int tid_opaque() { int t = threadIdx.x; asm volatile("" : "+v"(t)); return t; }
; __device__ __forceinline__ int crow(int r, int hf) { return (r & 3) + 8 * (r >> 2) + 4 * hf; }
; template <bool FIRST>
; __device__ __forceinline__ void residual_epilogue(const Params& p, f32x16 (&acc)[2][2], int m0, int ncolbase) {
;   const int tid = tid_opaque(), w = tid >> 6, l = tid & 63, lc = l & 31, hf = l >> 5;
;   const int wm = w >> 1, wn = w & 1;
; #pragma unroll
;   for (int i = 0; i < 2; ++i)
; #pragma unroll
;     for (int r = 0; r < 16; ++r) {
;       const int t = m0 + wm * 64 + i * 32 + crow(r, hf);
;       if (t < T) {
;         float* hp = hrow(p, t);
;         const float* hsrc = hp;
;         if (FIRST) { const int b = t / L, pp = t - b * L; hsrc = pp < NM ? p.meta + (size_t)pp * D : p.x + (size_t)(b * SEQ + pp - NM) * D; }
; #pragma unroll
;         for (int j = 0; j < 2; ++j) {
;           const int n = ncolbase + wn * 64 + j * 32 + lc;
;           float v = hsrc[n] + acc[i][j][r];
	v_mad_i32_i24 v174, v173, s46, v172
	v_cmp_gt_u32_e32 vcc, 16, v174
	v_lshlrev_b32_e32 v190, 12, v174
	v_lshl_add_u32 v175, v173, 25, v190
	v_lshl_add_u32 v188, v173, 16, v190
	v_cndmask_b32_e32 v176, v175, v188, vcc
	v_cndmask_b32_e32 v180, v160, v162, vcc
	v_cndmask_b32_e32 v181, v161, v163, vcc
	v_lshl_add_u64 v[128:129], v[176:177], 0, v[180:181]
	global_load_dword v224, v[128:129], off
	global_load_dword v225, v[128:129], off offset:128
	v_add_u32_e32 v76, 33, v171
	v_mul_hi_u32 v77, v76, s36
	v_mad_i32_i24 v78, v77, s46, v76
	v_cmp_gt_u32_e32 vcc, 16, v78
	v_lshlrev_b32_e32 v93, 12, v78
	v_lshl_add_u32 v79, v77, 25, v93
	v_lshl_add_u32 v92, v77, 16, v93
	v_cndmask_b32_e32 v80, v79, v92, vcc
	v_cndmask_b32_e32 v84, v160, v162, vcc
	v_cndmask_b32_e32 v85, v161, v163, vcc
	v_lshl_add_u64 v[130:131], v[80:81], 0, v[84:85]
	global_load_dword v226, v[130:131], off
	global_load_dword v227, v[130:131], off offset:128
	v_add_u32_e32 v172, 34, v171
	v_mul_hi_u32 v173, v172, s36
	v_mad_i32_i24 v174, v173, s46, v172
	v_cmp_gt_u32_e32 vcc, 16, v174
	v_lshlrev_b32_e32 v190, 12, v174
	v_lshl_add_u32 v175, v173, 25, v190
	v_lshl_add_u32 v188, v173, 16, v190
	v_cndmask_b32_e32 v176, v175, v188, vcc
	v_cndmask_b32_e32 v180, v160, v162, vcc
	v_cndmask_b32_e32 v181, v161, v163, vcc
	v_lshl_add_u64 v[132:133], v[176:177], 0, v[180:181]
	global_load_dword v228, v[132:133], off
	global_load_dword v229, v[132:133], off offset:128
	v_add_u32_e32 v76, 35, v171
	v_mul_hi_u32 v77, v76, s36
	v_mad_i32_i24 v78, v77, s46, v76
	v_cmp_gt_u32_e32 vcc, 16, v78
	v_lshlrev_b32_e32 v93, 12, v78
	v_lshl_add_u32 v79, v77, 25, v93
	v_lshl_add_u32 v92, v77, 16, v93
	v_cndmask_b32_e32 v80, v79, v92, vcc
	v_cndmask_b32_e32 v84, v160, v162, vcc
	v_cndmask_b32_e32 v85, v161, v163, vcc
	v_lshl_add_u64 v[134:135], v[80:81], 0, v[84:85]
	global_load_dword v230, v[134:135], off
	global_load_dword v231, v[134:135], off offset:128
	v_add_u32_e32 v172, 40, v171
	v_mul_hi_u32 v173, v172, s36
	v_mad_i32_i24 v174, v173, s46, v172
	v_cmp_gt_u32_e32 vcc, 16, v174
	v_lshlrev_b32_e32 v190, 12, v174
	v_lshl_add_u32 v175, v173, 25, v190
	v_lshl_add_u32 v188, v173, 16, v190
	v_cndmask_b32_e32 v176, v175, v188, vcc
	v_cndmask_b32_e32 v180, v160, v162, vcc
	v_cndmask_b32_e32 v181, v161, v163, vcc
	v_lshl_add_u64 v[136:137], v[176:177], 0, v[180:181]
	global_load_dword v232, v[136:137], off
	global_load_dword v233, v[136:137], off offset:128
	v_add_u32_e32 v76, 41, v171
	v_mul_hi_u32 v77, v76, s36
	v_mad_i32_i24 v78, v77, s46, v76
	v_cmp_gt_u32_e32 vcc, 16, v78
	v_lshlrev_b32_e32 v93, 12, v78
	v_lshl_add_u32 v79, v77, 25, v93
	v_lshl_add_u32 v92, v77, 16, v93
	v_cndmask_b32_e32 v80, v79, v92, vcc
	v_cndmask_b32_e32 v84, v160, v162, vcc
	v_cndmask_b32_e32 v85, v161, v163, vcc
	v_lshl_add_u64 v[138:139], v[80:81], 0, v[84:85]
	global_load_dword v234, v[138:139], off
	global_load_dword v235, v[138:139], off offset:128
	v_add_u32_e32 v172, 42, v171
	v_mul_hi_u32 v173, v172, s36
	v_mad_i32_i24 v174, v173, s46, v172
	v_cmp_gt_u32_e32 vcc, 16, v174
	v_lshlrev_b32_e32 v190, 12, v174
	v_lshl_add_u32 v175, v173, 25, v190
	v_lshl_add_u32 v188, v173, 16, v190
	v_cndmask_b32_e32 v176, v175, v188, vcc
	v_cndmask_b32_e32 v180, v160, v162, vcc
	v_cndmask_b32_e32 v181, v161, v163, vcc
	v_lshl_add_u64 v[140:141], v[176:177], 0, v[180:181]
	global_load_dword v236, v[140:141], off
	global_load_dword v237, v[140:141], off offset:128
	v_add_u32_e32 v76, 43, v171
	v_mul_hi_u32 v77, v76, s36
	v_mad_i32_i24 v78, v77, s46, v76
	v_cmp_gt_u32_e32 vcc, 16, v78
	v_lshlrev_b32_e32 v93, 12, v78
	v_lshl_add_u32 v79, v77, 25, v93
	v_lshl_add_u32 v92, v77, 16, v93
	v_cndmask_b32_e32 v80, v79, v92, vcc
	v_cndmask_b32_e32 v84, v160, v162, vcc
	v_cndmask_b32_e32 v85, v161, v163, vcc
	v_lshl_add_u64 v[142:143], v[80:81], 0, v[84:85]
	global_load_dword v238, v[142:143], off
	global_load_dword v239, v[142:143], off offset:128
	v_add_u32_e32 v172, 48, v171
	v_mul_hi_u32 v173, v172, s36
	v_mad_i32_i24 v174, v173, s46, v172
	v_cmp_gt_u32_e32 vcc, 16, v174
	v_lshlrev_b32_e32 v190, 12, v174
	v_lshl_add_u32 v175, v173, 25, v190
	v_lshl_add_u32 v188, v173, 16, v190
	v_cndmask_b32_e32 v176, v175, v188, vcc
	v_cndmask_b32_e32 v180, v160, v162, vcc
	v_cndmask_b32_e32 v181, v161, v163, vcc
	v_lshl_add_u64 v[144:145], v[176:177], 0, v[180:181]
	global_load_dword v240, v[144:145], off
	global_load_dword v241, v[144:145], off offset:128
	v_add_u32_e32 v76, 49, v171
	v_mul_hi_u32 v77, v76, s36
	v_mad_i32_i24 v78, v77, s46, v76
	v_cmp_gt_u32_e32 vcc, 16, v78
	v_lshlrev_b32_e32 v93, 12, v78
	v_lshl_add_u32 v79, v77, 25, v93
	v_lshl_add_u32 v92, v77, 16, v93
	v_cndmask_b32_e32 v80, v79, v92, vcc
	v_cndmask_b32_e32 v84, v160, v162, vcc
	v_cndmask_b32_e32 v85, v161, v163, vcc
	v_lshl_add_u64 v[146:147], v[80:81], 0, v[84:85]
	global_load_dword v242, v[146:147], off
	global_load_dword v243, v[146:147], off offset:128
	v_add_u32_e32 v172, 50, v171
	v_mul_hi_u32 v173, v172, s36
	v_mad_i32_i24 v174, v173, s46, v172
	v_cmp_gt_u32_e32 vcc, 16, v174
	v_lshlrev_b32_e32 v190, 12, v174
	v_lshl_add_u32 v175, v173, 25, v190
	v_lshl_add_u32 v188, v173, 16, v190
	v_cndmask_b32_e32 v176, v175, v188, vcc
	v_cndmask_b32_e32 v180, v160, v162, vcc
	v_cndmask_b32_e32 v181, v161, v163, vcc
	v_lshl_add_u64 v[148:149], v[176:177], 0, v[180:181]
	global_load_dword v244, v[148:149], off
	global_load_dword v245, v[148:149], off offset:128
	v_add_u32_e32 v76, 51, v171
	v_mul_hi_u32 v77, v76, s36
	v_mad_i32_i24 v78, v77, s46, v76
	v_cmp_gt_u32_e32 vcc, 16, v78
	v_lshlrev_b32_e32 v93, 12, v78
	v_lshl_add_u32 v79, v77, 25, v93
	v_lshl_add_u32 v92, v77, 16, v93
	v_cndmask_b32_e32 v80, v79, v92, vcc
; __device__ __forceinline__ int tid_opaque() { int t = threadIdx.x; asm volatile("" : "+v"(t)); return t; }
; __device__ __forceinline__ int crow(int r, int hf) { return (r & 3) + 8 * (r >> 2) + 4 * hf; }
; template <bool FIRST>
; __device__ __forceinline__ void residual_epilogue(const Params& p, f32x16 (&acc)[2][2], int m0, int ncolbase) {
;   const int tid = tid_opaque(), w = tid >> 6, l = tid & 63, lc = l & 31, hf = l >> 5;
;   const int wm = w >> 1, wn = w & 1;
; #pragma unroll
;   for (int i = 0; i < 2; ++i)
; #pragma unroll
;     for (int r = 0; r < 16; ++r) {
;       const int t = m0 + wm * 64 + i * 32 + crow(r, hf);
;       if (t < T) {
;         float* hp = hrow(p, t);
;         const float* hsrc = hp;
;         if (FIRST) { const int b = t / L, pp = t - b * L; hsrc = pp < NM ? p.meta + (size_t)pp * D : p.x + (size_t)(b * SEQ + pp - NM) * D; }
; #pragma unroll
;         for (int j = 0; j < 2; ++j) {
;           const int n = ncolbase + wn * 64 + j * 32 + lc;
;           float v = hsrc[n] + acc[i][j][r];
	v_cndmask_b32_e32 v84, v160, v162, vcc
	v_cndmask_b32_e32 v85, v161, v163, vcc
	v_lshl_add_u64 v[150:151], v[80:81], 0, v[84:85]
	global_load_dword v246, v[150:151], off
	global_load_dword v247, v[150:151], off offset:128
	v_add_u32_e32 v172, 56, v171
	v_mul_hi_u32 v173, v172, s36
	v_mad_i32_i24 v174, v173, s46, v172
	v_cmp_gt_u32_e32 vcc, 16, v174
	v_lshlrev_b32_e32 v190, 12, v174
	v_lshl_add_u32 v175, v173, 25, v190
	v_lshl_add_u32 v188, v173, 16, v190
	v_cndmask_b32_e32 v176, v175, v188, vcc
	v_cndmask_b32_e32 v180, v160, v162, vcc
	v_cndmask_b32_e32 v181, v161, v163, vcc
	v_lshl_add_u64 v[152:153], v[176:177], 0, v[180:181]
	global_load_dword v248, v[152:153], off
	global_load_dword v249, v[152:153], off offset:128
	v_add_u32_e32 v76, 57, v171
	v_mul_hi_u32 v77, v76, s36
	v_mad_i32_i24 v78, v77, s46, v76
	v_cmp_gt_u32_e32 vcc, 16, v78
	v_lshlrev_b32_e32 v93, 12, v78
	v_lshl_add_u32 v79, v77, 25, v93
	v_lshl_add_u32 v92, v77, 16, v93
	v_cndmask_b32_e32 v80, v79, v92, vcc
	v_cndmask_b32_e32 v84, v160, v162, vcc
	v_cndmask_b32_e32 v85, v161, v163, vcc
	v_lshl_add_u64 v[154:155], v[80:81], 0, v[84:85]
	global_load_dword v250, v[154:155], off
	global_load_dword v251, v[154:155], off offset:128
	v_add_u32_e32 v172, 58, v171
	v_mul_hi_u32 v173, v172, s36
	v_mad_i32_i24 v174, v173, s46, v172
	v_cmp_gt_u32_e32 vcc, 16, v174
	v_lshlrev_b32_e32 v190, 12, v174
	v_lshl_add_u32 v175, v173, 25, v190
	v_lshl_add_u32 v188, v173, 16, v190
	v_cndmask_b32_e32 v176, v175, v188, vcc
	v_cndmask_b32_e32 v180, v160, v162, vcc
	v_cndmask_b32_e32 v181, v161, v163, vcc
	v_lshl_add_u64 v[156:157], v[176:177], 0, v[180:181]
	global_load_dword v252, v[156:157], off
	global_load_dword v253, v[156:157], off offset:128
	v_add_u32_e32 v76, 59, v171
	v_mul_hi_u32 v77, v76, s36
	v_mad_i32_i24 v78, v77, s46, v76
	v_cmp_gt_u32_e32 vcc, 16, v78
	v_lshlrev_b32_e32 v93, 12, v78
	v_lshl_add_u32 v79, v77, 25, v93
	v_lshl_add_u32 v92, v77, 16, v93
	v_cndmask_b32_e32 v80, v79, v92, vcc
	v_cndmask_b32_e32 v84, v160, v162, vcc
	v_cndmask_b32_e32 v85, v161, v163, vcc
	v_lshl_add_u64 v[158:159], v[80:81], 0, v[84:85]
	global_load_dword v186, v[158:159], off
	global_load_dword v187, v[158:159], off offset:128
	s_waitcnt vmcnt(62)
	v_add_f32_e32 v48, v48, v192
	v_add_f32_e32 v32, v32, v193
	s_waitcnt vmcnt(60)
	v_add_f32_e32 v49, v49, v194
	v_add_f32_e32 v33, v33, v195
	s_waitcnt vmcnt(58)
	v_add_f32_e32 v50, v50, v196
	v_add_f32_e32 v34, v34, v197
	s_waitcnt vmcnt(56)
	v_add_f32_e32 v51, v51, v198
	v_add_f32_e32 v35, v35, v199
	s_waitcnt vmcnt(54)
	v_add_f32_e32 v52, v52, v200
	v_add_f32_e32 v36, v36, v201
	s_waitcnt vmcnt(52)
	v_add_f32_e32 v53, v53, v202
	v_add_f32_e32 v37, v37, v203
	s_waitcnt vmcnt(50)
	v_add_f32_e32 v54, v54, v204
	v_add_f32_e32 v38, v38, v205
	s_waitcnt vmcnt(48)
	v_add_f32_e32 v55, v55, v206
	v_add_f32_e32 v39, v39, v207
	s_waitcnt vmcnt(46)
	v_add_f32_e32 v56, v56, v208
	v_add_f32_e32 v40, v40, v209
	s_waitcnt vmcnt(44)
	v_add_f32_e32 v57, v57, v210
	v_add_f32_e32 v41, v41, v211
	s_waitcnt vmcnt(42)
	v_add_f32_e32 v58, v58, v212
	v_add_f32_e32 v42, v42, v213
	s_waitcnt vmcnt(40)
	v_add_f32_e32 v59, v59, v214
	v_add_f32_e32 v43, v43, v215
	s_waitcnt vmcnt(38)
	v_add_f32_e32 v60, v60, v216
	v_add_f32_e32 v44, v44, v217
	s_waitcnt vmcnt(36)
	v_add_f32_e32 v61, v61, v218
	v_add_f32_e32 v45, v45, v219
	s_waitcnt vmcnt(34)
	v_add_f32_e32 v62, v62, v220
	v_add_f32_e32 v46, v46, v221
	s_waitcnt vmcnt(32)
	v_add_f32_e32 v63, v63, v222
	v_add_f32_e32 v47, v47, v223
	s_waitcnt vmcnt(30)
	v_add_f32_e32 v16, v16, v224
	v_add_f32_e32 v0, v0, v225
	s_waitcnt vmcnt(28)
	v_add_f32_e32 v17, v17, v226
	v_add_f32_e32 v1, v1, v227
	s_waitcnt vmcnt(26)
	v_add_f32_e32 v18, v18, v228
	v_add_f32_e32 v2, v2, v229
	s_waitcnt vmcnt(24)
	v_add_f32_e32 v19, v19, v230
	v_add_f32_e32 v3, v3, v231
	s_waitcnt vmcnt(22)
	v_add_f32_e32 v20, v20, v232
	v_add_f32_e32 v4, v4, v233
	s_waitcnt vmcnt(20)
	v_add_f32_e32 v21, v21, v234
	v_add_f32_e32 v5, v5, v235
	s_waitcnt vmcnt(18)
	v_add_f32_e32 v22, v22, v236
	v_add_f32_e32 v6, v6, v237
	s_waitcnt vmcnt(16)
	v_add_f32_e32 v23, v23, v238
	v_add_f32_e32 v7, v7, v239
	s_waitcnt vmcnt(14)
	v_add_f32_e32 v24, v24, v240
	v_add_f32_e32 v8, v8, v241
	s_waitcnt vmcnt(12)
	v_add_f32_e32 v25, v25, v242
	v_add_f32_e32 v9, v9, v243
	s_waitcnt vmcnt(10)
	v_add_f32_e32 v26, v26, v244
	v_add_f32_e32 v10, v10, v245
	s_waitcnt vmcnt(8)
	v_add_f32_e32 v27, v27, v246
	v_add_f32_e32 v11, v11, v247
	s_waitcnt vmcnt(6)
	v_add_f32_e32 v28, v28, v248
	v_add_f32_e32 v12, v12, v249
	s_waitcnt vmcnt(4)
	v_add_f32_e32 v29, v29, v250
	v_add_f32_e32 v13, v13, v251
	s_waitcnt vmcnt(2)
	v_add_f32_e32 v30, v30, v252
	v_add_f32_e32 v14, v14, v253
	s_waitcnt vmcnt(0)
; __device__ __forceinline__ int crow(int r, int hf) { return (r & 3) + 8 * (r >> 2) + 4 * hf; }
; template <bool FIRST>
; __device__ __forceinline__ void residual_epilogue(const Params& p, f32x16 (&acc)[2][2], int m0, int ncolbase) {
;     ...
;   for (int i = 0; i < 2; ++i)
; #pragma unroll
;     for (int r = 0; r < 16; ++r) {
;       const int t = m0 + wm * 64 + i * 32 + crow(r, hf);
;       if (t < T) {
;         float* hp = hrow(p, t);
;         const float* hsrc = hp;
;         if (FIRST) { const int b = t / L, pp = t - b * L; hsrc = pp < NM ? p.meta + (size_t)pp * D : p.x + (size_t)(b * SEQ + pp - NM) * D; }
; #pragma unroll
;         for (int j = 0; j < 2; ++j) {
;           const int n = ncolbase + wn * 64 + j * 32 + lc;
;           float v = hsrc[n] + acc[i][j][r];
;           hp[n] = v;
;           p.hb[(size_t)t * D + n] = (u16)(cvtpk(v, 0.f) & 0xffffu);
;         }
	v_add_f32_e32 v31, v31, v186
	v_add_f32_e32 v15, v15, v187
	global_store_dword v[96:97], v48, off
	global_store_dword v[96:97], v32, off offset:128
	v_cvt_pk_bf16_f32 v64, v48, v75
	v_cvt_pk_bf16_f32 v65, v32, v75
	v_add_u32_e32 v76, 0, v171
	v_lshl_add_u32 v77, v76, 11, v170
	global_store_short v77, v64, s[76:77]
	global_store_short v77, v65, s[76:77] offset:64
	global_store_dword v[98:99], v49, off
	global_store_dword v[98:99], v33, off offset:128
	v_cvt_pk_bf16_f32 v66, v49, v75
	v_cvt_pk_bf16_f32 v67, v33, v75
	v_add_u32_e32 v78, 1, v171
	v_lshl_add_u32 v79, v78, 11, v170
	global_store_short v79, v66, s[76:77]
	global_store_short v79, v67, s[76:77] offset:64
	global_store_dword v[100:101], v50, off
	global_store_dword v[100:101], v34, off offset:128
	v_cvt_pk_bf16_f32 v68, v50, v75
	v_cvt_pk_bf16_f32 v69, v34, v75
	v_add_u32_e32 v80, 2, v171
	v_lshl_add_u32 v81, v80, 11, v170
	global_store_short v81, v68, s[76:77]
	global_store_short v81, v69, s[76:77] offset:64
	global_store_dword v[102:103], v51, off
	global_store_dword v[102:103], v35, off offset:128
	v_cvt_pk_bf16_f32 v70, v51, v75
	v_cvt_pk_bf16_f32 v71, v35, v75
	v_add_u32_e32 v82, 3, v171
	v_lshl_add_u32 v83, v82, 11, v170
	global_store_short v83, v70, s[76:77]
	global_store_short v83, v71, s[76:77] offset:64
	global_store_dword v[104:105], v52, off
	global_store_dword v[104:105], v36, off offset:128
	v_cvt_pk_bf16_f32 v64, v52, v75
	v_cvt_pk_bf16_f32 v65, v36, v75
	v_add_u32_e32 v76, 8, v171
	v_lshl_add_u32 v77, v76, 11, v170
	global_store_short v77, v64, s[76:77]
	global_store_short v77, v65, s[76:77] offset:64
	global_store_dword v[106:107], v53, off
	global_store_dword v[106:107], v37, off offset:128
	v_cvt_pk_bf16_f32 v66, v53, v75
	v_cvt_pk_bf16_f32 v67, v37, v75
	v_add_u32_e32 v78, 9, v171
	v_lshl_add_u32 v79, v78, 11, v170
	global_store_short v79, v66, s[76:77]
	global_store_short v79, v67, s[76:77] offset:64
	global_store_dword v[108:109], v54, off
	global_store_dword v[108:109], v38, off offset:128
	v_cvt_pk_bf16_f32 v68, v54, v75
	v_cvt_pk_bf16_f32 v69, v38, v75
	v_add_u32_e32 v80, 10, v171
	v_lshl_add_u32 v81, v80, 11, v170
	global_store_short v81, v68, s[76:77]
	global_store_short v81, v69, s[76:77] offset:64
	global_store_dword v[110:111], v55, off
	global_store_dword v[110:111], v39, off offset:128
	v_cvt_pk_bf16_f32 v70, v55, v75
	v_cvt_pk_bf16_f32 v71, v39, v75
	v_add_u32_e32 v82, 11, v171
	v_lshl_add_u32 v83, v82, 11, v170
	global_store_short v83, v70, s[76:77]
	global_store_short v83, v71, s[76:77] offset:64
	global_store_dword v[112:113], v56, off
	global_store_dword v[112:113], v40, off offset:128
	v_cvt_pk_bf16_f32 v64, v56, v75
	v_cvt_pk_bf16_f32 v65, v40, v75
	v_add_u32_e32 v76, 16, v171
	v_lshl_add_u32 v77, v76, 11, v170
	global_store_short v77, v64, s[76:77]
	global_store_short v77, v65, s[76:77] offset:64
	global_store_dword v[114:115], v57, off
	global_store_dword v[114:115], v41, off offset:128
	v_cvt_pk_bf16_f32 v66, v57, v75
	v_cvt_pk_bf16_f32 v67, v41, v75
	v_add_u32_e32 v78, 17, v171
	v_lshl_add_u32 v79, v78, 11, v170
	global_store_short v79, v66, s[76:77]
	global_store_short v79, v67, s[76:77] offset:64
	global_store_dword v[116:117], v58, off
	global_store_dword v[116:117], v42, off offset:128
	v_cvt_pk_bf16_f32 v68, v58, v75
	v_cvt_pk_bf16_f32 v69, v42, v75
	v_add_u32_e32 v80, 18, v171
	v_lshl_add_u32 v81, v80, 11, v170
	global_store_short v81, v68, s[76:77]
	global_store_short v81, v69, s[76:77] offset:64
	global_store_dword v[118:119], v59, off
	global_store_dword v[118:119], v43, off offset:128
	v_cvt_pk_bf16_f32 v70, v59, v75
	v_cvt_pk_bf16_f32 v71, v43, v75
	v_add_u32_e32 v82, 19, v171
	v_lshl_add_u32 v83, v82, 11, v170
	global_store_short v83, v70, s[76:77]
	global_store_short v83, v71, s[76:77] offset:64
	global_store_dword v[120:121], v60, off
	global_store_dword v[120:121], v44, off offset:128
	v_cvt_pk_bf16_f32 v64, v60, v75
	v_cvt_pk_bf16_f32 v65, v44, v75
	v_add_u32_e32 v76, 24, v171
	v_lshl_add_u32 v77, v76, 11, v170
	global_store_short v77, v64, s[76:77]
	global_store_short v77, v65, s[76:77] offset:64
	global_store_dword v[122:123], v61, off
	global_store_dword v[122:123], v45, off offset:128
	v_cvt_pk_bf16_f32 v66, v61, v75
	v_cvt_pk_bf16_f32 v67, v45, v75
	v_add_u32_e32 v78, 25, v171
	v_lshl_add_u32 v79, v78, 11, v170
	global_store_short v79, v66, s[76:77]
	global_store_short v79, v67, s[76:77] offset:64
	global_store_dword v[124:125], v62, off
	global_store_dword v[124:125], v46, off offset:128
	v_cvt_pk_bf16_f32 v68, v62, v75
	v_cvt_pk_bf16_f32 v69, v46, v75
	v_add_u32_e32 v80, 26, v171
	v_lshl_add_u32 v81, v80, 11, v170
	global_store_short v81, v68, s[76:77]
	global_store_short v81, v69, s[76:77] offset:64
	global_store_dword v[126:127], v63, off
	global_store_dword v[126:127], v47, off offset:128
	v_cvt_pk_bf16_f32 v70, v63, v75
	v_cvt_pk_bf16_f32 v71, v47, v75
	v_add_u32_e32 v82, 27, v171
	v_lshl_add_u32 v83, v82, 11, v170
	global_store_short v83, v70, s[76:77]
; __device__ __forceinline__ int crow(int r, int hf) { return (r & 3) + 8 * (r >> 2) + 4 * hf; }
; template <bool FIRST>
; __device__ __forceinline__ void residual_epilogue(const Params& p, f32x16 (&acc)[2][2], int m0, int ncolbase) {
;     ...
;   for (int i = 0; i < 2; ++i)
; #pragma unroll
;     for (int r = 0; r < 16; ++r) {
;       const int t = m0 + wm * 64 + i * 32 + crow(r, hf);
;       if (t < T) {
;         float* hp = hrow(p, t);
;         const float* hsrc = hp;
;         if (FIRST) { const int b = t / L, pp = t - b * L; hsrc = pp < NM ? p.meta + (size_t)pp * D : p.x + (size_t)(b * SEQ + pp - NM) * D; }
; #pragma unroll
;         for (int j = 0; j < 2; ++j) {
;           const int n = ncolbase + wn * 64 + j * 32 + lc;
;           float v = hsrc[n] + acc[i][j][r];
;           hp[n] = v;
;           p.hb[(size_t)t * D + n] = (u16)(cvtpk(v, 0.f) & 0xffffu);
;         }
	global_store_short v83, v71, s[76:77] offset:64
	global_store_dword v[128:129], v16, off
	global_store_dword v[128:129], v0, off offset:128
	v_cvt_pk_bf16_f32 v64, v16, v75
	v_cvt_pk_bf16_f32 v65, v0, v75
	v_add_u32_e32 v76, 32, v171
	v_lshl_add_u32 v77, v76, 11, v170
	global_store_short v77, v64, s[76:77]
	global_store_short v77, v65, s[76:77] offset:64
	global_store_dword v[130:131], v17, off
	global_store_dword v[130:131], v1, off offset:128
	v_cvt_pk_bf16_f32 v66, v17, v75
	v_cvt_pk_bf16_f32 v67, v1, v75
	v_add_u32_e32 v78, 33, v171
	v_lshl_add_u32 v79, v78, 11, v170
	global_store_short v79, v66, s[76:77]
	global_store_short v79, v67, s[76:77] offset:64
	global_store_dword v[132:133], v18, off
	global_store_dword v[132:133], v2, off offset:128
	v_cvt_pk_bf16_f32 v68, v18, v75
	v_cvt_pk_bf16_f32 v69, v2, v75
	v_add_u32_e32 v80, 34, v171
	v_lshl_add_u32 v81, v80, 11, v170
	global_store_short v81, v68, s[76:77]
	global_store_short v81, v69, s[76:77] offset:64
	global_store_dword v[134:135], v19, off
	global_store_dword v[134:135], v3, off offset:128
	v_cvt_pk_bf16_f32 v70, v19, v75
	v_cvt_pk_bf16_f32 v71, v3, v75
	v_add_u32_e32 v82, 35, v171
	v_lshl_add_u32 v83, v82, 11, v170
	global_store_short v83, v70, s[76:77]
	global_store_short v83, v71, s[76:77] offset:64
	global_store_dword v[136:137], v20, off
	global_store_dword v[136:137], v4, off offset:128
	v_cvt_pk_bf16_f32 v64, v20, v75
	v_cvt_pk_bf16_f32 v65, v4, v75
	v_add_u32_e32 v76, 40, v171
	v_lshl_add_u32 v77, v76, 11, v170
	global_store_short v77, v64, s[76:77]
	global_store_short v77, v65, s[76:77] offset:64
	global_store_dword v[138:139], v21, off
	global_store_dword v[138:139], v5, off offset:128
	v_cvt_pk_bf16_f32 v66, v21, v75
	v_cvt_pk_bf16_f32 v67, v5, v75
	v_add_u32_e32 v78, 41, v171
	v_lshl_add_u32 v79, v78, 11, v170
	global_store_short v79, v66, s[76:77]
	global_store_short v79, v67, s[76:77] offset:64
	global_store_dword v[140:141], v22, off
	global_store_dword v[140:141], v6, off offset:128
	v_cvt_pk_bf16_f32 v68, v22, v75
	v_cvt_pk_bf16_f32 v69, v6, v75
	v_add_u32_e32 v80, 42, v171
	v_lshl_add_u32 v81, v80, 11, v170
	global_store_short v81, v68, s[76:77]
	global_store_short v81, v69, s[76:77] offset:64
	global_store_dword v[142:143], v23, off
	global_store_dword v[142:143], v7, off offset:128
	v_cvt_pk_bf16_f32 v70, v23, v75
	v_cvt_pk_bf16_f32 v71, v7, v75
	v_add_u32_e32 v82, 43, v171
	v_lshl_add_u32 v83, v82, 11, v170
	global_store_short v83, v70, s[76:77]
	global_store_short v83, v71, s[76:77] offset:64
	global_store_dword v[144:145], v24, off
	global_store_dword v[144:145], v8, off offset:128
	v_cvt_pk_bf16_f32 v64, v24, v75
	v_cvt_pk_bf16_f32 v65, v8, v75
	v_add_u32_e32 v76, 48, v171
	v_lshl_add_u32 v77, v76, 11, v170
	global_store_short v77, v64, s[76:77]
	global_store_short v77, v65, s[76:77] offset:64
	global_store_dword v[146:147], v25, off
	global_store_dword v[146:147], v9, off offset:128
	v_cvt_pk_bf16_f32 v66, v25, v75
	v_cvt_pk_bf16_f32 v67, v9, v75
	v_add_u32_e32 v78, 49, v171
	v_lshl_add_u32 v79, v78, 11, v170
	global_store_short v79, v66, s[76:77]
	global_store_short v79, v67, s[76:77] offset:64
	global_store_dword v[148:149], v26, off
	global_store_dword v[148:149], v10, off offset:128
	v_cvt_pk_bf16_f32 v68, v26, v75
	v_cvt_pk_bf16_f32 v69, v10, v75
	v_add_u32_e32 v80, 50, v171
	v_lshl_add_u32 v81, v80, 11, v170
	global_store_short v81, v68, s[76:77]
	global_store_short v81, v69, s[76:77] offset:64
	global_store_dword v[150:151], v27, off
	global_store_dword v[150:151], v11, off offset:128
	v_cvt_pk_bf16_f32 v70, v27, v75
	v_cvt_pk_bf16_f32 v71, v11, v75
	v_add_u32_e32 v82, 51, v171
	v_lshl_add_u32 v83, v82, 11, v170
	global_store_short v83, v70, s[76:77]
	global_store_short v83, v71, s[76:77] offset:64
	global_store_dword v[152:153], v28, off
	global_store_dword v[152:153], v12, off offset:128
	v_cvt_pk_bf16_f32 v64, v28, v75
	v_cvt_pk_bf16_f32 v65, v12, v75
	v_add_u32_e32 v76, 56, v171
	v_lshl_add_u32 v77, v76, 11, v170
	global_store_short v77, v64, s[76:77]
	global_store_short v77, v65, s[76:77] offset:64
	global_store_dword v[154:155], v29, off
	global_store_dword v[154:155], v13, off offset:128
	v_cvt_pk_bf16_f32 v66, v29, v75
	v_cvt_pk_bf16_f32 v67, v13, v75
	v_add_u32_e32 v78, 57, v171
	v_lshl_add_u32 v79, v78, 11, v170
	global_store_short v79, v66, s[76:77]
	global_store_short v79, v67, s[76:77] offset:64
	global_store_dword v[156:157], v30, off
	global_store_dword v[156:157], v14, off offset:128
	v_cvt_pk_bf16_f32 v68, v30, v75
	v_cvt_pk_bf16_f32 v69, v14, v75
	v_add_u32_e32 v80, 58, v171
	v_lshl_add_u32 v81, v80, 11, v170
	global_store_short v81, v68, s[76:77]
	global_store_short v81, v69, s[76:77] offset:64
	global_store_dword v[158:159], v31, off
	global_store_dword v[158:159], v15, off offset:128
	v_cvt_pk_bf16_f32 v70, v31, v75
	v_cvt_pk_bf16_f32 v71, v15, v75
	v_add_u32_e32 v82, 59, v171
	v_lshl_add_u32 v83, v82, 11, v170
	global_store_short v83, v70, s[76:77]
	global_store_short v83, v71, s[76:77] offset:64
